# stack15 + dead zero-source moves dropped from the unit headers after the C=0 peel (12 instances; 8 moves in the EpiMix header)
# baseline (speedup 1.0000x reference)
; #define PG8_STAGE(bufoff, gbase, voff) do { _Pragma("unroll") for (int _i = 0; _i < 2; ++_i) \
;         __builtin_amdgcn_global_load_lds((const unsigned*)((const char*)(gbase) + (voff)[_i]), (PG8_LAS unsigned*)(lds + (bufoff) + ldsw + _i * 8192), 16, 0, 0); } while (0)
; #define PG8_LDA(dst, b, h) do { _Pragma("unroll") for (int m = 0; m < 4; ++m) _Pragma("unroll") for (int k = 0; k < 2; ++k) dst[m][k] = *(const PG8_LAS bf16x8*)(lds + PG8_SA(b, h) + aoff + m * 2048 + k * 1024); } while (0)
; #define PG8_LDB(dst, b, h) do { _Pragma("unroll") for (int n = 0; n < 2; ++n) _Pragma("unroll") for (int k = 0; k < 2; ++k) dst[n][k] = *(const PG8_LAS bf16x8*)(lds + PG8_SB(b, h) + boff + n * 2048 + k * 1024); } while (0)
; #define PG8_WAIT_V(n) asm volatile("s_waitcnt vmcnt(" #n ")" ::: "memory")
; #define PG8_WAIT_L(n) asm volatile("s_waitcnt lgkmcnt(" #n ")" ::: "memory")
; #define PG8_BAR __builtin_amdgcn_s_barrier()
; #define PG8_SCHED __builtin_amdgcn_sched_barrier(0)
; template <class Epi, class Sched, bool ALIGN_EPI = false, bool SP2 = false, bool ABLK = false, bool BBLK = false>
; __device__ __forceinline__ void gemm_phase(PG8_LAS unsigned char* lds, const Gemm g, const Sched& S, const Epi& E) {
;     ...
;         const bool has_next = S.next(ui + 1, nxt);
;         const char* nA = has_next ? (const char*)g.A + (size_t)nxt.pm * tstepA : cA; const char* nB = has_next ? (const char*)g.Bt + (size_t)nxt.pn * tstepB : cB;
;         for (int t = 0; t < nt; t += 2) {
;             const bool last = (t == nt - 2);
;             const char* a1 = cA + (size_t)(t + 1) * kstepA;
;             const char* a2 = last ? nA : cA + (size_t)(t + 2) * kstepA; const char* b2 = last ? nB : cB + (size_t)(t + 2) * kstepB;
;             const char* a3 = a2 + kstepA; const char* b3 = b2 + kstepB;
;             if (last && has_next) S.a_ready(nxt);
;             if constexpr (SP2) {
;             PG8_LDB(B0, 0, 0); PG8_LDB(B1, 0, 1); PG8_SCHED; PG8_LDA(At, 0, 0); PG8_STAGE(PG8_SA(1, 1), a1 + hstepA, voffA);
;             PG8_WAIT_V(8); PG8_WAIT_L(0); PG8_BAR; PG8_MMA(0, 0, At, B0); PG8_MMA(0, 1, At, B1); PG8_BAR; PG8_SCHED;
;             PG8_LDA(At, 0, 1); PG8_STAGE(PG8_SB(0, 0), b2, voffB); PG8_STAGE(PG8_SB(0, 1), b2 + hstepB, voffB); PG8_STAGE(PG8_SA(0, 0), a2, voffA);
;             PG8_WAIT_V(8); PG8_WAIT_L(0); PG8_BAR; PG8_MMA(1, 0, At, B0); PG8_MMA(1, 1, At, B1); PG8_BAR; PG8_SCHED;
.LBB0_215:
	s_ashr_i32 s15, s14, 31
	s_lshl_b64 s[18:19], s[14:15], 20
	s_add_u32 s18, s35, s18
	s_addc_u32 s19, s36, s19
	s_and_b64 s[20:21], s[4:5], exec
	s_cselect_b32 s15, s19, s23
	s_cselect_b32 s65, s18, s22
	s_ashr_i32 s13, s12, 31
	s_lshl_b64 s[20:21], s[12:13], 20
	s_add_u32 s20, s37, s20
	s_addc_u32 s21, s40, s21
	s_and_b64 s[26:27], s[4:5], exec
	s_cselect_b32 s13, s21, s25
	s_cselect_b32 s68, s20, s24
	s_add_u32 s22, s22, 0xc000
	s_addc_u32 s23, s23, 0
	s_add_u32 s72, s24, 0x10000
	s_addc_u32 s73, s25, 0
	s_mov_b32 s81, -2
	s_add_u32 s24, s22, 0x4000
	s_addc_u32 s25, s23, 0
	s_cmp_eq_u32 s81, 28
	s_cselect_b32 s28, s65, s24
	s_cselect_b32 s29, s15, s25
	s_cselect_b32 s26, s68, s72
	s_cselect_b32 s27, s13, s73
	s_add_u32 s24, s28, 0x8000
	s_addc_u32 s25, s29, 0
	s_add_i32 s75, 0, 0x10000
	v_add_u32_e32 v142, s75, v145
	s_add_i32 s80, 0, 0x14000
	ds_read_b128 v[148:151], v142
	ds_read_b128 v[152:155], v142 offset:1024
	ds_read_b128 v[156:159], v142 offset:2048
	ds_read_b128 v[160:163], v142 offset:3072
	v_add_u32_e32 v142, s80, v145
	ds_read_b128 v[164:167], v142
	ds_read_b128 v[168:171], v142 offset:1024
	ds_read_b128 v[172:175], v142 offset:2048
	ds_read_b128 v[176:179], v142 offset:3072
	v_lshl_add_u64 v[142:143], s[22:23], 0, v[138:139]
	s_add_i32 m0, s43, 0xc000
	ds_read_b128 v[180:183], v146
	ds_read_b128 v[196:199], v146 offset:1024
	ds_read_b128 v[200:203], v146 offset:2048
	ds_read_b128 v[204:207], v146 offset:3072
	ds_read_b128 v[208:211], v146 offset:4096
	ds_read_b128 v[212:215], v146 offset:5120
	ds_read_b128 v[216:219], v146 offset:6144
	ds_read_b128 v[220:223], v146 offset:7168
	global_load_lds_dwordx4 v[142:143], off
	v_lshl_add_u64 v[142:143], s[22:23], 0, v[140:141]
	s_add_i32 m0, s43, 0xe000
	s_nop 0
	global_load_lds_dwordx4 v[142:143], off
	s_waitcnt vmcnt(8)
	s_waitcnt lgkmcnt(0)
	s_barrier
	s_setprio 1
	s_waitcnt lgkmcnt(0)
	v_mfma_f32_16x16x32_bf16 v[126:129], v[148:151], v[180:183], 0
	v_mfma_f32_16x16x32_bf16 v[118:121], v[156:159], v[180:183], 0
	v_mfma_f32_16x16x32_bf16 v[110:113], v[148:151], v[200:203], 0
	v_mfma_f32_16x16x32_bf16 v[102:105], v[156:159], v[200:203], 0
	v_mfma_f32_16x16x32_bf16 v[94:97], v[148:151], v[208:211], 0
	v_mfma_f32_16x16x32_bf16 v[86:89], v[156:159], v[208:211], 0
	v_mfma_f32_16x16x32_bf16 v[78:81], v[148:151], v[216:219], 0
	v_mfma_f32_16x16x32_bf16 v[70:73], v[156:159], v[216:219], 0
	v_mfma_f32_16x16x32_bf16 v[126:129], v[152:155], v[196:199], v[126:129]
	v_mfma_f32_16x16x32_bf16 v[118:121], v[160:163], v[196:199], v[118:121]
	v_mfma_f32_16x16x32_bf16 v[110:113], v[152:155], v[204:207], v[110:113]
	v_mfma_f32_16x16x32_bf16 v[102:105], v[160:163], v[204:207], v[102:105]
	v_mfma_f32_16x16x32_bf16 v[94:97], v[152:155], v[212:215], v[94:97]
	v_mfma_f32_16x16x32_bf16 v[86:89], v[160:163], v[212:215], v[86:89]
	v_mfma_f32_16x16x32_bf16 v[78:81], v[152:155], v[220:223], v[78:81]
	v_mfma_f32_16x16x32_bf16 v[70:73], v[160:163], v[220:223], v[70:73]
	s_setprio 0
	s_setprio 1
	v_mfma_f32_16x16x32_bf16 v[122:125], v[164:167], v[180:183], 0
	v_mfma_f32_16x16x32_bf16 v[114:117], v[172:175], v[180:183], 0
	v_mfma_f32_16x16x32_bf16 v[106:109], v[164:167], v[200:203], 0
	v_mfma_f32_16x16x32_bf16 v[98:101], v[172:175], v[200:203], 0
	v_mfma_f32_16x16x32_bf16 v[90:93], v[164:167], v[208:211], 0
	v_mfma_f32_16x16x32_bf16 v[82:85], v[172:175], v[208:211], 0
	v_mfma_f32_16x16x32_bf16 v[74:77], v[164:167], v[216:219], 0
	v_mfma_f32_16x16x32_bf16 v[66:69], v[172:175], v[216:219], 0
	v_mfma_f32_16x16x32_bf16 v[122:125], v[168:171], v[196:199], v[122:125]
	v_mfma_f32_16x16x32_bf16 v[114:117], v[176:179], v[196:199], v[114:117]
	v_mfma_f32_16x16x32_bf16 v[106:109], v[168:171], v[204:207], v[106:109]
	v_mfma_f32_16x16x32_bf16 v[98:101], v[176:179], v[204:207], v[98:101]
	v_mfma_f32_16x16x32_bf16 v[90:93], v[168:171], v[212:215], v[90:93]
	v_mfma_f32_16x16x32_bf16 v[82:85], v[176:179], v[212:215], v[82:85]
	v_mfma_f32_16x16x32_bf16 v[74:77], v[168:171], v[220:223], v[74:77]
	v_mfma_f32_16x16x32_bf16 v[66:69], v[176:179], v[220:223], v[66:69]
	s_setprio 0
	s_barrier
; #define PG8_STAGE(bufoff, gbase, voff) do { _Pragma("unroll") for (int _i = 0; _i < 2; ++_i) \
;         __builtin_amdgcn_global_load_lds((const unsigned*)((const char*)(gbase) + (voff)[_i]), (PG8_LAS unsigned*)(lds + (bufoff) + ldsw + _i * 8192), 16, 0, 0); } while (0)
; #define PG8_LDA(dst, b, h) do { _Pragma("unroll") for (int m = 0; m < 4; ++m) _Pragma("unroll") for (int k = 0; k < 2; ++k) dst[m][k] = *(const PG8_LAS bf16x8*)(lds + PG8_SA(b, h) + aoff + m * 2048 + k * 1024); } while (0)
; #define PG8_MMA(ai, bj, At, Bt) do { __builtin_amdgcn_s_setprio(1); _Pragma("unroll") for (int m = 0; m < 4; ++m) _Pragma("unroll") for (int n = 0; n < 2; ++n) _Pragma("unroll") for (int k = 0; k < 2; ++k) \
;         acc[ai][bj][m][n] = __builtin_amdgcn_mfma_f32_16x16x32_bf16(Bt[n][k], At[m][k], acc[ai][bj][m][n], 0, 0, 0); __builtin_amdgcn_s_setprio(0); } while (0)
; #define PG8_WAIT_V(n) asm volatile("s_waitcnt vmcnt(" #n ")" ::: "memory")
; #define PG8_WAIT_L(n) asm volatile("s_waitcnt lgkmcnt(" #n ")" ::: "memory")
; #define PG8_BAR __builtin_amdgcn_s_barrier()
; #define PG8_SCHED __builtin_amdgcn_sched_barrier(0)
; template <class Epi, class Sched, bool ALIGN_EPI = false, bool SP2 = false, bool ABLK = false, bool BBLK = false>
; __device__ __forceinline__ void gemm_phase(PG8_LAS unsigned char* lds, const Gemm g, const Sched& S, const Epi& E) {
;     ...
;             PG8_LDA(At, 0, 1); PG8_STAGE(PG8_SB(0, 0), b2, voffB); PG8_STAGE(PG8_SB(0, 1), b2 + hstepB, voffB); PG8_STAGE(PG8_SA(0, 0), a2, voffA);
;             PG8_WAIT_V(8); PG8_WAIT_L(0); PG8_BAR; PG8_MMA(1, 0, At, B0); PG8_MMA(1, 1, At, B1); PG8_BAR; PG8_SCHED;
	s_add_i32 s75, s75, s41
	v_lshl_add_u64 v[142:143], s[26:27], 0, v[134:135]
	s_mov_b32 m0, s75
	ds_read_b128 v[180:183], v146 offset:16384
	ds_read_b128 v[196:199], v146 offset:17408
	ds_read_b128 v[200:203], v146 offset:18432
	ds_read_b128 v[204:207], v146 offset:19456
	ds_read_b128 v[208:211], v146 offset:20480
	ds_read_b128 v[212:215], v146 offset:21504
	ds_read_b128 v[216:219], v146 offset:22528
	ds_read_b128 v[220:223], v146 offset:23552
	global_load_lds_dwordx4 v[142:143], off
	s_add_i32 m0, s75, 0x2000
	s_add_u32 s82, s26, 0x4000
	v_lshl_add_u64 v[142:143], s[26:27], 0, v[130:131]
	s_addc_u32 s83, s27, 0
	s_add_i32 s75, s80, s41
	global_load_lds_dwordx4 v[142:143], off
	v_lshl_add_u64 v[142:143], s[82:83], 0, v[134:135]
	s_mov_b32 m0, s75
	s_nop 0
	global_load_lds_dwordx4 v[142:143], off
	v_lshl_add_u64 v[142:143], s[82:83], 0, v[130:131]
	s_add_i32 m0, s75, 0x2000
	s_nop 0
	global_load_lds_dwordx4 v[142:143], off
	v_lshl_add_u64 v[142:143], s[28:29], 0, v[136:137]
	s_mov_b32 m0, s43
	s_nop 0
	global_load_lds_dwordx4 v[142:143], off
	v_lshl_add_u64 v[142:143], s[28:29], 0, v[132:133]
	s_mov_b32 m0, s44
	s_nop 0
	global_load_lds_dwordx4 v[142:143], off
	s_waitcnt vmcnt(8)
	s_waitcnt lgkmcnt(0)
	s_barrier
	s_setprio 1
	s_waitcnt lgkmcnt(0)
	v_mfma_f32_16x16x32_bf16 v[62:65], v[148:151], v[180:183], 0
	v_mfma_f32_16x16x32_bf16 v[54:57], v[156:159], v[180:183], 0
	v_mfma_f32_16x16x32_bf16 v[46:49], v[148:151], v[200:203], 0
	v_mfma_f32_16x16x32_bf16 v[38:41], v[156:159], v[200:203], 0
	v_mfma_f32_16x16x32_bf16 v[30:33], v[148:151], v[208:211], 0
	v_mfma_f32_16x16x32_bf16 v[22:25], v[156:159], v[208:211], 0
	v_mfma_f32_16x16x32_bf16 v[14:17], v[148:151], v[216:219], 0
	v_mfma_f32_16x16x32_bf16 v[6:9], v[156:159], v[216:219], 0
	v_mfma_f32_16x16x32_bf16 v[62:65], v[152:155], v[196:199], v[62:65]
	v_mfma_f32_16x16x32_bf16 v[54:57], v[160:163], v[196:199], v[54:57]
	v_mfma_f32_16x16x32_bf16 v[46:49], v[152:155], v[204:207], v[46:49]
	v_mfma_f32_16x16x32_bf16 v[38:41], v[160:163], v[204:207], v[38:41]
	v_mfma_f32_16x16x32_bf16 v[30:33], v[152:155], v[212:215], v[30:33]
	v_mfma_f32_16x16x32_bf16 v[22:25], v[160:163], v[212:215], v[22:25]
	v_mfma_f32_16x16x32_bf16 v[14:17], v[152:155], v[220:223], v[14:17]
	v_mfma_f32_16x16x32_bf16 v[6:9], v[160:163], v[220:223], v[6:9]
	s_setprio 0
	s_setprio 1
	v_mfma_f32_16x16x32_bf16 v[58:61], v[164:167], v[180:183], 0
	v_mfma_f32_16x16x32_bf16 v[50:53], v[172:175], v[180:183], 0
	v_mfma_f32_16x16x32_bf16 v[42:45], v[164:167], v[200:203], 0
	v_mfma_f32_16x16x32_bf16 v[34:37], v[172:175], v[200:203], 0
	v_mfma_f32_16x16x32_bf16 v[26:29], v[164:167], v[208:211], 0
	v_mfma_f32_16x16x32_bf16 v[18:21], v[172:175], v[208:211], 0
	v_mfma_f32_16x16x32_bf16 v[10:13], v[164:167], v[216:219], 0
	v_mfma_f32_16x16x32_bf16 v[2:5], v[172:175], v[216:219], 0
	v_mfma_f32_16x16x32_bf16 v[58:61], v[168:171], v[196:199], v[58:61]
	v_mfma_f32_16x16x32_bf16 v[50:53], v[176:179], v[196:199], v[50:53]
	v_mfma_f32_16x16x32_bf16 v[42:45], v[168:171], v[204:207], v[42:45]
	v_mfma_f32_16x16x32_bf16 v[34:37], v[176:179], v[204:207], v[34:37]
	v_mfma_f32_16x16x32_bf16 v[26:29], v[168:171], v[212:215], v[26:29]
	v_mfma_f32_16x16x32_bf16 v[18:21], v[176:179], v[212:215], v[18:21]
	v_mfma_f32_16x16x32_bf16 v[10:13], v[168:171], v[220:223], v[10:13]
	v_mfma_f32_16x16x32_bf16 v[2:5], v[176:179], v[220:223], v[2:5]
	s_setprio 0
	s_barrier
	s_branch .Lmid_216

; #define PG8_STAGE(bufoff, gbase, voff) do { _Pragma("unroll") for (int _i = 0; _i < 2; ++_i) \
;         __builtin_amdgcn_global_load_lds((const unsigned*)((const char*)(gbase) + (voff)[_i]), (PG8_LAS unsigned*)(lds + (bufoff) + ldsw + _i * 8192), 16, 0, 0); } while (0)
; #define PG8_LDA(dst, b, h) do { _Pragma("unroll") for (int m = 0; m < 4; ++m) _Pragma("unroll") for (int k = 0; k < 2; ++k) dst[m][k] = *(const PG8_LAS bf16x8*)(lds + PG8_SA(b, h) + aoff + m * 2048 + k * 1024); } while (0)
; #define PG8_LDB(dst, b, h) do { _Pragma("unroll") for (int n = 0; n < 2; ++n) _Pragma("unroll") for (int k = 0; k < 2; ++k) dst[n][k] = *(const PG8_LAS bf16x8*)(lds + PG8_SB(b, h) + boff + n * 2048 + k * 1024); } while (0)
; #define PG8_WAIT_V(n) asm volatile("s_waitcnt vmcnt(" #n ")" ::: "memory")
; #define PG8_WAIT_L(n) asm volatile("s_waitcnt lgkmcnt(" #n ")" ::: "memory")
; #define PG8_BAR __builtin_amdgcn_s_barrier()
; #define PG8_SCHED __builtin_amdgcn_sched_barrier(0)
; template <class Epi, class Sched, bool ALIGN_EPI = false, bool SP2 = false, bool ABLK = false, bool BBLK = false>
; __device__ __forceinline__ void gemm_phase(PG8_LAS unsigned char* lds, const Gemm g, const Sched& S, const Epi& E) {
;     ...
;         const bool has_next = S.next(ui + 1, nxt);
;         const char* nA = has_next ? (const char*)g.A + (size_t)nxt.pm * tstepA : cA; const char* nB = has_next ? (const char*)g.Bt + (size_t)nxt.pn * tstepB : cB;
;         for (int t = 0; t < nt; t += 2) {
;             const bool last = (t == nt - 2);
;             const char* a1 = cA + (size_t)(t + 1) * kstepA;
;             const char* a2 = last ? nA : cA + (size_t)(t + 2) * kstepA; const char* b2 = last ? nB : cB + (size_t)(t + 2) * kstepB;
;             const char* a3 = a2 + kstepA; const char* b3 = b2 + kstepB;
;             if (last && has_next) S.a_ready(nxt);
;             if constexpr (SP2) {
;             PG8_LDB(B0, 0, 0); PG8_LDB(B1, 0, 1); PG8_SCHED; PG8_LDA(At, 0, 0); PG8_STAGE(PG8_SA(1, 1), a1 + hstepA, voffA);
;             PG8_WAIT_V(8); PG8_WAIT_L(0); PG8_BAR; PG8_MMA(0, 0, At, B0); PG8_MMA(0, 1, At, B1); PG8_BAR; PG8_SCHED;
;             PG8_LDA(At, 0, 1); PG8_STAGE(PG8_SB(0, 0), b2, voffB); PG8_STAGE(PG8_SB(0, 1), b2 + hstepB, voffB); PG8_STAGE(PG8_SA(0, 0), a2, voffA);
;             PG8_WAIT_V(8); PG8_WAIT_L(0); PG8_BAR; PG8_MMA(1, 0, At, B0); PG8_MMA(1, 1, At, B1); PG8_BAR; PG8_SCHED;
.LBB0_304:
	s_add_u32 s0, s0, 0xc000
	s_addc_u32 s1, s1, 0
	s_add_u32 s29, s34, 0x10000
	s_addc_u32 s31, s35, 0
	s_mov_b32 s33, -2
	s_add_u32 s8, s0, 0x4000
	s_addc_u32 s9, s1, 0
	s_cmpk_eq_i32 s33, 0x54
	s_cselect_b32 s36, s24, s8
	s_cselect_b32 s37, s25, s9
	s_cselect_b32 s34, s26, s29
	s_cselect_b32 s35, s27, s31
	s_add_u32 s8, s36, 0x8000
	s_addc_u32 s9, s37, 0
	s_add_i32 s40, 0, 0x10000
	s_add_i32 s44, 0, 0x14000
	v_add_u32_e32 v142, s40, v206
	v_add_u32_e32 v158, s44, v206
	ds_read_b128 v[130:133], v142
	ds_read_b128 v[134:137], v142 offset:1024
	ds_read_b128 v[138:141], v142 offset:2048
	ds_read_b128 v[142:145], v142 offset:3072
	ds_read_b128 v[146:149], v158
	ds_read_b128 v[150:153], v158 offset:1024
	ds_read_b128 v[154:157], v158 offset:2048
	ds_read_b128 v[158:161], v158 offset:3072
	v_lshl_add_u64 v[202:203], s[0:1], 0, v[184:185]
	s_add_i32 m0, s3, 0xc000
	ds_read_b128 v[162:165], v207
	ds_read_b128 v[166:169], v207 offset:1024
	ds_read_b128 v[170:173], v207 offset:2048
	ds_read_b128 v[174:177], v207 offset:3072
	ds_read_b128 v[198:201], v207 offset:4096
	ds_read_b128 v[208:211], v207 offset:5120
	ds_read_b128 v[212:215], v207 offset:6144
	ds_read_b128 v[216:219], v207 offset:7168
	global_load_lds_dwordx4 v[202:203], off
	v_lshl_add_u64 v[202:203], s[0:1], 0, v[196:197]
	s_add_i32 m0, s3, 0xe000
	s_nop 0
	global_load_lds_dwordx4 v[202:203], off
	s_waitcnt vmcnt(8)
	s_waitcnt lgkmcnt(0)
	s_barrier
	s_setprio 1
	s_waitcnt lgkmcnt(0)
	v_mfma_f32_16x16x32_bf16 v[30:33], v[130:133], v[162:165], 0
	v_mfma_f32_16x16x32_bf16 v[22:25], v[138:141], v[162:165], 0
	v_mfma_f32_16x16x32_bf16 v[10:13], v[130:133], v[170:173], 0
	v_mfma_f32_16x16x32_bf16 v[6:9], v[138:141], v[170:173], 0
	v_mfma_f32_16x16x32_bf16 v[50:53], v[130:133], v[198:201], 0
	v_mfma_f32_16x16x32_bf16 v[54:57], v[138:141], v[198:201], 0
	v_mfma_f32_16x16x32_bf16 v[74:77], v[130:133], v[212:215], 0
	v_mfma_f32_16x16x32_bf16 v[78:81], v[138:141], v[212:215], 0
	v_mfma_f32_16x16x32_bf16 v[30:33], v[134:137], v[166:169], v[30:33]
	v_mfma_f32_16x16x32_bf16 v[22:25], v[142:145], v[166:169], v[22:25]
	v_mfma_f32_16x16x32_bf16 v[10:13], v[134:137], v[174:177], v[10:13]
	v_mfma_f32_16x16x32_bf16 v[6:9], v[142:145], v[174:177], v[6:9]
	v_mfma_f32_16x16x32_bf16 v[50:53], v[134:137], v[208:211], v[50:53]
	v_mfma_f32_16x16x32_bf16 v[54:57], v[142:145], v[208:211], v[54:57]
	v_mfma_f32_16x16x32_bf16 v[74:77], v[134:137], v[216:219], v[74:77]
	v_mfma_f32_16x16x32_bf16 v[78:81], v[142:145], v[216:219], v[78:81]
	s_setprio 0
	s_setprio 1
	v_mfma_f32_16x16x32_bf16 v[26:29], v[146:149], v[162:165], 0
	v_mfma_f32_16x16x32_bf16 v[18:21], v[154:157], v[162:165], 0
	v_mfma_f32_16x16x32_bf16 v[42:45], v[146:149], v[170:173], 0
	v_mfma_f32_16x16x32_bf16 v[46:49], v[154:157], v[170:173], 0
	v_mfma_f32_16x16x32_bf16 v[66:69], v[146:149], v[198:201], 0
	v_mfma_f32_16x16x32_bf16 v[70:73], v[154:157], v[198:201], 0
	v_mfma_f32_16x16x32_bf16 v[82:85], v[146:149], v[212:215], 0
	v_mfma_f32_16x16x32_bf16 v[86:89], v[154:157], v[212:215], 0
	v_mfma_f32_16x16x32_bf16 v[26:29], v[150:153], v[166:169], v[26:29]
	v_mfma_f32_16x16x32_bf16 v[18:21], v[158:161], v[166:169], v[18:21]
	v_mfma_f32_16x16x32_bf16 v[42:45], v[150:153], v[174:177], v[42:45]
	v_mfma_f32_16x16x32_bf16 v[46:49], v[158:161], v[174:177], v[46:49]
	v_mfma_f32_16x16x32_bf16 v[66:69], v[150:153], v[208:211], v[66:69]
	v_mfma_f32_16x16x32_bf16 v[70:73], v[158:161], v[208:211], v[70:73]
	v_mfma_f32_16x16x32_bf16 v[82:85], v[150:153], v[216:219], v[82:85]
	v_mfma_f32_16x16x32_bf16 v[86:89], v[158:161], v[216:219], v[86:89]
	s_setprio 0
	s_barrier
; #define PG8_STAGE(bufoff, gbase, voff) do { _Pragma("unroll") for (int _i = 0; _i < 2; ++_i) \
;         __builtin_amdgcn_global_load_lds((const unsigned*)((const char*)(gbase) + (voff)[_i]), (PG8_LAS unsigned*)(lds + (bufoff) + ldsw + _i * 8192), 16, 0, 0); } while (0)
; #define PG8_LDA(dst, b, h) do { _Pragma("unroll") for (int m = 0; m < 4; ++m) _Pragma("unroll") for (int k = 0; k < 2; ++k) dst[m][k] = *(const PG8_LAS bf16x8*)(lds + PG8_SA(b, h) + aoff + m * 2048 + k * 1024); } while (0)
; #define PG8_MMA(ai, bj, At, Bt) do { __builtin_amdgcn_s_setprio(1); _Pragma("unroll") for (int m = 0; m < 4; ++m) _Pragma("unroll") for (int n = 0; n < 2; ++n) _Pragma("unroll") for (int k = 0; k < 2; ++k) \
;         acc[ai][bj][m][n] = __builtin_amdgcn_mfma_f32_16x16x32_bf16(Bt[n][k], At[m][k], acc[ai][bj][m][n], 0, 0, 0); __builtin_amdgcn_s_setprio(0); } while (0)
; #define PG8_WAIT_V(n) asm volatile("s_waitcnt vmcnt(" #n ")" ::: "memory")
; #define PG8_WAIT_L(n) asm volatile("s_waitcnt lgkmcnt(" #n ")" ::: "memory")
; #define PG8_BAR __builtin_amdgcn_s_barrier()
; #define PG8_SCHED __builtin_amdgcn_sched_barrier(0)
; template <class Epi, class Sched, bool ALIGN_EPI = false, bool SP2 = false, bool ABLK = false, bool BBLK = false>
; __device__ __forceinline__ void gemm_phase(PG8_LAS unsigned char* lds, const Gemm g, const Sched& S, const Epi& E) {
;     ...
;             PG8_LDA(At, 0, 1); PG8_STAGE(PG8_SB(0, 0), b2, voffB); PG8_STAGE(PG8_SB(0, 1), b2 + hstepB, voffB); PG8_STAGE(PG8_SA(0, 0), a2, voffA);
;             PG8_WAIT_V(8); PG8_WAIT_L(0); PG8_BAR; PG8_MMA(1, 0, At, B0); PG8_MMA(1, 1, At, B1); PG8_BAR; PG8_SCHED;
	s_add_i32 s40, s40, s2
	v_lshl_add_u64 v[202:203], s[34:35], 0, v[186:187]
	s_mov_b32 m0, s40
	ds_read_b128 v[162:165], v207 offset:16384
	ds_read_b128 v[166:169], v207 offset:17408
	ds_read_b128 v[170:173], v207 offset:18432
	ds_read_b128 v[174:177], v207 offset:19456
	ds_read_b128 v[198:201], v207 offset:20480
	ds_read_b128 v[208:211], v207 offset:21504
	ds_read_b128 v[212:215], v207 offset:22528
	ds_read_b128 v[216:219], v207 offset:23552
	global_load_lds_dwordx4 v[202:203], off
	s_add_i32 m0, s40, 0x2000
	s_add_u32 s40, s34, 0x4000
	v_lshl_add_u64 v[202:203], s[34:35], 0, v[182:183]
	s_addc_u32 s41, s35, 0
	s_add_i32 s44, s44, s2
	global_load_lds_dwordx4 v[202:203], off
	v_lshl_add_u64 v[202:203], s[40:41], 0, v[186:187]
	s_mov_b32 m0, s44
	s_nop 0
	global_load_lds_dwordx4 v[202:203], off
	v_lshl_add_u64 v[202:203], s[40:41], 0, v[182:183]
	s_add_i32 m0, s44, 0x2000
	s_nop 0
	global_load_lds_dwordx4 v[202:203], off
	v_lshl_add_u64 v[202:203], s[36:37], 0, v[178:179]
	s_mov_b32 m0, s3
	s_nop 0
	global_load_lds_dwordx4 v[202:203], off
	v_lshl_add_u64 v[202:203], s[36:37], 0, v[180:181]
	s_mov_b32 m0, s42
	s_nop 0
	global_load_lds_dwordx4 v[202:203], off
	s_waitcnt vmcnt(8)
	s_waitcnt lgkmcnt(0)
	s_barrier
	s_setprio 1
	s_waitcnt lgkmcnt(0)
	v_mfma_f32_16x16x32_bf16 v[106:109], v[130:133], v[162:165], 0
	v_mfma_f32_16x16x32_bf16 v[110:113], v[138:141], v[162:165], 0
	v_mfma_f32_16x16x32_bf16 v[122:125], v[130:133], v[170:173], 0
	v_mfma_f32_16x16x32_bf16 v[126:129], v[138:141], v[170:173], 0
	v_mfma_f32_16x16x32_bf16 v[94:97], v[130:133], v[198:201], 0
	v_mfma_f32_16x16x32_bf16 v[90:93], v[138:141], v[198:201], 0
	v_mfma_f32_16x16x32_bf16 v[38:41], v[130:133], v[212:215], 0
	v_mfma_f32_16x16x32_bf16 v[34:37], v[138:141], v[212:215], 0
	v_mfma_f32_16x16x32_bf16 v[106:109], v[134:137], v[166:169], v[106:109]
	v_mfma_f32_16x16x32_bf16 v[110:113], v[142:145], v[166:169], v[110:113]
	v_mfma_f32_16x16x32_bf16 v[122:125], v[134:137], v[174:177], v[122:125]
	v_mfma_f32_16x16x32_bf16 v[126:129], v[142:145], v[174:177], v[126:129]
	v_mfma_f32_16x16x32_bf16 v[94:97], v[134:137], v[208:211], v[94:97]
	v_mfma_f32_16x16x32_bf16 v[90:93], v[142:145], v[208:211], v[90:93]
	v_mfma_f32_16x16x32_bf16 v[38:41], v[134:137], v[216:219], v[38:41]
	v_mfma_f32_16x16x32_bf16 v[34:37], v[142:145], v[216:219], v[34:37]
	s_setprio 0
	s_setprio 1
	v_mfma_f32_16x16x32_bf16 v[114:117], v[146:149], v[162:165], 0
	v_mfma_f32_16x16x32_bf16 v[118:121], v[154:157], v[162:165], 0
	v_mfma_f32_16x16x32_bf16 v[102:105], v[146:149], v[170:173], 0
	v_mfma_f32_16x16x32_bf16 v[98:101], v[154:157], v[170:173], 0
	v_mfma_f32_16x16x32_bf16 v[62:65], v[146:149], v[198:201], 0
	v_mfma_f32_16x16x32_bf16 v[58:61], v[154:157], v[198:201], 0
	v_mfma_f32_16x16x32_bf16 v[14:17], v[146:149], v[212:215], 0
	v_mfma_f32_16x16x32_bf16 v[2:5], v[154:157], v[212:215], 0
	v_mfma_f32_16x16x32_bf16 v[114:117], v[150:153], v[166:169], v[114:117]
	v_mfma_f32_16x16x32_bf16 v[118:121], v[158:161], v[166:169], v[118:121]
	v_mfma_f32_16x16x32_bf16 v[102:105], v[150:153], v[174:177], v[102:105]
	v_mfma_f32_16x16x32_bf16 v[98:101], v[158:161], v[174:177], v[98:101]
	v_mfma_f32_16x16x32_bf16 v[62:65], v[150:153], v[208:211], v[62:65]
	v_mfma_f32_16x16x32_bf16 v[58:61], v[158:161], v[208:211], v[58:61]
	v_mfma_f32_16x16x32_bf16 v[14:17], v[150:153], v[216:219], v[14:17]
	v_mfma_f32_16x16x32_bf16 v[2:5], v[158:161], v[216:219], v[2:5]
	s_setprio 0
	s_barrier
	s_branch .Lmid_305

; #define PG8_STAGE(bufoff, gbase, voff) do { _Pragma("unroll") for (int _i = 0; _i < 2; ++_i) \
;         __builtin_amdgcn_global_load_lds((const unsigned*)((const char*)(gbase) + (voff)[_i]), (PG8_LAS unsigned*)(lds + (bufoff) + ldsw + _i * 8192), 16, 0, 0); } while (0)
; #define PG8_LDA(dst, b, h) do { _Pragma("unroll") for (int m = 0; m < 4; ++m) _Pragma("unroll") for (int k = 0; k < 2; ++k) dst[m][k] = *(const PG8_LAS bf16x8*)(lds + PG8_SA(b, h) + aoff + m * 2048 + k * 1024); } while (0)
; #define PG8_LDB(dst, b, h) do { _Pragma("unroll") for (int n = 0; n < 2; ++n) _Pragma("unroll") for (int k = 0; k < 2; ++k) dst[n][k] = *(const PG8_LAS bf16x8*)(lds + PG8_SB(b, h) + boff + n * 2048 + k * 1024); } while (0)
; #define PG8_WAIT_V(n) asm volatile("s_waitcnt vmcnt(" #n ")" ::: "memory")
; #define PG8_WAIT_L(n) asm volatile("s_waitcnt lgkmcnt(" #n ")" ::: "memory")
;     __device__ __forceinline__ void operator()(const f32x4 (&acc)[2][2][4][2], const Unit& u, int wr, int wc, int fr_, int fq) const {
;     ...
;         f32x4 bv[2][2];
; #pragma unroll
;         for (int bj = 0; bj < 2; ++bj)
; #pragma unroll
;             for (int n = 0; n < 2; ++n) bv[bj][n] = *(const f32x4*)(bmg + (gate ? colt : 0) + cl + bj * HALF + 4 * n) * (gate ? 1.0f : 0.0f);
; template <class Epi, class Sched, bool ALIGN_EPI = false, bool SP2 = false, bool ABLK = false, bool BBLK = false>
; __device__ __forceinline__ void gemm_phase(PG8_LAS unsigned char* lds, const Gemm g, const Sched& S, const Epi& E) {
;     ...
;         const char* nA = has_next ? (const char*)g.A + (size_t)nxt.pm * tstepA : cA; const char* nB = has_next ? (const char*)g.Bt + (size_t)nxt.pn * tstepB : cB;
;         for (int t = 0; t < nt; t += 2) {
;             const bool last = (t == nt - 2);
;             const char* a1 = cA + (size_t)(t + 1) * kstepA;
;             const char* a2 = last ? nA : cA + (size_t)(t + 2) * kstepA; const char* b2 = last ? nB : cB + (size_t)(t + 2) * kstepB;
;             const char* a3 = a2 + kstepA; const char* b3 = b2 + kstepB;
;             if (last && has_next) S.a_ready(nxt);
;             if constexpr (SP2) {
;             PG8_LDB(B0, 0, 0); PG8_LDB(B1, 0, 1); PG8_SCHED; PG8_LDA(At, 0, 0); PG8_STAGE(PG8_SA(1, 1), a1 + hstepA, voffA);
;             PG8_WAIT_V(8); PG8_WAIT_L(0); PG8_BAR; PG8_MMA(0, 0, At, B0); PG8_MMA(0, 1, At, B1); PG8_BAR; PG8_SCHED;
.LBB0_593:
	s_ashr_i32 s21, s20, 31
	s_lshl_b64 s[24:25], s[20:21], 20
	s_add_u32 s24, s51, s24
	s_addc_u32 s25, s53, s25
	s_and_b64 s[26:27], s[6:7], exec
	s_cselect_b32 s9, s25, s1
	s_cselect_b32 s16, s24, s0
	s_ashr_i32 s23, s22, 31
	s_lshl_b64 s[26:27], s[22:23], 20
	s_add_u32 s26, s44, s26
	s_addc_u32 s27, s45, s27
	s_and_b64 s[34:35], s[6:7], exec
	s_cselect_b32 s21, s27, s31
	s_cselect_b32 s23, s26, s30
	s_add_u32 s0, s0, 0xc000
	s_addc_u32 s1, s1, 0
	s_add_u32 s29, s30, 0x10000
	s_addc_u32 s40, s31, 0
	s_mov_b32 s41, -2
	s_waitcnt vmcnt(0)
	s_lshl_b32 s100, s8, 8
	s_add_i32 s100, s100, 0xfffff200
	s_cmp_gt_i32 s8, 13
	s_cselect_b32 s100, s100, 0
	s_ashr_i32 s101, s100, 31
	v_lshl_add_u64 v[250:251], s[100:101], 2, v[154:155]
	global_load_dwordx4 v[224:227], v[250:251], off
	global_load_dwordx4 v[246:249], v[250:251], off offset:16
	global_load_dwordx4 v[188:191], v[250:251], off offset:528
	s_nop 0
	global_load_dwordx4 v[250:253], v[250:251], off offset:512
	s_add_u32 s30, s0, 0x4000
	s_addc_u32 s31, s1, 0
	s_cmp_eq_u32 s41, 28
	s_cselect_b32 s36, s16, s30
	s_cselect_b32 s37, s9, s31
	s_cselect_b32 s34, s23, s29
	s_cselect_b32 s35, s21, s40
	s_add_u32 s30, s36, 0x8000
	s_addc_u32 s31, s37, 0
	s_add_i32 s60, 0, 0x10000
	s_add_i32 s75, 0, 0x14000
	v_add_u32_e32 v142, s60, v169
	v_add_u32_e32 v171, s75, v169
	ds_read_b128 v[130:133], v142
	ds_read_b128 v[134:137], v142 offset:1024
	ds_read_b128 v[138:141], v142 offset:2048
	ds_read_b128 v[142:145], v142 offset:3072
	ds_read_b128 v[160:163], v171
	ds_read_b128 v[164:167], v171 offset:1024
	ds_read_b128 v[172:175], v171 offset:2048
	ds_read_b128 v[176:179], v171 offset:3072
	v_lshl_add_u64 v[184:185], s[0:1], 0, v[156:157]
	s_add_i32 m0, s83, 0xc000
	ds_read_b128 v[180:183], v170
	ds_read_b128 v[196:199], v170 offset:1024
	ds_read_b128 v[200:203], v170 offset:2048
	ds_read_b128 v[204:207], v170 offset:3072
	ds_read_b128 v[208:211], v170 offset:4096
	ds_read_b128 v[212:215], v170 offset:5120
	ds_read_b128 v[216:219], v170 offset:6144
	ds_read_b128 v[220:223], v170 offset:7168
	global_load_lds_dwordx4 v[184:185], off
	v_lshl_add_u64 v[184:185], s[0:1], 0, v[158:159]
	s_add_i32 m0, s83, 0xe000
	s_nop 0
	global_load_lds_dwordx4 v[184:185], off
	s_waitcnt vmcnt(8)
	s_waitcnt lgkmcnt(0)
	s_barrier
	s_setprio 1
	s_waitcnt lgkmcnt(0)
	v_mfma_f32_16x16x32_bf16 v[126:129], v[130:133], v[180:183], 0
	v_mfma_f32_16x16x32_bf16 v[122:125], v[138:141], v[180:183], 0
	v_mfma_f32_16x16x32_bf16 v[110:113], v[130:133], v[200:203], 0
	v_mfma_f32_16x16x32_bf16 v[106:109], v[138:141], v[200:203], 0
	v_mfma_f32_16x16x32_bf16 v[94:97], v[130:133], v[208:211], 0
	v_mfma_f32_16x16x32_bf16 v[90:93], v[138:141], v[208:211], 0
	v_mfma_f32_16x16x32_bf16 v[78:81], v[130:133], v[216:219], 0
	v_mfma_f32_16x16x32_bf16 v[74:77], v[138:141], v[216:219], 0
	v_mfma_f32_16x16x32_bf16 v[126:129], v[134:137], v[196:199], v[126:129]
	v_mfma_f32_16x16x32_bf16 v[122:125], v[142:145], v[196:199], v[122:125]
	v_mfma_f32_16x16x32_bf16 v[110:113], v[134:137], v[204:207], v[110:113]
	v_mfma_f32_16x16x32_bf16 v[106:109], v[142:145], v[204:207], v[106:109]
	v_mfma_f32_16x16x32_bf16 v[94:97], v[134:137], v[212:215], v[94:97]
	v_mfma_f32_16x16x32_bf16 v[90:93], v[142:145], v[212:215], v[90:93]
	v_mfma_f32_16x16x32_bf16 v[78:81], v[134:137], v[220:223], v[78:81]
	v_mfma_f32_16x16x32_bf16 v[74:77], v[142:145], v[220:223], v[74:77]
	s_setprio 0
	s_setprio 1
	v_mfma_f32_16x16x32_bf16 v[118:121], v[160:163], v[180:183], 0
	v_mfma_f32_16x16x32_bf16 v[114:117], v[172:175], v[180:183], 0
	v_mfma_f32_16x16x32_bf16 v[102:105], v[160:163], v[200:203], 0
	v_mfma_f32_16x16x32_bf16 v[98:101], v[172:175], v[200:203], 0
	v_mfma_f32_16x16x32_bf16 v[86:89], v[160:163], v[208:211], 0
	v_mfma_f32_16x16x32_bf16 v[82:85], v[172:175], v[208:211], 0
	v_mfma_f32_16x16x32_bf16 v[70:73], v[160:163], v[216:219], 0
	v_mfma_f32_16x16x32_bf16 v[66:69], v[172:175], v[216:219], 0
	v_mfma_f32_16x16x32_bf16 v[118:121], v[164:167], v[196:199], v[118:121]
	v_mfma_f32_16x16x32_bf16 v[114:117], v[176:179], v[196:199], v[114:117]
	v_mfma_f32_16x16x32_bf16 v[102:105], v[164:167], v[204:207], v[102:105]
	v_mfma_f32_16x16x32_bf16 v[98:101], v[176:179], v[204:207], v[98:101]
	v_mfma_f32_16x16x32_bf16 v[86:89], v[164:167], v[212:215], v[86:89]
	v_mfma_f32_16x16x32_bf16 v[82:85], v[176:179], v[212:215], v[82:85]
	v_mfma_f32_16x16x32_bf16 v[70:73], v[164:167], v[220:223], v[70:73]
	v_mfma_f32_16x16x32_bf16 v[66:69], v[176:179], v[220:223], v[66:69]
	s_setprio 0
	s_barrier
; #define PG8_STAGE(bufoff, gbase, voff) do { _Pragma("unroll") for (int _i = 0; _i < 2; ++_i) \
;         __builtin_amdgcn_global_load_lds((const unsigned*)((const char*)(gbase) + (voff)[_i]), (PG8_LAS unsigned*)(lds + (bufoff) + ldsw + _i * 8192), 16, 0, 0); } while (0)
; #define PG8_LDA(dst, b, h) do { _Pragma("unroll") for (int m = 0; m < 4; ++m) _Pragma("unroll") for (int k = 0; k < 2; ++k) dst[m][k] = *(const PG8_LAS bf16x8*)(lds + PG8_SA(b, h) + aoff + m * 2048 + k * 1024); } while (0)
; #define PG8_MMA(ai, bj, At, Bt) do { __builtin_amdgcn_s_setprio(1); _Pragma("unroll") for (int m = 0; m < 4; ++m) _Pragma("unroll") for (int n = 0; n < 2; ++n) _Pragma("unroll") for (int k = 0; k < 2; ++k) \
;         acc[ai][bj][m][n] = __builtin_amdgcn_mfma_f32_16x16x32_bf16(Bt[n][k], At[m][k], acc[ai][bj][m][n], 0, 0, 0); __builtin_amdgcn_s_setprio(0); } while (0)
; #define PG8_WAIT_V(n) asm volatile("s_waitcnt vmcnt(" #n ")" ::: "memory")
; #define PG8_WAIT_L(n) asm volatile("s_waitcnt lgkmcnt(" #n ")" ::: "memory")
; #define PG8_BAR __builtin_amdgcn_s_barrier()
; #define PG8_SCHED __builtin_amdgcn_sched_barrier(0)
; template <class Epi, class Sched, bool ALIGN_EPI = false, bool SP2 = false, bool ABLK = false, bool BBLK = false>
; __device__ __forceinline__ void gemm_phase(PG8_LAS unsigned char* lds, const Gemm g, const Sched& S, const Epi& E) {
;     ...
;             PG8_LDA(At, 0, 1); PG8_STAGE(PG8_SB(0, 0), b2, voffB); PG8_STAGE(PG8_SB(0, 1), b2 + hstepB, voffB); PG8_STAGE(PG8_SA(0, 0), a2, voffA);
;             PG8_WAIT_V(8); PG8_WAIT_L(0); PG8_BAR; PG8_MMA(1, 0, At, B0); PG8_MMA(1, 1, At, B1); PG8_BAR; PG8_SCHED;
	s_add_i32 s60, s60, s81
	v_lshl_add_u64 v[184:185], s[34:35], 0, v[148:149]
	s_mov_b32 m0, s60
	ds_read_b128 v[180:183], v170 offset:16384
	ds_read_b128 v[196:199], v170 offset:17408
	ds_read_b128 v[200:203], v170 offset:18432
	ds_read_b128 v[204:207], v170 offset:19456
	ds_read_b128 v[208:211], v170 offset:20480
	ds_read_b128 v[212:215], v170 offset:21504
	ds_read_b128 v[216:219], v170 offset:22528
	ds_read_b128 v[220:223], v170 offset:23552
	global_load_lds_dwordx4 v[184:185], off
	s_add_i32 m0, s60, 0x2000
	s_add_u32 s60, s34, 0x4000
	v_lshl_add_u64 v[184:185], s[34:35], 0, v[152:153]
	s_addc_u32 s61, s35, 0
	s_add_i32 s75, s75, s81
	global_load_lds_dwordx4 v[184:185], off
	v_lshl_add_u64 v[184:185], s[60:61], 0, v[148:149]
	s_mov_b32 m0, s75
	s_nop 0
	global_load_lds_dwordx4 v[184:185], off
	v_lshl_add_u64 v[184:185], s[60:61], 0, v[152:153]
	s_add_i32 m0, s75, 0x2000
	s_nop 0
	global_load_lds_dwordx4 v[184:185], off
	v_lshl_add_u64 v[184:185], s[36:37], 0, v[146:147]
	s_mov_b32 m0, s83
	s_nop 0
	global_load_lds_dwordx4 v[184:185], off
	v_lshl_add_u64 v[184:185], s[36:37], 0, v[150:151]
	s_mov_b32 m0, s84
	s_nop 0
	global_load_lds_dwordx4 v[184:185], off
	s_waitcnt vmcnt(8)
	s_waitcnt lgkmcnt(0)
	s_barrier
	s_setprio 1
	s_waitcnt lgkmcnt(0)
	v_mfma_f32_16x16x32_bf16 v[62:65], v[130:133], v[180:183], 0
	v_mfma_f32_16x16x32_bf16 v[58:61], v[138:141], v[180:183], 0
	v_mfma_f32_16x16x32_bf16 v[46:49], v[130:133], v[200:203], 0
	v_mfma_f32_16x16x32_bf16 v[42:45], v[138:141], v[200:203], 0
	v_mfma_f32_16x16x32_bf16 v[30:33], v[130:133], v[208:211], 0
	v_mfma_f32_16x16x32_bf16 v[26:29], v[138:141], v[208:211], 0
	v_mfma_f32_16x16x32_bf16 v[14:17], v[130:133], v[216:219], 0
	v_mfma_f32_16x16x32_bf16 v[10:13], v[138:141], v[216:219], 0
	v_mfma_f32_16x16x32_bf16 v[62:65], v[134:137], v[196:199], v[62:65]
	v_mfma_f32_16x16x32_bf16 v[58:61], v[142:145], v[196:199], v[58:61]
	v_mfma_f32_16x16x32_bf16 v[46:49], v[134:137], v[204:207], v[46:49]
	v_mfma_f32_16x16x32_bf16 v[42:45], v[142:145], v[204:207], v[42:45]
	v_mfma_f32_16x16x32_bf16 v[30:33], v[134:137], v[212:215], v[30:33]
	v_mfma_f32_16x16x32_bf16 v[26:29], v[142:145], v[212:215], v[26:29]
	v_mfma_f32_16x16x32_bf16 v[14:17], v[134:137], v[220:223], v[14:17]
	v_mfma_f32_16x16x32_bf16 v[10:13], v[142:145], v[220:223], v[10:13]
	s_setprio 0
	s_setprio 1
	v_mfma_f32_16x16x32_bf16 v[54:57], v[160:163], v[180:183], 0
	v_mfma_f32_16x16x32_bf16 v[50:53], v[172:175], v[180:183], 0
	v_mfma_f32_16x16x32_bf16 v[38:41], v[160:163], v[200:203], 0
	v_mfma_f32_16x16x32_bf16 v[34:37], v[172:175], v[200:203], 0
	v_mfma_f32_16x16x32_bf16 v[22:25], v[160:163], v[208:211], 0
	v_mfma_f32_16x16x32_bf16 v[18:21], v[172:175], v[208:211], 0
	v_mfma_f32_16x16x32_bf16 v[6:9], v[160:163], v[216:219], 0
	v_mfma_f32_16x16x32_bf16 v[2:5], v[172:175], v[216:219], 0
	v_mfma_f32_16x16x32_bf16 v[54:57], v[164:167], v[196:199], v[54:57]
	v_mfma_f32_16x16x32_bf16 v[50:53], v[176:179], v[196:199], v[50:53]
	v_mfma_f32_16x16x32_bf16 v[38:41], v[164:167], v[204:207], v[38:41]
	v_mfma_f32_16x16x32_bf16 v[34:37], v[176:179], v[204:207], v[34:37]
	v_mfma_f32_16x16x32_bf16 v[22:25], v[164:167], v[212:215], v[22:25]
	v_mfma_f32_16x16x32_bf16 v[18:21], v[176:179], v[212:215], v[18:21]
	v_mfma_f32_16x16x32_bf16 v[6:9], v[164:167], v[220:223], v[6:9]
	v_mfma_f32_16x16x32_bf16 v[2:5], v[176:179], v[220:223], v[2:5]
	s_setprio 0
	s_barrier
	s_branch .Lmid_594

; #define PG8_STAGE(bufoff, gbase, voff) do { _Pragma("unroll") for (int _i = 0; _i < 2; ++_i) \
;         __builtin_amdgcn_global_load_lds((const unsigned*)((const char*)(gbase) + (voff)[_i]), (PG8_LAS unsigned*)(lds + (bufoff) + ldsw + _i * 8192), 16, 0, 0); } while (0)
; #define PG8_LDA(dst, b, h) do { _Pragma("unroll") for (int m = 0; m < 4; ++m) _Pragma("unroll") for (int k = 0; k < 2; ++k) dst[m][k] = *(const PG8_LAS bf16x8*)(lds + PG8_SA(b, h) + aoff + m * 2048 + k * 1024); } while (0)
; #define PG8_LDB(dst, b, h) do { _Pragma("unroll") for (int n = 0; n < 2; ++n) _Pragma("unroll") for (int k = 0; k < 2; ++k) dst[n][k] = *(const PG8_LAS bf16x8*)(lds + PG8_SB(b, h) + boff + n * 2048 + k * 1024); } while (0)
; #define PG8_MMA(ai, bj, At, Bt) do { __builtin_amdgcn_s_setprio(1); _Pragma("unroll") for (int m = 0; m < 4; ++m) _Pragma("unroll") for (int n = 0; n < 2; ++n) _Pragma("unroll") for (int k = 0; k < 2; ++k) \
;         acc[ai][bj][m][n] = __builtin_amdgcn_mfma_f32_16x16x32_bf16(Bt[n][k], At[m][k], acc[ai][bj][m][n], 0, 0, 0); __builtin_amdgcn_s_setprio(0); } while (0)
; #define PG8_WAIT_V(n) asm volatile("s_waitcnt vmcnt(" #n ")" ::: "memory")
; #define PG8_WAIT_L(n) asm volatile("s_waitcnt lgkmcnt(" #n ")" ::: "memory")
; #define PG8_BAR __builtin_amdgcn_s_barrier()
; template <class Epi, class Sched, bool ALIGN_EPI = false, bool SP2 = false, bool ABLK = false, bool BBLK = false>
; __device__ __forceinline__ void gemm_phase(PG8_LAS unsigned char* lds, const Gemm g, const Sched& S, const Epi& E) {
;     ...
;         const char* nA = has_next ? (const char*)g.A + (size_t)nxt.pm * tstepA : cA; const char* nB = has_next ? (const char*)g.Bt + (size_t)nxt.pn * tstepB : cB;
;         for (int t = 0; t < nt; t += 2) {
;             const bool last = (t == nt - 2);
;             const char* a1 = cA + (size_t)(t + 1) * kstepA;
;             const char* a2 = last ? nA : cA + (size_t)(t + 2) * kstepA; const char* b2 = last ? nB : cB + (size_t)(t + 2) * kstepB;
;             const char* a3 = a2 + kstepA; const char* b3 = b2 + kstepB;
;             if (last && has_next) S.a_ready(nxt);
;             if constexpr (SP2) {
;             PG8_LDB(B0, 0, 0); PG8_LDB(B1, 0, 1); PG8_SCHED; PG8_LDA(At, 0, 0); PG8_STAGE(PG8_SA(1, 1), a1 + hstepA, voffA);
;             PG8_WAIT_V(8); PG8_WAIT_L(0); PG8_BAR; PG8_MMA(0, 0, At, B0); PG8_MMA(0, 1, At, B1); PG8_BAR; PG8_SCHED;
.LBB0_657:
	s_ashr_i32 s13, s12, 31
	s_lshl_b64 s[14:15], s[12:13], 20
	s_add_u32 s14, s31, s14
	s_addc_u32 s15, s33, s15
	s_and_b64 s[18:19], s[6:7], exec
	s_cselect_b32 s13, s15, s23
	s_cselect_b32 s61, s14, s22
	s_ashr_i32 s1, s0, 31
	s_lshl_b64 s[18:19], s[0:1], 20
	s_add_u32 s18, s51, s18
	s_addc_u32 s19, s53, s19
	s_and_b64 s[26:27], s[6:7], exec
	s_cselect_b32 s1, s19, s25
	s_cselect_b32 s65, s18, s24
	s_add_u32 s22, s22, 0xc000
	s_addc_u32 s23, s23, 0
	s_add_u32 s68, s24, 0x10000
	s_addc_u32 s72, s25, 0
	s_mov_b32 s73, -2
	s_add_u32 s24, s22, 0x4000
	s_addc_u32 s25, s23, 0
	s_cmp_eq_u32 s73, 28
	s_cselect_b32 s28, s61, s24
	s_cselect_b32 s29, s13, s25
	s_cselect_b32 s26, s65, s68
	s_cselect_b32 s27, s1, s72
	s_add_u32 s24, s28, 0x8000
	s_addc_u32 s25, s29, 0
	s_add_i32 s75, 0, 0x10000
	s_add_i32 s82, 0, 0x14000
	v_add_u32_e32 v158, s75, v147
	v_add_u32_e32 v174, s82, v147
	ds_read_b128 v[142:145], v158
	ds_read_b128 v[150:153], v158 offset:1024
	ds_read_b128 v[154:157], v158 offset:2048
	ds_read_b128 v[158:161], v158 offset:3072
	ds_read_b128 v[162:165], v174
	ds_read_b128 v[166:169], v174 offset:1024
	ds_read_b128 v[170:173], v174 offset:2048
	ds_read_b128 v[174:177], v174 offset:3072
	v_lshl_add_u64 v[220:221], s[22:23], 0, v[138:139]
	s_add_i32 m0, s40, 0xc000
	ds_read_b128 v[178:181], v149
	ds_read_b128 v[182:185], v149 offset:1024
	ds_read_b128 v[196:199], v149 offset:2048
	ds_read_b128 v[200:203], v149 offset:3072
	ds_read_b128 v[204:207], v149 offset:4096
	ds_read_b128 v[208:211], v149 offset:5120
	ds_read_b128 v[212:215], v149 offset:6144
	ds_read_b128 v[216:219], v149 offset:7168
	global_load_lds_dwordx4 v[220:221], off
	v_lshl_add_u64 v[220:221], s[22:23], 0, v[140:141]
	s_add_i32 m0, s40, 0xe000
	s_nop 0
	global_load_lds_dwordx4 v[220:221], off
	s_waitcnt vmcnt(8)
	s_waitcnt lgkmcnt(0)
	s_barrier
	s_setprio 1
	s_waitcnt lgkmcnt(0)
	v_mfma_f32_16x16x32_bf16 v[126:129], v[142:145], v[178:181], 0
	v_mfma_f32_16x16x32_bf16 v[122:125], v[154:157], v[178:181], 0
	v_mfma_f32_16x16x32_bf16 v[114:117], v[142:145], v[196:199], 0
	v_mfma_f32_16x16x32_bf16 v[106:109], v[154:157], v[196:199], 0
	v_mfma_f32_16x16x32_bf16 v[102:105], v[142:145], v[204:207], 0
	v_mfma_f32_16x16x32_bf16 v[94:97], v[154:157], v[204:207], 0
	v_mfma_f32_16x16x32_bf16 v[86:89], v[142:145], v[212:215], 0
	v_mfma_f32_16x16x32_bf16 v[78:81], v[154:157], v[212:215], 0
	v_mfma_f32_16x16x32_bf16 v[126:129], v[150:153], v[182:185], v[126:129]
	v_mfma_f32_16x16x32_bf16 v[122:125], v[158:161], v[182:185], v[122:125]
	v_mfma_f32_16x16x32_bf16 v[114:117], v[150:153], v[200:203], v[114:117]
	v_mfma_f32_16x16x32_bf16 v[106:109], v[158:161], v[200:203], v[106:109]
	v_mfma_f32_16x16x32_bf16 v[102:105], v[150:153], v[208:211], v[102:105]
	v_mfma_f32_16x16x32_bf16 v[94:97], v[158:161], v[208:211], v[94:97]
	v_mfma_f32_16x16x32_bf16 v[86:89], v[150:153], v[216:219], v[86:89]
	v_mfma_f32_16x16x32_bf16 v[78:81], v[158:161], v[216:219], v[78:81]
	s_setprio 0
	s_setprio 1
	v_mfma_f32_16x16x32_bf16 v[118:121], v[162:165], v[178:181], 0
	v_mfma_f32_16x16x32_bf16 v[110:113], v[170:173], v[178:181], 0
	v_mfma_f32_16x16x32_bf16 v[98:101], v[162:165], v[196:199], 0
	v_mfma_f32_16x16x32_bf16 v[90:93], v[170:173], v[196:199], 0
	v_mfma_f32_16x16x32_bf16 v[82:85], v[162:165], v[204:207], 0
	v_mfma_f32_16x16x32_bf16 v[74:77], v[170:173], v[204:207], 0
	v_mfma_f32_16x16x32_bf16 v[70:73], v[162:165], v[212:215], 0
	v_mfma_f32_16x16x32_bf16 v[66:69], v[170:173], v[212:215], 0
	v_mfma_f32_16x16x32_bf16 v[118:121], v[166:169], v[182:185], v[118:121]
	v_mfma_f32_16x16x32_bf16 v[110:113], v[174:177], v[182:185], v[110:113]
	v_mfma_f32_16x16x32_bf16 v[98:101], v[166:169], v[200:203], v[98:101]
	v_mfma_f32_16x16x32_bf16 v[90:93], v[174:177], v[200:203], v[90:93]
	v_mfma_f32_16x16x32_bf16 v[82:85], v[166:169], v[208:211], v[82:85]
	v_mfma_f32_16x16x32_bf16 v[74:77], v[174:177], v[208:211], v[74:77]
	v_mfma_f32_16x16x32_bf16 v[70:73], v[166:169], v[216:219], v[70:73]
	v_mfma_f32_16x16x32_bf16 v[66:69], v[174:177], v[216:219], v[66:69]
	s_setprio 0
	s_barrier
; #define PG8_STAGE(bufoff, gbase, voff) do { _Pragma("unroll") for (int _i = 0; _i < 2; ++_i) \
;         __builtin_amdgcn_global_load_lds((const unsigned*)((const char*)(gbase) + (voff)[_i]), (PG8_LAS unsigned*)(lds + (bufoff) + ldsw + _i * 8192), 16, 0, 0); } while (0)
; #define PG8_LDA(dst, b, h) do { _Pragma("unroll") for (int m = 0; m < 4; ++m) _Pragma("unroll") for (int k = 0; k < 2; ++k) dst[m][k] = *(const PG8_LAS bf16x8*)(lds + PG8_SA(b, h) + aoff + m * 2048 + k * 1024); } while (0)
; #define PG8_MMA(ai, bj, At, Bt) do { __builtin_amdgcn_s_setprio(1); _Pragma("unroll") for (int m = 0; m < 4; ++m) _Pragma("unroll") for (int n = 0; n < 2; ++n) _Pragma("unroll") for (int k = 0; k < 2; ++k) \
;         acc[ai][bj][m][n] = __builtin_amdgcn_mfma_f32_16x16x32_bf16(Bt[n][k], At[m][k], acc[ai][bj][m][n], 0, 0, 0); __builtin_amdgcn_s_setprio(0); } while (0)
; #define PG8_WAIT_V(n) asm volatile("s_waitcnt vmcnt(" #n ")" ::: "memory")
; #define PG8_WAIT_L(n) asm volatile("s_waitcnt lgkmcnt(" #n ")" ::: "memory")
; #define PG8_BAR __builtin_amdgcn_s_barrier()
; #define PG8_SCHED __builtin_amdgcn_sched_barrier(0)
; template <class Epi, class Sched, bool ALIGN_EPI = false, bool SP2 = false, bool ABLK = false, bool BBLK = false>
; __device__ __forceinline__ void gemm_phase(PG8_LAS unsigned char* lds, const Gemm g, const Sched& S, const Epi& E) {
;     ...
;             PG8_LDA(At, 0, 1); PG8_STAGE(PG8_SB(0, 0), b2, voffB); PG8_STAGE(PG8_SB(0, 1), b2 + hstepB, voffB); PG8_STAGE(PG8_SA(0, 0), a2, voffA);
;             PG8_WAIT_V(8); PG8_WAIT_L(0); PG8_BAR; PG8_MMA(1, 0, At, B0); PG8_MMA(1, 1, At, B1); PG8_BAR; PG8_SCHED;
	s_add_i32 s75, s75, s37
	v_lshl_add_u64 v[220:221], s[26:27], 0, v[134:135]
	s_mov_b32 m0, s75
	ds_read_b128 v[178:181], v149 offset:16384
	ds_read_b128 v[182:185], v149 offset:17408
	ds_read_b128 v[196:199], v149 offset:18432
	ds_read_b128 v[200:203], v149 offset:19456
	ds_read_b128 v[204:207], v149 offset:20480
	ds_read_b128 v[208:211], v149 offset:21504
	ds_read_b128 v[212:215], v149 offset:22528
	ds_read_b128 v[216:219], v149 offset:23552
	global_load_lds_dwordx4 v[220:221], off
	s_add_i32 m0, s75, 0x2000
	s_add_u32 s80, s26, 0x4000
	v_lshl_add_u64 v[220:221], s[26:27], 0, v[130:131]
	s_addc_u32 s81, s27, 0
	s_add_i32 s75, s82, s37
	global_load_lds_dwordx4 v[220:221], off
	v_lshl_add_u64 v[220:221], s[80:81], 0, v[134:135]
	s_mov_b32 m0, s75
	s_nop 0
	global_load_lds_dwordx4 v[220:221], off
	v_lshl_add_u64 v[220:221], s[80:81], 0, v[130:131]
	s_add_i32 m0, s75, 0x2000
	s_nop 0
	global_load_lds_dwordx4 v[220:221], off
	v_lshl_add_u64 v[220:221], s[28:29], 0, v[136:137]
	s_mov_b32 m0, s40
	s_nop 0
	global_load_lds_dwordx4 v[220:221], off
	v_lshl_add_u64 v[220:221], s[28:29], 0, v[132:133]
	s_mov_b32 m0, s41
	s_nop 0
	global_load_lds_dwordx4 v[220:221], off
	s_waitcnt vmcnt(8)
	s_waitcnt lgkmcnt(0)
	s_barrier
	s_setprio 1
	s_waitcnt lgkmcnt(0)
	v_mfma_f32_16x16x32_bf16 v[62:65], v[142:145], v[178:181], 0
	v_mfma_f32_16x16x32_bf16 v[58:61], v[154:157], v[178:181], 0
	v_mfma_f32_16x16x32_bf16 v[50:53], v[142:145], v[196:199], 0
	v_mfma_f32_16x16x32_bf16 v[42:45], v[154:157], v[196:199], 0
	v_mfma_f32_16x16x32_bf16 v[38:41], v[142:145], v[204:207], 0
	v_mfma_f32_16x16x32_bf16 v[30:33], v[154:157], v[204:207], 0
	v_mfma_f32_16x16x32_bf16 v[22:25], v[142:145], v[212:215], 0
	v_mfma_f32_16x16x32_bf16 v[14:17], v[154:157], v[212:215], 0
	v_mfma_f32_16x16x32_bf16 v[62:65], v[150:153], v[182:185], v[62:65]
	v_mfma_f32_16x16x32_bf16 v[58:61], v[158:161], v[182:185], v[58:61]
	v_mfma_f32_16x16x32_bf16 v[50:53], v[150:153], v[200:203], v[50:53]
	v_mfma_f32_16x16x32_bf16 v[42:45], v[158:161], v[200:203], v[42:45]
	v_mfma_f32_16x16x32_bf16 v[38:41], v[150:153], v[208:211], v[38:41]
	v_mfma_f32_16x16x32_bf16 v[30:33], v[158:161], v[208:211], v[30:33]
	v_mfma_f32_16x16x32_bf16 v[22:25], v[150:153], v[216:219], v[22:25]
	v_mfma_f32_16x16x32_bf16 v[14:17], v[158:161], v[216:219], v[14:17]
	s_setprio 0
	s_setprio 1
	v_mfma_f32_16x16x32_bf16 v[54:57], v[162:165], v[178:181], 0
	v_mfma_f32_16x16x32_bf16 v[46:49], v[170:173], v[178:181], 0
	v_mfma_f32_16x16x32_bf16 v[34:37], v[162:165], v[196:199], 0
	v_mfma_f32_16x16x32_bf16 v[26:29], v[170:173], v[196:199], 0
	v_mfma_f32_16x16x32_bf16 v[18:21], v[162:165], v[204:207], 0
	v_mfma_f32_16x16x32_bf16 v[10:13], v[170:173], v[204:207], 0
	v_mfma_f32_16x16x32_bf16 v[6:9], v[162:165], v[212:215], 0
	v_mfma_f32_16x16x32_bf16 v[2:5], v[170:173], v[212:215], 0
	v_mfma_f32_16x16x32_bf16 v[54:57], v[166:169], v[182:185], v[54:57]
	v_mfma_f32_16x16x32_bf16 v[46:49], v[174:177], v[182:185], v[46:49]
	v_mfma_f32_16x16x32_bf16 v[34:37], v[166:169], v[200:203], v[34:37]
	v_mfma_f32_16x16x32_bf16 v[26:29], v[174:177], v[200:203], v[26:29]
	v_mfma_f32_16x16x32_bf16 v[18:21], v[166:169], v[208:211], v[18:21]
	v_mfma_f32_16x16x32_bf16 v[10:13], v[174:177], v[208:211], v[10:13]
	v_mfma_f32_16x16x32_bf16 v[6:9], v[166:169], v[216:219], v[6:9]
	v_mfma_f32_16x16x32_bf16 v[2:5], v[174:177], v[216:219], v[2:5]
	s_setprio 0
	s_barrier
	s_branch .Lmid_658

; #define PG8_STAGE(bufoff, gbase, voff) do { _Pragma("unroll") for (int _i = 0; _i < 2; ++_i) \
;         __builtin_amdgcn_global_load_lds((const unsigned*)((const char*)(gbase) + (voff)[_i]), (PG8_LAS unsigned*)(lds + (bufoff) + ldsw + _i * 8192), 16, 0, 0); } while (0)
; #define PG8_LDA(dst, b, h) do { _Pragma("unroll") for (int m = 0; m < 4; ++m) _Pragma("unroll") for (int k = 0; k < 2; ++k) dst[m][k] = *(const PG8_LAS bf16x8*)(lds + PG8_SA(b, h) + aoff + m * 2048 + k * 1024); } while (0)
; #define PG8_LDB(dst, b, h) do { _Pragma("unroll") for (int n = 0; n < 2; ++n) _Pragma("unroll") for (int k = 0; k < 2; ++k) dst[n][k] = *(const PG8_LAS bf16x8*)(lds + PG8_SB(b, h) + boff + n * 2048 + k * 1024); } while (0)
; #define PG8_MMA(ai, bj, At, Bt) do { __builtin_amdgcn_s_setprio(1); _Pragma("unroll") for (int m = 0; m < 4; ++m) _Pragma("unroll") for (int n = 0; n < 2; ++n) _Pragma("unroll") for (int k = 0; k < 2; ++k) \
;         acc[ai][bj][m][n] = __builtin_amdgcn_mfma_f32_16x16x32_bf16(Bt[n][k], At[m][k], acc[ai][bj][m][n], 0, 0, 0); __builtin_amdgcn_s_setprio(0); } while (0)
; #define PG8_WAIT_V(n) asm volatile("s_waitcnt vmcnt(" #n ")" ::: "memory")
; #define PG8_WAIT_L(n) asm volatile("s_waitcnt lgkmcnt(" #n ")" ::: "memory")
; #define PG8_BAR __builtin_amdgcn_s_barrier()
; template <class Epi, class Sched, bool ALIGN_EPI = false, bool SP2 = false, bool ABLK = false, bool BBLK = false>
; __device__ __forceinline__ void gemm_phase(PG8_LAS unsigned char* lds, const Gemm g, const Sched& S, const Epi& E) {
;     ...
;         const char* nA = has_next ? (const char*)g.A + (size_t)nxt.pm * tstepA : cA; const char* nB = has_next ? (const char*)g.Bt + (size_t)nxt.pn * tstepB : cB;
;         for (int t = 0; t < nt; t += 2) {
;             const bool last = (t == nt - 2);
;             const char* a1 = cA + (size_t)(t + 1) * kstepA;
;             const char* a2 = last ? nA : cA + (size_t)(t + 2) * kstepA; const char* b2 = last ? nB : cB + (size_t)(t + 2) * kstepB;
;             const char* a3 = a2 + kstepA; const char* b3 = b2 + kstepB;
;             if (last && has_next) S.a_ready(nxt);
;             if constexpr (SP2) {
;             PG8_LDB(B0, 0, 0); PG8_LDB(B1, 0, 1); PG8_SCHED; PG8_LDA(At, 0, 0); PG8_STAGE(PG8_SA(1, 1), a1 + hstepA, voffA);
;             PG8_WAIT_V(8); PG8_WAIT_L(0); PG8_BAR; PG8_MMA(0, 0, At, B0); PG8_MMA(0, 1, At, B1); PG8_BAR; PG8_SCHED;
.LBB0_765:
	s_ashr_i32 s15, s14, 31
	s_lshl_b64 s[18:19], s[14:15], 20
	s_add_u32 s18, s33, s18
	s_addc_u32 s19, s34, s19
	s_and_b64 s[20:21], s[6:7], exec
	s_cselect_b32 s1, s19, s25
	s_cselect_b32 s11, s18, s24
	s_ashr_i32 s13, s12, 31
	s_lshl_b64 s[20:21], s[12:13], 20
	s_add_u32 s20, s35, s20
	s_addc_u32 s21, s36, s21
	s_and_b64 s[28:29], s[6:7], exec
	s_cselect_b32 s13, s21, s27
	s_cselect_b32 s15, s20, s26
	s_add_u32 s24, s24, 0x80080
	s_addc_u32 s25, s25, 0
	s_add_u32 s23, s26, 0x100
	s_addc_u32 s65, s27, 0
	s_mov_b32 s68, -2
	s_add_u32 s26, s24, 0xfff80080
	s_addc_u32 s27, s25, -1
	s_add_i32 s72, 0, 0x10000
	s_cmp_eq_u32 s68, 28
	s_cselect_b32 s29, s1, s27
	s_cselect_b32 s28, s11, s26
	v_add_u32_e32 v142, s72, v145
	s_cselect_b32 s27, s13, s65
	s_cselect_b32 s26, s15, s23
	s_add_i32 s75, 0, 0x14000
	ds_read_b128 v[148:151], v142
	ds_read_b128 v[152:155], v142 offset:1024
	ds_read_b128 v[156:159], v142 offset:2048
	ds_read_b128 v[160:163], v142 offset:3072
	v_add_u32_e32 v142, s75, v145
	ds_read_b128 v[164:167], v142
	ds_read_b128 v[168:171], v142 offset:1024
	ds_read_b128 v[172:175], v142 offset:2048
	ds_read_b128 v[176:179], v142 offset:3072
	v_lshl_add_u64 v[142:143], s[24:25], 0, v[138:139]
	s_add_i32 m0, s45, 0xc000
	ds_read_b128 v[180:183], v146
	ds_read_b128 v[196:199], v146 offset:1024
	ds_read_b128 v[200:203], v146 offset:2048
	ds_read_b128 v[204:207], v146 offset:3072
	ds_read_b128 v[208:211], v146 offset:4096
	ds_read_b128 v[212:215], v146 offset:5120
	ds_read_b128 v[216:219], v146 offset:6144
	ds_read_b128 v[220:223], v146 offset:7168
	global_load_lds_dwordx4 v[142:143], off
	v_lshl_add_u64 v[142:143], s[24:25], 0, v[140:141]
	s_add_i32 m0, s45, 0xe000
	s_nop 0
	global_load_lds_dwordx4 v[142:143], off
	s_waitcnt vmcnt(8)
	s_waitcnt lgkmcnt(0)
	s_barrier
	s_setprio 1
	s_waitcnt lgkmcnt(0)
	v_mfma_f32_16x16x32_bf16 v[126:129], v[148:151], v[180:183], 0
	v_mfma_f32_16x16x32_bf16 v[122:125], v[156:159], v[180:183], 0
	v_mfma_f32_16x16x32_bf16 v[114:117], v[148:151], v[200:203], 0
	v_mfma_f32_16x16x32_bf16 v[106:109], v[156:159], v[200:203], 0
	v_mfma_f32_16x16x32_bf16 v[98:101], v[148:151], v[208:211], 0
	v_mfma_f32_16x16x32_bf16 v[90:93], v[156:159], v[208:211], 0
	v_mfma_f32_16x16x32_bf16 v[82:85], v[148:151], v[216:219], 0
	v_mfma_f32_16x16x32_bf16 v[74:77], v[156:159], v[216:219], 0
	v_mfma_f32_16x16x32_bf16 v[126:129], v[152:155], v[196:199], v[126:129]
	v_mfma_f32_16x16x32_bf16 v[122:125], v[160:163], v[196:199], v[122:125]
	v_mfma_f32_16x16x32_bf16 v[114:117], v[152:155], v[204:207], v[114:117]
	v_mfma_f32_16x16x32_bf16 v[106:109], v[160:163], v[204:207], v[106:109]
	v_mfma_f32_16x16x32_bf16 v[98:101], v[152:155], v[212:215], v[98:101]
	v_mfma_f32_16x16x32_bf16 v[90:93], v[160:163], v[212:215], v[90:93]
	v_mfma_f32_16x16x32_bf16 v[82:85], v[152:155], v[220:223], v[82:85]
	v_mfma_f32_16x16x32_bf16 v[74:77], v[160:163], v[220:223], v[74:77]
	s_setprio 0
	s_setprio 1
	v_mfma_f32_16x16x32_bf16 v[118:121], v[164:167], v[180:183], 0
	v_mfma_f32_16x16x32_bf16 v[110:113], v[172:175], v[180:183], 0
	v_mfma_f32_16x16x32_bf16 v[102:105], v[164:167], v[200:203], 0
	v_mfma_f32_16x16x32_bf16 v[94:97], v[172:175], v[200:203], 0
	v_mfma_f32_16x16x32_bf16 v[86:89], v[164:167], v[208:211], 0
	v_mfma_f32_16x16x32_bf16 v[78:81], v[172:175], v[208:211], 0
	v_mfma_f32_16x16x32_bf16 v[70:73], v[164:167], v[216:219], 0
	v_mfma_f32_16x16x32_bf16 v[66:69], v[172:175], v[216:219], 0
	v_mfma_f32_16x16x32_bf16 v[118:121], v[168:171], v[196:199], v[118:121]
	v_mfma_f32_16x16x32_bf16 v[110:113], v[176:179], v[196:199], v[110:113]
	v_mfma_f32_16x16x32_bf16 v[102:105], v[168:171], v[204:207], v[102:105]
	v_mfma_f32_16x16x32_bf16 v[94:97], v[176:179], v[204:207], v[94:97]
	v_mfma_f32_16x16x32_bf16 v[86:89], v[168:171], v[212:215], v[86:89]
	v_mfma_f32_16x16x32_bf16 v[78:81], v[176:179], v[212:215], v[78:81]
	v_mfma_f32_16x16x32_bf16 v[70:73], v[168:171], v[220:223], v[70:73]
	v_mfma_f32_16x16x32_bf16 v[66:69], v[176:179], v[220:223], v[66:69]
	s_setprio 0
	s_barrier
; #define PG8_STAGE(bufoff, gbase, voff) do { _Pragma("unroll") for (int _i = 0; _i < 2; ++_i) \
;         __builtin_amdgcn_global_load_lds((const unsigned*)((const char*)(gbase) + (voff)[_i]), (PG8_LAS unsigned*)(lds + (bufoff) + ldsw + _i * 8192), 16, 0, 0); } while (0)
; #define PG8_LDA(dst, b, h) do { _Pragma("unroll") for (int m = 0; m < 4; ++m) _Pragma("unroll") for (int k = 0; k < 2; ++k) dst[m][k] = *(const PG8_LAS bf16x8*)(lds + PG8_SA(b, h) + aoff + m * 2048 + k * 1024); } while (0)
; #define PG8_MMA(ai, bj, At, Bt) do { __builtin_amdgcn_s_setprio(1); _Pragma("unroll") for (int m = 0; m < 4; ++m) _Pragma("unroll") for (int n = 0; n < 2; ++n) _Pragma("unroll") for (int k = 0; k < 2; ++k) \
;         acc[ai][bj][m][n] = __builtin_amdgcn_mfma_f32_16x16x32_bf16(Bt[n][k], At[m][k], acc[ai][bj][m][n], 0, 0, 0); __builtin_amdgcn_s_setprio(0); } while (0)
; #define PG8_WAIT_V(n) asm volatile("s_waitcnt vmcnt(" #n ")" ::: "memory")
; #define PG8_WAIT_L(n) asm volatile("s_waitcnt lgkmcnt(" #n ")" ::: "memory")
; #define PG8_BAR __builtin_amdgcn_s_barrier()
; #define PG8_SCHED __builtin_amdgcn_sched_barrier(0)
; template <class Epi, class Sched, bool ALIGN_EPI = false, bool SP2 = false, bool ABLK = false, bool BBLK = false>
; __device__ __forceinline__ void gemm_phase(PG8_LAS unsigned char* lds, const Gemm g, const Sched& S, const Epi& E) {
;     ...
;             PG8_LDA(At, 0, 1); PG8_STAGE(PG8_SB(0, 0), b2, voffB); PG8_STAGE(PG8_SB(0, 1), b2 + hstepB, voffB); PG8_STAGE(PG8_SA(0, 0), a2, voffA);
;             PG8_WAIT_V(8); PG8_WAIT_L(0); PG8_BAR; PG8_MMA(1, 0, At, B0); PG8_MMA(1, 1, At, B1); PG8_BAR; PG8_SCHED;
	s_add_i32 s72, s72, s37
	v_lshl_add_u64 v[142:143], s[26:27], 0, v[134:135]
	s_mov_b32 m0, s72
	ds_read_b128 v[180:183], v146 offset:16384
	ds_read_b128 v[196:199], v146 offset:17408
	ds_read_b128 v[200:203], v146 offset:18432
	ds_read_b128 v[204:207], v146 offset:19456
	ds_read_b128 v[208:211], v146 offset:20480
	ds_read_b128 v[212:215], v146 offset:21504
	ds_read_b128 v[216:219], v146 offset:22528
	ds_read_b128 v[220:223], v146 offset:23552
	global_load_lds_dwordx4 v[142:143], off
	s_add_i32 m0, s72, 0x2000
	s_add_u32 s72, s26, 0x80000
	v_lshl_add_u64 v[184:185], s[26:27], 0, v[130:131]
	s_addc_u32 s73, s27, 0
	s_add_i32 s75, s75, s37
	global_load_lds_dwordx4 v[184:185], off
	v_lshl_add_u64 v[224:225], s[72:73], 0, v[134:135]
	s_mov_b32 m0, s75
	v_lshl_add_u64 v[226:227], s[28:29], 0, v[132:133]
	global_load_lds_dwordx4 v[224:225], off
	v_lshl_add_u64 v[224:225], s[72:73], 0, v[130:131]
	s_add_i32 m0, s75, 0x2000
	s_nop 0
	global_load_lds_dwordx4 v[224:225], off
	v_lshl_add_u64 v[224:225], s[28:29], 0, v[136:137]
	s_mov_b32 m0, s45
	s_nop 0
	global_load_lds_dwordx4 v[224:225], off
	s_mov_b32 m0, s46
	s_nop 0
	global_load_lds_dwordx4 v[226:227], off
	s_waitcnt vmcnt(8)
	s_waitcnt lgkmcnt(0)
	s_barrier
	s_setprio 1
	s_waitcnt lgkmcnt(0)
	v_mfma_f32_16x16x32_bf16 v[62:65], v[148:151], v[180:183], 0
	v_mfma_f32_16x16x32_bf16 v[58:61], v[156:159], v[180:183], 0
	v_mfma_f32_16x16x32_bf16 v[50:53], v[148:151], v[200:203], 0
	v_mfma_f32_16x16x32_bf16 v[42:45], v[156:159], v[200:203], 0
	v_mfma_f32_16x16x32_bf16 v[34:37], v[148:151], v[208:211], 0
	v_mfma_f32_16x16x32_bf16 v[26:29], v[156:159], v[208:211], 0
	v_mfma_f32_16x16x32_bf16 v[18:21], v[148:151], v[216:219], 0
	v_mfma_f32_16x16x32_bf16 v[10:13], v[156:159], v[216:219], 0
	v_mfma_f32_16x16x32_bf16 v[62:65], v[152:155], v[196:199], v[62:65]
	v_mfma_f32_16x16x32_bf16 v[58:61], v[160:163], v[196:199], v[58:61]
	v_mfma_f32_16x16x32_bf16 v[50:53], v[152:155], v[204:207], v[50:53]
	v_mfma_f32_16x16x32_bf16 v[42:45], v[160:163], v[204:207], v[42:45]
	v_mfma_f32_16x16x32_bf16 v[34:37], v[152:155], v[212:215], v[34:37]
	v_mfma_f32_16x16x32_bf16 v[26:29], v[160:163], v[212:215], v[26:29]
	v_mfma_f32_16x16x32_bf16 v[18:21], v[152:155], v[220:223], v[18:21]
	v_mfma_f32_16x16x32_bf16 v[10:13], v[160:163], v[220:223], v[10:13]
	s_setprio 0
	s_setprio 1
	v_mfma_f32_16x16x32_bf16 v[54:57], v[164:167], v[180:183], 0
	v_mfma_f32_16x16x32_bf16 v[46:49], v[172:175], v[180:183], 0
	v_mfma_f32_16x16x32_bf16 v[38:41], v[164:167], v[200:203], 0
	v_mfma_f32_16x16x32_bf16 v[30:33], v[172:175], v[200:203], 0
	v_mfma_f32_16x16x32_bf16 v[22:25], v[164:167], v[208:211], 0
	v_mfma_f32_16x16x32_bf16 v[14:17], v[172:175], v[208:211], 0
	v_mfma_f32_16x16x32_bf16 v[6:9], v[164:167], v[216:219], 0
	v_mfma_f32_16x16x32_bf16 v[2:5], v[172:175], v[216:219], 0
	v_mfma_f32_16x16x32_bf16 v[54:57], v[168:171], v[196:199], v[54:57]
	v_mfma_f32_16x16x32_bf16 v[46:49], v[176:179], v[196:199], v[46:49]
	v_mfma_f32_16x16x32_bf16 v[38:41], v[168:171], v[204:207], v[38:41]
	v_mfma_f32_16x16x32_bf16 v[30:33], v[176:179], v[204:207], v[30:33]
	v_mfma_f32_16x16x32_bf16 v[22:25], v[168:171], v[212:215], v[22:25]
	v_mfma_f32_16x16x32_bf16 v[14:17], v[176:179], v[212:215], v[14:17]
	v_mfma_f32_16x16x32_bf16 v[6:9], v[168:171], v[220:223], v[6:9]
	v_mfma_f32_16x16x32_bf16 v[2:5], v[176:179], v[220:223], v[2:5]
	s_setprio 0
	s_barrier
	s_branch .Lmid_766

; #define PG8_STAGE(bufoff, gbase, voff) do { _Pragma("unroll") for (int _i = 0; _i < 2; ++_i) \
;         __builtin_amdgcn_global_load_lds((const unsigned*)((const char*)(gbase) + (voff)[_i]), (PG8_LAS unsigned*)(lds + (bufoff) + ldsw + _i * 8192), 16, 0, 0); } while (0)
; #define PG8_LDA(dst, b, h) do { _Pragma("unroll") for (int m = 0; m < 4; ++m) _Pragma("unroll") for (int k = 0; k < 2; ++k) dst[m][k] = *(const PG8_LAS bf16x8*)(lds + PG8_SA(b, h) + aoff + m * 2048 + k * 1024); } while (0)
; #define PG8_LDB(dst, b, h) do { _Pragma("unroll") for (int n = 0; n < 2; ++n) _Pragma("unroll") for (int k = 0; k < 2; ++k) dst[n][k] = *(const PG8_LAS bf16x8*)(lds + PG8_SB(b, h) + boff + n * 2048 + k * 1024); } while (0)
; #define PG8_MMA(ai, bj, At, Bt) do { __builtin_amdgcn_s_setprio(1); _Pragma("unroll") for (int m = 0; m < 4; ++m) _Pragma("unroll") for (int n = 0; n < 2; ++n) _Pragma("unroll") for (int k = 0; k < 2; ++k) \
;         acc[ai][bj][m][n] = __builtin_amdgcn_mfma_f32_16x16x32_bf16(Bt[n][k], At[m][k], acc[ai][bj][m][n], 0, 0, 0); __builtin_amdgcn_s_setprio(0); } while (0)
; #define PG8_WAIT_V(n) asm volatile("s_waitcnt vmcnt(" #n ")" ::: "memory")
; #define PG8_WAIT_L(n) asm volatile("s_waitcnt lgkmcnt(" #n ")" ::: "memory")
; #define PG8_BAR __builtin_amdgcn_s_barrier()
; template <class Epi, class Sched, bool ALIGN_EPI = false, bool SP2 = false, bool ABLK = false, bool BBLK = false>
; __device__ __forceinline__ void gemm_phase(PG8_LAS unsigned char* lds, const Gemm g, const Sched& S, const Epi& E) {
;     ...
;         const char* nA = has_next ? (const char*)g.A + (size_t)nxt.pm * tstepA : cA; const char* nB = has_next ? (const char*)g.Bt + (size_t)nxt.pn * tstepB : cB;
;         for (int t = 0; t < nt; t += 2) {
;             const bool last = (t == nt - 2);
;             const char* a1 = cA + (size_t)(t + 1) * kstepA;
;             const char* a2 = last ? nA : cA + (size_t)(t + 2) * kstepA; const char* b2 = last ? nB : cB + (size_t)(t + 2) * kstepB;
;             const char* a3 = a2 + kstepA; const char* b3 = b2 + kstepB;
;             if (last && has_next) S.a_ready(nxt);
;             if constexpr (SP2) {
;             PG8_LDB(B0, 0, 0); PG8_LDB(B1, 0, 1); PG8_SCHED; PG8_LDA(At, 0, 0); PG8_STAGE(PG8_SA(1, 1), a1 + hstepA, voffA);
;             PG8_WAIT_V(8); PG8_WAIT_L(0); PG8_BAR; PG8_MMA(0, 0, At, B0); PG8_MMA(0, 1, At, B1); PG8_BAR; PG8_SCHED;
.LBB0_789:
	s_ashr_i32 s15, s14, 31
	s_lshl_b64 s[18:19], s[14:15], 20
	s_add_u32 s18, s36, s18
	s_addc_u32 s19, s37, s19
	s_and_b64 s[20:21], s[6:7], exec
	s_cselect_b32 s1, s19, s25
	s_cselect_b32 s11, s18, s24
	s_ashr_i32 s13, s12, 31
	s_lshl_b64 s[20:21], s[12:13], 20
	s_add_u32 s20, s44, s20
	s_addc_u32 s21, s45, s21
	s_and_b64 s[28:29], s[6:7], exec
	s_cselect_b32 s13, s21, s27
	s_cselect_b32 s15, s20, s26
	s_add_u32 s24, s24, 0x80080
	s_addc_u32 s25, s25, 0
	s_add_u32 s23, s26, 0x100
	s_addc_u32 s73, s27, 0
	s_mov_b32 s81, -2
	s_add_u32 s26, s24, 0xfff80080
	s_addc_u32 s27, s25, -1
	s_add_i32 s51, 0, 0x10000
	s_cmp_eq_u32 s81, 28
	s_cselect_b32 s29, s1, s27
	s_cselect_b32 s28, s11, s26
	v_add_u32_e32 v142, s51, v145
	s_cselect_b32 s27, s13, s73
	s_cselect_b32 s26, s15, s23
	s_add_i32 s75, 0, 0x14000
	ds_read_b128 v[148:151], v142
	ds_read_b128 v[152:155], v142 offset:1024
	ds_read_b128 v[156:159], v142 offset:2048
	ds_read_b128 v[160:163], v142 offset:3072
	v_add_u32_e32 v142, s75, v145
	ds_read_b128 v[164:167], v142
	ds_read_b128 v[168:171], v142 offset:1024
	ds_read_b128 v[172:175], v142 offset:2048
	ds_read_b128 v[176:179], v142 offset:3072
	v_lshl_add_u64 v[142:143], s[24:25], 0, v[138:139]
	s_add_i32 m0, s46, 0xc000
	ds_read_b128 v[180:183], v146
	ds_read_b128 v[196:199], v146 offset:1024
	ds_read_b128 v[200:203], v146 offset:2048
	ds_read_b128 v[204:207], v146 offset:3072
	ds_read_b128 v[208:211], v146 offset:4096
	ds_read_b128 v[212:215], v146 offset:5120
	ds_read_b128 v[216:219], v146 offset:6144
	ds_read_b128 v[220:223], v146 offset:7168
	global_load_lds_dwordx4 v[142:143], off
	v_lshl_add_u64 v[142:143], s[24:25], 0, v[140:141]
	s_add_i32 m0, s46, 0xe000
	s_nop 0
	global_load_lds_dwordx4 v[142:143], off
	s_waitcnt vmcnt(8)
	s_waitcnt lgkmcnt(0)
	s_barrier
	s_setprio 1
	s_waitcnt lgkmcnt(0)
	v_mfma_f32_16x16x32_bf16 v[126:129], v[148:151], v[180:183], 0
	v_mfma_f32_16x16x32_bf16 v[122:125], v[156:159], v[180:183], 0
	v_mfma_f32_16x16x32_bf16 v[114:117], v[148:151], v[200:203], 0
	v_mfma_f32_16x16x32_bf16 v[106:109], v[156:159], v[200:203], 0
	v_mfma_f32_16x16x32_bf16 v[98:101], v[148:151], v[208:211], 0
	v_mfma_f32_16x16x32_bf16 v[90:93], v[156:159], v[208:211], 0
	v_mfma_f32_16x16x32_bf16 v[82:85], v[148:151], v[216:219], 0
	v_mfma_f32_16x16x32_bf16 v[74:77], v[156:159], v[216:219], 0
	v_mfma_f32_16x16x32_bf16 v[126:129], v[152:155], v[196:199], v[126:129]
	v_mfma_f32_16x16x32_bf16 v[122:125], v[160:163], v[196:199], v[122:125]
	v_mfma_f32_16x16x32_bf16 v[114:117], v[152:155], v[204:207], v[114:117]
	v_mfma_f32_16x16x32_bf16 v[106:109], v[160:163], v[204:207], v[106:109]
	v_mfma_f32_16x16x32_bf16 v[98:101], v[152:155], v[212:215], v[98:101]
	v_mfma_f32_16x16x32_bf16 v[90:93], v[160:163], v[212:215], v[90:93]
	v_mfma_f32_16x16x32_bf16 v[82:85], v[152:155], v[220:223], v[82:85]
	v_mfma_f32_16x16x32_bf16 v[74:77], v[160:163], v[220:223], v[74:77]
	s_setprio 0
	s_setprio 1
	v_mfma_f32_16x16x32_bf16 v[118:121], v[164:167], v[180:183], 0
	v_mfma_f32_16x16x32_bf16 v[110:113], v[172:175], v[180:183], 0
	v_mfma_f32_16x16x32_bf16 v[102:105], v[164:167], v[200:203], 0
	v_mfma_f32_16x16x32_bf16 v[94:97], v[172:175], v[200:203], 0
	v_mfma_f32_16x16x32_bf16 v[86:89], v[164:167], v[208:211], 0
	v_mfma_f32_16x16x32_bf16 v[78:81], v[172:175], v[208:211], 0
	v_mfma_f32_16x16x32_bf16 v[70:73], v[164:167], v[216:219], 0
	v_mfma_f32_16x16x32_bf16 v[66:69], v[172:175], v[216:219], 0
	v_mfma_f32_16x16x32_bf16 v[118:121], v[168:171], v[196:199], v[118:121]
	v_mfma_f32_16x16x32_bf16 v[110:113], v[176:179], v[196:199], v[110:113]
	v_mfma_f32_16x16x32_bf16 v[102:105], v[168:171], v[204:207], v[102:105]
	v_mfma_f32_16x16x32_bf16 v[94:97], v[176:179], v[204:207], v[94:97]
	v_mfma_f32_16x16x32_bf16 v[86:89], v[168:171], v[212:215], v[86:89]
	v_mfma_f32_16x16x32_bf16 v[78:81], v[176:179], v[212:215], v[78:81]
	v_mfma_f32_16x16x32_bf16 v[70:73], v[168:171], v[220:223], v[70:73]
	v_mfma_f32_16x16x32_bf16 v[66:69], v[176:179], v[220:223], v[66:69]
	s_setprio 0
	s_barrier
; #define PG8_STAGE(bufoff, gbase, voff) do { _Pragma("unroll") for (int _i = 0; _i < 2; ++_i) \
;         __builtin_amdgcn_global_load_lds((const unsigned*)((const char*)(gbase) + (voff)[_i]), (PG8_LAS unsigned*)(lds + (bufoff) + ldsw + _i * 8192), 16, 0, 0); } while (0)
; #define PG8_LDA(dst, b, h) do { _Pragma("unroll") for (int m = 0; m < 4; ++m) _Pragma("unroll") for (int k = 0; k < 2; ++k) dst[m][k] = *(const PG8_LAS bf16x8*)(lds + PG8_SA(b, h) + aoff + m * 2048 + k * 1024); } while (0)
; #define PG8_MMA(ai, bj, At, Bt) do { __builtin_amdgcn_s_setprio(1); _Pragma("unroll") for (int m = 0; m < 4; ++m) _Pragma("unroll") for (int n = 0; n < 2; ++n) _Pragma("unroll") for (int k = 0; k < 2; ++k) \
;         acc[ai][bj][m][n] = __builtin_amdgcn_mfma_f32_16x16x32_bf16(Bt[n][k], At[m][k], acc[ai][bj][m][n], 0, 0, 0); __builtin_amdgcn_s_setprio(0); } while (0)
; #define PG8_WAIT_V(n) asm volatile("s_waitcnt vmcnt(" #n ")" ::: "memory")
; #define PG8_WAIT_L(n) asm volatile("s_waitcnt lgkmcnt(" #n ")" ::: "memory")
; #define PG8_BAR __builtin_amdgcn_s_barrier()
; #define PG8_SCHED __builtin_amdgcn_sched_barrier(0)
; template <class Epi, class Sched, bool ALIGN_EPI = false, bool SP2 = false, bool ABLK = false, bool BBLK = false>
; __device__ __forceinline__ void gemm_phase(PG8_LAS unsigned char* lds, const Gemm g, const Sched& S, const Epi& E) {
;     ...
;             PG8_LDA(At, 0, 1); PG8_STAGE(PG8_SB(0, 0), b2, voffB); PG8_STAGE(PG8_SB(0, 1), b2 + hstepB, voffB); PG8_STAGE(PG8_SA(0, 0), a2, voffA);
;             PG8_WAIT_V(8); PG8_WAIT_L(0); PG8_BAR; PG8_MMA(1, 0, At, B0); PG8_MMA(1, 1, At, B1); PG8_BAR; PG8_SCHED;
	s_add_i32 s51, s51, s35
	v_lshl_add_u64 v[142:143], s[26:27], 0, v[132:133]
	s_mov_b32 m0, s51
	ds_read_b128 v[180:183], v146 offset:16384
	ds_read_b128 v[196:199], v146 offset:17408
	ds_read_b128 v[200:203], v146 offset:18432
	ds_read_b128 v[204:207], v146 offset:19456
	ds_read_b128 v[208:211], v146 offset:20480
	ds_read_b128 v[212:215], v146 offset:21504
	ds_read_b128 v[216:219], v146 offset:22528
	ds_read_b128 v[220:223], v146 offset:23552
	global_load_lds_dwordx4 v[142:143], off
	s_add_i32 m0, s51, 0x2000
	s_add_u32 s82, s26, 0x80000
	v_lshl_add_u64 v[184:185], s[26:27], 0, v[136:137]
	s_addc_u32 s83, s27, 0
	s_add_i32 s51, s75, s35
	global_load_lds_dwordx4 v[184:185], off
	v_lshl_add_u64 v[224:225], s[82:83], 0, v[132:133]
	s_mov_b32 m0, s51
	v_lshl_add_u64 v[226:227], s[28:29], 0, v[134:135]
	global_load_lds_dwordx4 v[224:225], off
	v_lshl_add_u64 v[224:225], s[82:83], 0, v[136:137]
	s_add_i32 m0, s51, 0x2000
	s_nop 0
	global_load_lds_dwordx4 v[224:225], off
	v_lshl_add_u64 v[224:225], s[28:29], 0, v[130:131]
	s_mov_b32 m0, s46
	s_nop 0
	global_load_lds_dwordx4 v[224:225], off
	s_mov_b32 m0, s47
	s_nop 0
	global_load_lds_dwordx4 v[226:227], off
	s_waitcnt vmcnt(8)
	s_waitcnt lgkmcnt(0)
	s_barrier
	s_setprio 1
	s_waitcnt lgkmcnt(0)
	v_mfma_f32_16x16x32_bf16 v[62:65], v[148:151], v[180:183], 0
	v_mfma_f32_16x16x32_bf16 v[58:61], v[156:159], v[180:183], 0
	v_mfma_f32_16x16x32_bf16 v[50:53], v[148:151], v[200:203], 0
	v_mfma_f32_16x16x32_bf16 v[42:45], v[156:159], v[200:203], 0
	v_mfma_f32_16x16x32_bf16 v[34:37], v[148:151], v[208:211], 0
	v_mfma_f32_16x16x32_bf16 v[26:29], v[156:159], v[208:211], 0
	v_mfma_f32_16x16x32_bf16 v[18:21], v[148:151], v[216:219], 0
	v_mfma_f32_16x16x32_bf16 v[10:13], v[156:159], v[216:219], 0
	v_mfma_f32_16x16x32_bf16 v[62:65], v[152:155], v[196:199], v[62:65]
	v_mfma_f32_16x16x32_bf16 v[58:61], v[160:163], v[196:199], v[58:61]
	v_mfma_f32_16x16x32_bf16 v[50:53], v[152:155], v[204:207], v[50:53]
	v_mfma_f32_16x16x32_bf16 v[42:45], v[160:163], v[204:207], v[42:45]
	v_mfma_f32_16x16x32_bf16 v[34:37], v[152:155], v[212:215], v[34:37]
	v_mfma_f32_16x16x32_bf16 v[26:29], v[160:163], v[212:215], v[26:29]
	v_mfma_f32_16x16x32_bf16 v[18:21], v[152:155], v[220:223], v[18:21]
	v_mfma_f32_16x16x32_bf16 v[10:13], v[160:163], v[220:223], v[10:13]
	s_setprio 0
	s_setprio 1
	v_mfma_f32_16x16x32_bf16 v[54:57], v[164:167], v[180:183], 0
	v_mfma_f32_16x16x32_bf16 v[46:49], v[172:175], v[180:183], 0
	v_mfma_f32_16x16x32_bf16 v[38:41], v[164:167], v[200:203], 0
	v_mfma_f32_16x16x32_bf16 v[30:33], v[172:175], v[200:203], 0
	v_mfma_f32_16x16x32_bf16 v[22:25], v[164:167], v[208:211], 0
	v_mfma_f32_16x16x32_bf16 v[14:17], v[172:175], v[208:211], 0
	v_mfma_f32_16x16x32_bf16 v[6:9], v[164:167], v[216:219], 0
	v_mfma_f32_16x16x32_bf16 v[2:5], v[172:175], v[216:219], 0
	v_mfma_f32_16x16x32_bf16 v[54:57], v[168:171], v[196:199], v[54:57]
	v_mfma_f32_16x16x32_bf16 v[46:49], v[176:179], v[196:199], v[46:49]
	v_mfma_f32_16x16x32_bf16 v[38:41], v[168:171], v[204:207], v[38:41]
	v_mfma_f32_16x16x32_bf16 v[30:33], v[176:179], v[204:207], v[30:33]
	v_mfma_f32_16x16x32_bf16 v[22:25], v[168:171], v[212:215], v[22:25]
	v_mfma_f32_16x16x32_bf16 v[14:17], v[176:179], v[212:215], v[14:17]
	v_mfma_f32_16x16x32_bf16 v[6:9], v[168:171], v[220:223], v[6:9]
	v_mfma_f32_16x16x32_bf16 v[2:5], v[176:179], v[220:223], v[2:5]
	s_setprio 0
	s_barrier
	s_branch .Lmid_790

; #define PG8_STAGE(bufoff, gbase, voff) do { _Pragma("unroll") for (int _i = 0; _i < 2; ++_i) \
;         __builtin_amdgcn_global_load_lds((const unsigned*)((const char*)(gbase) + (voff)[_i]), (PG8_LAS unsigned*)(lds + (bufoff) + ldsw + _i * 8192), 16, 0, 0); } while (0)
; #define PG8_LDA(dst, b, h) do { _Pragma("unroll") for (int m = 0; m < 4; ++m) _Pragma("unroll") for (int k = 0; k < 2; ++k) dst[m][k] = *(const PG8_LAS bf16x8*)(lds + PG8_SA(b, h) + aoff + m * 2048 + k * 1024); } while (0)
; #define PG8_LDB(dst, b, h) do { _Pragma("unroll") for (int n = 0; n < 2; ++n) _Pragma("unroll") for (int k = 0; k < 2; ++k) dst[n][k] = *(const PG8_LAS bf16x8*)(lds + PG8_SB(b, h) + boff + n * 2048 + k * 1024); } while (0)
; #define PG8_MMA(ai, bj, At, Bt) do { __builtin_amdgcn_s_setprio(1); _Pragma("unroll") for (int m = 0; m < 4; ++m) _Pragma("unroll") for (int n = 0; n < 2; ++n) _Pragma("unroll") for (int k = 0; k < 2; ++k) \
;         acc[ai][bj][m][n] = __builtin_amdgcn_mfma_f32_16x16x32_bf16(Bt[n][k], At[m][k], acc[ai][bj][m][n], 0, 0, 0); __builtin_amdgcn_s_setprio(0); } while (0)
; #define PG8_WAIT_V(n) asm volatile("s_waitcnt vmcnt(" #n ")" ::: "memory")
; #define PG8_WAIT_L(n) asm volatile("s_waitcnt lgkmcnt(" #n ")" ::: "memory")
; #define PG8_BAR __builtin_amdgcn_s_barrier()
; template <class Epi, class Sched, bool ALIGN_EPI = false, bool SP2 = false, bool ABLK = false, bool BBLK = false>
; __device__ __forceinline__ void gemm_phase(PG8_LAS unsigned char* lds, const Gemm g, const Sched& S, const Epi& E) {
;     ...
;         const char* nA = has_next ? (const char*)g.A + (size_t)nxt.pm * tstepA : cA; const char* nB = has_next ? (const char*)g.Bt + (size_t)nxt.pn * tstepB : cB;
;         for (int t = 0; t < nt; t += 2) {
;             const bool last = (t == nt - 2);
;             const char* a1 = cA + (size_t)(t + 1) * kstepA;
;             const char* a2 = last ? nA : cA + (size_t)(t + 2) * kstepA; const char* b2 = last ? nB : cB + (size_t)(t + 2) * kstepB;
;             const char* a3 = a2 + kstepA; const char* b3 = b2 + kstepB;
;             if (last && has_next) S.a_ready(nxt);
;             if constexpr (SP2) {
;             PG8_LDB(B0, 0, 0); PG8_LDB(B1, 0, 1); PG8_SCHED; PG8_LDA(At, 0, 0); PG8_STAGE(PG8_SA(1, 1), a1 + hstepA, voffA);
;             PG8_WAIT_V(8); PG8_WAIT_L(0); PG8_BAR; PG8_MMA(0, 0, At, B0); PG8_MMA(0, 1, At, B1); PG8_BAR; PG8_SCHED;
.LBB0_1116:
	s_ashr_i32 s23, s22, 31
	s_lshl_b64 s[24:25], s[22:23], 18
	s_add_u32 s24, s33, s24
	s_addc_u32 s25, s44, s25
	s_and_b64 s[26:27], s[6:7], exec
	s_cselect_b32 s23, s25, s35
	s_cselect_b32 s31, s24, s34
	s_ashr_i32 s21, s20, 31
	s_lshl_b64 s[26:27], s[20:21], 18
	s_add_u32 s26, s45, s26
	s_addc_u32 s27, s46, s27
	s_and_b64 s[36:37], s[6:7], exec
	s_cselect_b32 s21, s27, s1
	s_cselect_b32 s91, s26, s0
	s_add_u32 s92, s0, 0x10000
	s_addc_u32 s93, s1, 0
	s_add_u32 s0, s34, 0x20080
	s_addc_u32 s1, s35, 0
	s_mov_b32 s94, -2
	s_add_u32 s34, s0, 0xfffe0080
	s_addc_u32 s35, s1, -1
	s_add_i32 s52, 0, 0x10000
	s_cmp_eq_u32 s94, 4
	s_cselect_b32 s37, s23, s35
	s_cselect_b32 s36, s31, s34
	s_cselect_b32 s35, s21, s93
	s_cselect_b32 s34, s91, s92
	s_add_i32 s75, 0, 0x14000
	v_add_u32_e32 v142, s52, v163
	v_add_u32_e32 v160, s75, v163
	ds_read_b128 v[130:133], v142
	ds_read_b128 v[134:137], v142 offset:1024
	ds_read_b128 v[138:141], v142 offset:2048
	ds_read_b128 v[142:145], v142 offset:3072
	ds_read_b128 v[146:149], v160
	ds_read_b128 v[166:169], v160 offset:1024
	ds_read_b128 v[170:173], v160 offset:2048
	ds_read_b128 v[174:177], v160 offset:3072
	v_lshl_add_u64 v[160:161], s[0:1], 0, v[156:157]
	s_add_i32 m0, s29, 0xc000
	ds_read_b128 v[178:181], v165
	ds_read_b128 v[182:185], v165 offset:1024
	ds_read_b128 v[196:199], v165 offset:2048
	ds_read_b128 v[200:203], v165 offset:3072
	ds_read_b128 v[204:207], v165 offset:4096
	ds_read_b128 v[208:211], v165 offset:5120
	ds_read_b128 v[212:215], v165 offset:6144
	ds_read_b128 v[216:219], v165 offset:7168
	global_load_lds_dwordx4 v[160:161], off
	v_lshl_add_u64 v[160:161], s[0:1], 0, v[158:159]
	s_add_i32 m0, s29, 0xe000
	s_nop 0
	global_load_lds_dwordx4 v[160:161], off
	s_waitcnt vmcnt(8)
	s_waitcnt lgkmcnt(0)
	s_barrier
	s_setprio 1
	s_waitcnt lgkmcnt(0)
	v_mfma_f32_16x16x32_bf16 v[126:129], v[130:133], v[178:181], 0
	v_mfma_f32_16x16x32_bf16 v[122:125], v[138:141], v[178:181], 0
	v_mfma_f32_16x16x32_bf16 v[118:121], v[130:133], v[196:199], 0
	v_mfma_f32_16x16x32_bf16 v[114:117], v[138:141], v[196:199], 0
	v_mfma_f32_16x16x32_bf16 v[94:97], v[130:133], v[204:207], 0
	v_mfma_f32_16x16x32_bf16 v[90:93], v[138:141], v[204:207], 0
	v_mfma_f32_16x16x32_bf16 v[78:81], v[130:133], v[212:215], 0
	v_mfma_f32_16x16x32_bf16 v[74:77], v[138:141], v[212:215], 0
	v_mfma_f32_16x16x32_bf16 v[126:129], v[134:137], v[182:185], v[126:129]
	v_mfma_f32_16x16x32_bf16 v[122:125], v[142:145], v[182:185], v[122:125]
	v_mfma_f32_16x16x32_bf16 v[118:121], v[134:137], v[200:203], v[118:121]
	v_mfma_f32_16x16x32_bf16 v[114:117], v[142:145], v[200:203], v[114:117]
	v_mfma_f32_16x16x32_bf16 v[94:97], v[134:137], v[208:211], v[94:97]
	v_mfma_f32_16x16x32_bf16 v[90:93], v[142:145], v[208:211], v[90:93]
	v_mfma_f32_16x16x32_bf16 v[78:81], v[134:137], v[216:219], v[78:81]
	v_mfma_f32_16x16x32_bf16 v[74:77], v[142:145], v[216:219], v[74:77]
	s_setprio 0
	s_setprio 1
	v_mfma_f32_16x16x32_bf16 v[110:113], v[146:149], v[178:181], 0
	v_mfma_f32_16x16x32_bf16 v[106:109], v[170:173], v[178:181], 0
	v_mfma_f32_16x16x32_bf16 v[102:105], v[146:149], v[196:199], 0
	v_mfma_f32_16x16x32_bf16 v[98:101], v[170:173], v[196:199], 0
	v_mfma_f32_16x16x32_bf16 v[86:89], v[146:149], v[204:207], 0
	v_mfma_f32_16x16x32_bf16 v[82:85], v[170:173], v[204:207], 0
	v_mfma_f32_16x16x32_bf16 v[70:73], v[146:149], v[212:215], 0
	v_mfma_f32_16x16x32_bf16 v[66:69], v[170:173], v[212:215], 0
	v_mfma_f32_16x16x32_bf16 v[110:113], v[166:169], v[182:185], v[110:113]
	v_mfma_f32_16x16x32_bf16 v[106:109], v[174:177], v[182:185], v[106:109]
	v_mfma_f32_16x16x32_bf16 v[102:105], v[166:169], v[200:203], v[102:105]
	v_mfma_f32_16x16x32_bf16 v[98:101], v[174:177], v[200:203], v[98:101]
	v_mfma_f32_16x16x32_bf16 v[86:89], v[166:169], v[208:211], v[86:89]
	v_mfma_f32_16x16x32_bf16 v[82:85], v[174:177], v[208:211], v[82:85]
	v_mfma_f32_16x16x32_bf16 v[70:73], v[166:169], v[216:219], v[70:73]
	v_mfma_f32_16x16x32_bf16 v[66:69], v[174:177], v[216:219], v[66:69]
	s_setprio 0
	s_barrier
; #define PG8_STAGE(bufoff, gbase, voff) do { _Pragma("unroll") for (int _i = 0; _i < 2; ++_i) \
;         __builtin_amdgcn_global_load_lds((const unsigned*)((const char*)(gbase) + (voff)[_i]), (PG8_LAS unsigned*)(lds + (bufoff) + ldsw + _i * 8192), 16, 0, 0); } while (0)
; #define PG8_LDA(dst, b, h) do { _Pragma("unroll") for (int m = 0; m < 4; ++m) _Pragma("unroll") for (int k = 0; k < 2; ++k) dst[m][k] = *(const PG8_LAS bf16x8*)(lds + PG8_SA(b, h) + aoff + m * 2048 + k * 1024); } while (0)
; #define PG8_MMA(ai, bj, At, Bt) do { __builtin_amdgcn_s_setprio(1); _Pragma("unroll") for (int m = 0; m < 4; ++m) _Pragma("unroll") for (int n = 0; n < 2; ++n) _Pragma("unroll") for (int k = 0; k < 2; ++k) \
;         acc[ai][bj][m][n] = __builtin_amdgcn_mfma_f32_16x16x32_bf16(Bt[n][k], At[m][k], acc[ai][bj][m][n], 0, 0, 0); __builtin_amdgcn_s_setprio(0); } while (0)
; #define PG8_WAIT_V(n) asm volatile("s_waitcnt vmcnt(" #n ")" ::: "memory")
; #define PG8_WAIT_L(n) asm volatile("s_waitcnt lgkmcnt(" #n ")" ::: "memory")
; #define PG8_BAR __builtin_amdgcn_s_barrier()
; #define PG8_SCHED __builtin_amdgcn_sched_barrier(0)
; template <class Epi, class Sched, bool ALIGN_EPI = false, bool SP2 = false, bool ABLK = false, bool BBLK = false>
; __device__ __forceinline__ void gemm_phase(PG8_LAS unsigned char* lds, const Gemm g, const Sched& S, const Epi& E) {
;     ...
;             PG8_LDA(At, 0, 1); PG8_STAGE(PG8_SB(0, 0), b2, voffB); PG8_STAGE(PG8_SB(0, 1), b2 + hstepB, voffB); PG8_STAGE(PG8_SA(0, 0), a2, voffA);
;             PG8_WAIT_V(8); PG8_WAIT_L(0); PG8_BAR; PG8_MMA(1, 0, At, B0); PG8_MMA(1, 1, At, B1); PG8_BAR; PG8_SCHED;
	s_add_i32 s52, s52, s47
	v_lshl_add_u64 v[160:161], s[34:35], 0, v[150:151]
	s_mov_b32 m0, s52
	ds_read_b128 v[178:181], v165 offset:16384
	ds_read_b128 v[182:185], v165 offset:17408
	ds_read_b128 v[196:199], v165 offset:18432
	ds_read_b128 v[200:203], v165 offset:19456
	ds_read_b128 v[204:207], v165 offset:20480
	ds_read_b128 v[208:211], v165 offset:21504
	ds_read_b128 v[212:215], v165 offset:22528
	ds_read_b128 v[216:219], v165 offset:23552
	global_load_lds_dwordx4 v[160:161], off
	s_add_i32 m0, s52, 0x2000
	s_add_u32 s96, s34, 0x4000
	v_lshl_add_u64 v[160:161], s[34:35], 0, v[154:155]
	s_addc_u32 s97, s35, 0
	s_add_i32 s52, s75, s47
	global_load_lds_dwordx4 v[160:161], off
	v_lshl_add_u64 v[160:161], s[96:97], 0, v[150:151]
	s_mov_b32 m0, s52
	v_lshl_add_u64 v[188:189], s[36:37], 0, v[152:153]
	global_load_lds_dwordx4 v[160:161], off
	v_lshl_add_u64 v[160:161], s[96:97], 0, v[154:155]
	s_add_i32 m0, s52, 0x2000
	s_nop 0
	global_load_lds_dwordx4 v[160:161], off
	v_lshl_add_u64 v[160:161], s[36:37], 0, v[186:187]
	s_mov_b32 m0, s29
	s_nop 0
	global_load_lds_dwordx4 v[160:161], off
	s_mov_b32 m0, s65
	s_nop 0
	global_load_lds_dwordx4 v[188:189], off
	s_waitcnt vmcnt(8)
	s_waitcnt lgkmcnt(0)
	s_barrier
	s_setprio 1
	s_waitcnt lgkmcnt(0)
	v_mfma_f32_16x16x32_bf16 v[62:65], v[130:133], v[178:181], 0
	v_mfma_f32_16x16x32_bf16 v[58:61], v[138:141], v[178:181], 0
	v_mfma_f32_16x16x32_bf16 v[46:49], v[130:133], v[196:199], 0
	v_mfma_f32_16x16x32_bf16 v[42:45], v[138:141], v[196:199], 0
	v_mfma_f32_16x16x32_bf16 v[30:33], v[130:133], v[204:207], 0
	v_mfma_f32_16x16x32_bf16 v[26:29], v[138:141], v[204:207], 0
	v_mfma_f32_16x16x32_bf16 v[14:17], v[130:133], v[212:215], 0
	v_mfma_f32_16x16x32_bf16 v[10:13], v[138:141], v[212:215], 0
	v_mfma_f32_16x16x32_bf16 v[62:65], v[134:137], v[182:185], v[62:65]
	v_mfma_f32_16x16x32_bf16 v[58:61], v[142:145], v[182:185], v[58:61]
	v_mfma_f32_16x16x32_bf16 v[46:49], v[134:137], v[200:203], v[46:49]
	v_mfma_f32_16x16x32_bf16 v[42:45], v[142:145], v[200:203], v[42:45]
	v_mfma_f32_16x16x32_bf16 v[30:33], v[134:137], v[208:211], v[30:33]
	v_mfma_f32_16x16x32_bf16 v[26:29], v[142:145], v[208:211], v[26:29]
	v_mfma_f32_16x16x32_bf16 v[14:17], v[134:137], v[216:219], v[14:17]
	v_mfma_f32_16x16x32_bf16 v[10:13], v[142:145], v[216:219], v[10:13]
	s_setprio 0
	s_setprio 1
	v_mfma_f32_16x16x32_bf16 v[54:57], v[146:149], v[178:181], 0
	v_mfma_f32_16x16x32_bf16 v[50:53], v[170:173], v[178:181], 0
	v_mfma_f32_16x16x32_bf16 v[38:41], v[146:149], v[196:199], 0
	v_mfma_f32_16x16x32_bf16 v[34:37], v[170:173], v[196:199], 0
	v_mfma_f32_16x16x32_bf16 v[22:25], v[146:149], v[204:207], 0
	v_mfma_f32_16x16x32_bf16 v[18:21], v[170:173], v[204:207], 0
	v_mfma_f32_16x16x32_bf16 v[6:9], v[146:149], v[212:215], 0
	v_mfma_f32_16x16x32_bf16 v[2:5], v[170:173], v[212:215], 0
	v_mfma_f32_16x16x32_bf16 v[54:57], v[166:169], v[182:185], v[54:57]
	v_mfma_f32_16x16x32_bf16 v[50:53], v[174:177], v[182:185], v[50:53]
	v_mfma_f32_16x16x32_bf16 v[38:41], v[166:169], v[200:203], v[38:41]
	v_mfma_f32_16x16x32_bf16 v[34:37], v[174:177], v[200:203], v[34:37]
	v_mfma_f32_16x16x32_bf16 v[22:25], v[166:169], v[208:211], v[22:25]
	v_mfma_f32_16x16x32_bf16 v[18:21], v[174:177], v[208:211], v[18:21]
	v_mfma_f32_16x16x32_bf16 v[6:9], v[166:169], v[216:219], v[6:9]
	v_mfma_f32_16x16x32_bf16 v[2:5], v[174:177], v[216:219], v[2:5]
	s_setprio 0
	s_barrier
	s_branch .Lmid_1117

; #define PG8_STAGE(bufoff, gbase, voff) do { _Pragma("unroll") for (int _i = 0; _i < 2; ++_i) \
;         __builtin_amdgcn_global_load_lds((const unsigned*)((const char*)(gbase) + (voff)[_i]), (PG8_LAS unsigned*)(lds + (bufoff) + ldsw + _i * 8192), 16, 0, 0); } while (0)
; #define PG8_LDA(dst, b, h) do { _Pragma("unroll") for (int m = 0; m < 4; ++m) _Pragma("unroll") for (int k = 0; k < 2; ++k) dst[m][k] = *(const PG8_LAS bf16x8*)(lds + PG8_SA(b, h) + aoff + m * 2048 + k * 1024); } while (0)
; #define PG8_LDB(dst, b, h) do { _Pragma("unroll") for (int n = 0; n < 2; ++n) _Pragma("unroll") for (int k = 0; k < 2; ++k) dst[n][k] = *(const PG8_LAS bf16x8*)(lds + PG8_SB(b, h) + boff + n * 2048 + k * 1024); } while (0)
; #define PG8_MMA(ai, bj, At, Bt) do { __builtin_amdgcn_s_setprio(1); _Pragma("unroll") for (int m = 0; m < 4; ++m) _Pragma("unroll") for (int n = 0; n < 2; ++n) _Pragma("unroll") for (int k = 0; k < 2; ++k) \
;         acc[ai][bj][m][n] = __builtin_amdgcn_mfma_f32_16x16x32_bf16(Bt[n][k], At[m][k], acc[ai][bj][m][n], 0, 0, 0); __builtin_amdgcn_s_setprio(0); } while (0)
; #define PG8_WAIT_V(n) asm volatile("s_waitcnt vmcnt(" #n ")" ::: "memory")
; #define PG8_WAIT_L(n) asm volatile("s_waitcnt lgkmcnt(" #n ")" ::: "memory")
; #define PG8_BAR __builtin_amdgcn_s_barrier()
; template <class Epi, class Sched, bool ALIGN_EPI = false, bool SP2 = false, bool ABLK = false, bool BBLK = false>
; __device__ __forceinline__ void gemm_phase(PG8_LAS unsigned char* lds, const Gemm g, const Sched& S, const Epi& E) {
;     ...
;         const char* nA = has_next ? (const char*)g.A + (size_t)nxt.pm * tstepA : cA; const char* nB = has_next ? (const char*)g.Bt + (size_t)nxt.pn * tstepB : cB;
;         for (int t = 0; t < nt; t += 2) {
;             const bool last = (t == nt - 2);
;             const char* a1 = cA + (size_t)(t + 1) * kstepA;
;             const char* a2 = last ? nA : cA + (size_t)(t + 2) * kstepA; const char* b2 = last ? nB : cB + (size_t)(t + 2) * kstepB;
;             const char* a3 = a2 + kstepA; const char* b3 = b2 + kstepB;
;             if (last && has_next) S.a_ready(nxt);
;             if constexpr (SP2) {
;             PG8_LDB(B0, 0, 0); PG8_LDB(B1, 0, 1); PG8_SCHED; PG8_LDA(At, 0, 0); PG8_STAGE(PG8_SA(1, 1), a1 + hstepA, voffA);
;             PG8_WAIT_V(8); PG8_WAIT_L(0); PG8_BAR; PG8_MMA(0, 0, At, B0); PG8_MMA(0, 1, At, B1); PG8_BAR; PG8_SCHED;
.LBB0_1139:
	s_ashr_i32 s23, s22, 31
	s_lshl_b64 s[24:25], s[22:23], 19
	s_add_u32 s24, s46, s24
	s_addc_u32 s25, s47, s25
	s_and_b64 s[26:27], s[6:7], exec
	s_cselect_b32 s23, s25, s35
	s_cselect_b32 s31, s24, s34
	s_ashr_i32 s21, s20, 31
	s_lshl_b64 s[26:27], s[20:21], 19
	s_add_u32 s26, s33, s26
	s_addc_u32 s27, s44, s27
	s_and_b64 s[36:37], s[6:7], exec
	s_cselect_b32 s21, s27, s1
	s_cselect_b32 s91, s26, s0
	s_add_u32 s92, s0, 0x10000
	s_addc_u32 s93, s1, 0
	s_add_u32 s0, s34, 0x40080
	s_addc_u32 s1, s35, 0
	s_mov_b32 s94, -2
	s_add_u32 s34, s0, 0xfffc0080
	s_addc_u32 s35, s1, -1
	s_add_i32 s52, 0, 0x10000
	s_cmp_eq_u32 s94, 12
	s_cselect_b32 s37, s23, s35
	s_cselect_b32 s36, s31, s34
	s_cselect_b32 s35, s21, s93
	s_cselect_b32 s34, s91, s92
	s_add_i32 s75, 0, 0x14000
	v_add_u32_e32 v142, s52, v223
	v_add_u32_e32 v158, s75, v223
	ds_read_b128 v[130:133], v142
	ds_read_b128 v[134:137], v142 offset:1024
	ds_read_b128 v[138:141], v142 offset:2048
	ds_read_b128 v[142:145], v142 offset:3072
	ds_read_b128 v[146:149], v158
	ds_read_b128 v[150:153], v158 offset:1024
	ds_read_b128 v[154:157], v158 offset:2048
	ds_read_b128 v[158:161], v158 offset:3072
	v_lshl_add_u64 v[188:189], s[0:1], 0, v[202:203]
	s_add_i32 m0, s29, 0xc000
	ds_read_b128 v[162:165], v225
	ds_read_b128 v[166:169], v225 offset:1024
	ds_read_b128 v[170:173], v225 offset:2048
	ds_read_b128 v[174:177], v225 offset:3072
	ds_read_b128 v[178:181], v225 offset:4096
	ds_read_b128 v[182:185], v225 offset:5120
	ds_read_b128 v[206:209], v225 offset:6144
	ds_read_b128 v[210:213], v225 offset:7168
	global_load_lds_dwordx4 v[188:189], off
	v_lshl_add_u64 v[188:189], s[0:1], 0, v[204:205]
	s_add_i32 m0, s29, 0xe000
	s_nop 0
	global_load_lds_dwordx4 v[188:189], off
	s_waitcnt vmcnt(8)
	s_waitcnt lgkmcnt(0)
	s_barrier
	s_setprio 1
	s_waitcnt lgkmcnt(0)
	v_mfma_f32_16x16x32_bf16 v[126:129], v[130:133], v[162:165], 0
	v_mfma_f32_16x16x32_bf16 v[122:125], v[138:141], v[162:165], 0
	v_mfma_f32_16x16x32_bf16 v[110:113], v[130:133], v[170:173], 0
	v_mfma_f32_16x16x32_bf16 v[106:109], v[138:141], v[170:173], 0
	v_mfma_f32_16x16x32_bf16 v[94:97], v[130:133], v[178:181], 0
	v_mfma_f32_16x16x32_bf16 v[90:93], v[138:141], v[178:181], 0
	v_mfma_f32_16x16x32_bf16 v[78:81], v[130:133], v[206:209], 0
	v_mfma_f32_16x16x32_bf16 v[74:77], v[138:141], v[206:209], 0
	v_mfma_f32_16x16x32_bf16 v[126:129], v[134:137], v[166:169], v[126:129]
	v_mfma_f32_16x16x32_bf16 v[122:125], v[142:145], v[166:169], v[122:125]
	v_mfma_f32_16x16x32_bf16 v[110:113], v[134:137], v[174:177], v[110:113]
	v_mfma_f32_16x16x32_bf16 v[106:109], v[142:145], v[174:177], v[106:109]
	v_mfma_f32_16x16x32_bf16 v[94:97], v[134:137], v[182:185], v[94:97]
	v_mfma_f32_16x16x32_bf16 v[90:93], v[142:145], v[182:185], v[90:93]
	v_mfma_f32_16x16x32_bf16 v[78:81], v[134:137], v[210:213], v[78:81]
	v_mfma_f32_16x16x32_bf16 v[74:77], v[142:145], v[210:213], v[74:77]
	s_setprio 0
	s_setprio 1
	v_mfma_f32_16x16x32_bf16 v[118:121], v[146:149], v[162:165], 0
	v_mfma_f32_16x16x32_bf16 v[114:117], v[154:157], v[162:165], 0
	v_mfma_f32_16x16x32_bf16 v[102:105], v[146:149], v[170:173], 0
	v_mfma_f32_16x16x32_bf16 v[98:101], v[154:157], v[170:173], 0
	v_mfma_f32_16x16x32_bf16 v[86:89], v[146:149], v[178:181], 0
	v_mfma_f32_16x16x32_bf16 v[82:85], v[154:157], v[178:181], 0
	v_mfma_f32_16x16x32_bf16 v[70:73], v[146:149], v[206:209], 0
	v_mfma_f32_16x16x32_bf16 v[66:69], v[154:157], v[206:209], 0
	v_mfma_f32_16x16x32_bf16 v[118:121], v[150:153], v[166:169], v[118:121]
	v_mfma_f32_16x16x32_bf16 v[114:117], v[158:161], v[166:169], v[114:117]
	v_mfma_f32_16x16x32_bf16 v[102:105], v[150:153], v[174:177], v[102:105]
	v_mfma_f32_16x16x32_bf16 v[98:101], v[158:161], v[174:177], v[98:101]
	v_mfma_f32_16x16x32_bf16 v[86:89], v[150:153], v[182:185], v[86:89]
	v_mfma_f32_16x16x32_bf16 v[82:85], v[158:161], v[182:185], v[82:85]
	v_mfma_f32_16x16x32_bf16 v[70:73], v[150:153], v[210:213], v[70:73]
	v_mfma_f32_16x16x32_bf16 v[66:69], v[158:161], v[210:213], v[66:69]
	s_setprio 0
	s_barrier
; #define PG8_STAGE(bufoff, gbase, voff) do { _Pragma("unroll") for (int _i = 0; _i < 2; ++_i) \
;         __builtin_amdgcn_global_load_lds((const unsigned*)((const char*)(gbase) + (voff)[_i]), (PG8_LAS unsigned*)(lds + (bufoff) + ldsw + _i * 8192), 16, 0, 0); } while (0)
; #define PG8_LDA(dst, b, h) do { _Pragma("unroll") for (int m = 0; m < 4; ++m) _Pragma("unroll") for (int k = 0; k < 2; ++k) dst[m][k] = *(const PG8_LAS bf16x8*)(lds + PG8_SA(b, h) + aoff + m * 2048 + k * 1024); } while (0)
; #define PG8_MMA(ai, bj, At, Bt) do { __builtin_amdgcn_s_setprio(1); _Pragma("unroll") for (int m = 0; m < 4; ++m) _Pragma("unroll") for (int n = 0; n < 2; ++n) _Pragma("unroll") for (int k = 0; k < 2; ++k) \
;         acc[ai][bj][m][n] = __builtin_amdgcn_mfma_f32_16x16x32_bf16(Bt[n][k], At[m][k], acc[ai][bj][m][n], 0, 0, 0); __builtin_amdgcn_s_setprio(0); } while (0)
; #define PG8_WAIT_V(n) asm volatile("s_waitcnt vmcnt(" #n ")" ::: "memory")
; #define PG8_WAIT_L(n) asm volatile("s_waitcnt lgkmcnt(" #n ")" ::: "memory")
; #define PG8_BAR __builtin_amdgcn_s_barrier()
; #define PG8_SCHED __builtin_amdgcn_sched_barrier(0)
; template <class Epi, class Sched, bool ALIGN_EPI = false, bool SP2 = false, bool ABLK = false, bool BBLK = false>
; __device__ __forceinline__ void gemm_phase(PG8_LAS unsigned char* lds, const Gemm g, const Sched& S, const Epi& E) {
;     ...
;             PG8_LDA(At, 0, 1); PG8_STAGE(PG8_SB(0, 0), b2, voffB); PG8_STAGE(PG8_SB(0, 1), b2 + hstepB, voffB); PG8_STAGE(PG8_SA(0, 0), a2, voffA);
;             PG8_WAIT_V(8); PG8_WAIT_L(0); PG8_BAR; PG8_MMA(1, 0, At, B0); PG8_MMA(1, 1, At, B1); PG8_BAR; PG8_SCHED;
	s_add_i32 s52, s52, s45
	v_lshl_add_u64 v[188:189], s[34:35], 0, v[196:197]
	s_mov_b32 m0, s52
	ds_read_b128 v[162:165], v225 offset:16384
	ds_read_b128 v[166:169], v225 offset:17408
	ds_read_b128 v[170:173], v225 offset:18432
	ds_read_b128 v[174:177], v225 offset:19456
	ds_read_b128 v[178:181], v225 offset:20480
	ds_read_b128 v[182:185], v225 offset:21504
	ds_read_b128 v[206:209], v225 offset:22528
	ds_read_b128 v[210:213], v225 offset:23552
	global_load_lds_dwordx4 v[188:189], off
	s_add_i32 m0, s52, 0x2000
	s_add_u32 s96, s34, 0x4000
	v_lshl_add_u64 v[188:189], s[34:35], 0, v[200:201]
	s_addc_u32 s97, s35, 0
	s_add_i32 s52, s75, s45
	global_load_lds_dwordx4 v[188:189], off
	v_lshl_add_u64 v[188:189], s[96:97], 0, v[196:197]
	s_mov_b32 m0, s52
	v_lshl_add_u64 v[190:191], s[36:37], 0, v[198:199]
	global_load_lds_dwordx4 v[188:189], off
	v_lshl_add_u64 v[188:189], s[96:97], 0, v[200:201]
	s_add_i32 m0, s52, 0x2000
	s_nop 0
	global_load_lds_dwordx4 v[188:189], off
	v_lshl_add_u64 v[188:189], s[36:37], 0, v[186:187]
	s_mov_b32 m0, s29
	s_nop 0
	global_load_lds_dwordx4 v[188:189], off
	s_mov_b32 m0, s65
	s_nop 0
	global_load_lds_dwordx4 v[190:191], off
	s_waitcnt vmcnt(8)
	s_waitcnt lgkmcnt(0)
	s_barrier
	s_setprio 1
	s_waitcnt lgkmcnt(0)
	v_mfma_f32_16x16x32_bf16 v[62:65], v[130:133], v[162:165], 0
	v_mfma_f32_16x16x32_bf16 v[58:61], v[138:141], v[162:165], 0
	v_mfma_f32_16x16x32_bf16 v[46:49], v[130:133], v[170:173], 0
	v_mfma_f32_16x16x32_bf16 v[42:45], v[138:141], v[170:173], 0
	v_mfma_f32_16x16x32_bf16 v[30:33], v[130:133], v[178:181], 0
	v_mfma_f32_16x16x32_bf16 v[26:29], v[138:141], v[178:181], 0
	v_mfma_f32_16x16x32_bf16 v[14:17], v[130:133], v[206:209], 0
	v_mfma_f32_16x16x32_bf16 v[10:13], v[138:141], v[206:209], 0
	v_mfma_f32_16x16x32_bf16 v[62:65], v[134:137], v[166:169], v[62:65]
	v_mfma_f32_16x16x32_bf16 v[58:61], v[142:145], v[166:169], v[58:61]
	v_mfma_f32_16x16x32_bf16 v[46:49], v[134:137], v[174:177], v[46:49]
	v_mfma_f32_16x16x32_bf16 v[42:45], v[142:145], v[174:177], v[42:45]
	v_mfma_f32_16x16x32_bf16 v[30:33], v[134:137], v[182:185], v[30:33]
	v_mfma_f32_16x16x32_bf16 v[26:29], v[142:145], v[182:185], v[26:29]
	v_mfma_f32_16x16x32_bf16 v[14:17], v[134:137], v[210:213], v[14:17]
	v_mfma_f32_16x16x32_bf16 v[10:13], v[142:145], v[210:213], v[10:13]
	s_setprio 0
	s_setprio 1
	v_mfma_f32_16x16x32_bf16 v[54:57], v[146:149], v[162:165], 0
	v_mfma_f32_16x16x32_bf16 v[50:53], v[154:157], v[162:165], 0
	v_mfma_f32_16x16x32_bf16 v[38:41], v[146:149], v[170:173], 0
	v_mfma_f32_16x16x32_bf16 v[34:37], v[154:157], v[170:173], 0
	v_mfma_f32_16x16x32_bf16 v[22:25], v[146:149], v[178:181], 0
	v_mfma_f32_16x16x32_bf16 v[18:21], v[154:157], v[178:181], 0
	v_mfma_f32_16x16x32_bf16 v[6:9], v[146:149], v[206:209], 0
	v_mfma_f32_16x16x32_bf16 v[2:5], v[154:157], v[206:209], 0
	v_mfma_f32_16x16x32_bf16 v[54:57], v[150:153], v[166:169], v[54:57]
	v_mfma_f32_16x16x32_bf16 v[50:53], v[158:161], v[166:169], v[50:53]
	v_mfma_f32_16x16x32_bf16 v[38:41], v[150:153], v[174:177], v[38:41]
	v_mfma_f32_16x16x32_bf16 v[34:37], v[158:161], v[174:177], v[34:37]
	v_mfma_f32_16x16x32_bf16 v[22:25], v[150:153], v[182:185], v[22:25]
	v_mfma_f32_16x16x32_bf16 v[18:21], v[158:161], v[182:185], v[18:21]
	v_mfma_f32_16x16x32_bf16 v[6:9], v[150:153], v[210:213], v[6:9]
	v_mfma_f32_16x16x32_bf16 v[2:5], v[158:161], v[210:213], v[2:5]
	s_setprio 0
	s_barrier
	s_branch .Lmid_1140

; #define PG8_STAGE(bufoff, gbase, voff) do { _Pragma("unroll") for (int _i = 0; _i < 2; ++_i) \
;         __builtin_amdgcn_global_load_lds((const unsigned*)((const char*)(gbase) + (voff)[_i]), (PG8_LAS unsigned*)(lds + (bufoff) + ldsw + _i * 8192), 16, 0, 0); } while (0)
; #define PG8_LDA(dst, b, h) do { _Pragma("unroll") for (int m = 0; m < 4; ++m) _Pragma("unroll") for (int k = 0; k < 2; ++k) dst[m][k] = *(const PG8_LAS bf16x8*)(lds + PG8_SA(b, h) + aoff + m * 2048 + k * 1024); } while (0)
; #define PG8_LDB(dst, b, h) do { _Pragma("unroll") for (int n = 0; n < 2; ++n) _Pragma("unroll") for (int k = 0; k < 2; ++k) dst[n][k] = *(const PG8_LAS bf16x8*)(lds + PG8_SB(b, h) + boff + n * 2048 + k * 1024); } while (0)
; #define PG8_MMA(ai, bj, At, Bt) do { __builtin_amdgcn_s_setprio(1); _Pragma("unroll") for (int m = 0; m < 4; ++m) _Pragma("unroll") for (int n = 0; n < 2; ++n) _Pragma("unroll") for (int k = 0; k < 2; ++k) \
;         acc[ai][bj][m][n] = __builtin_amdgcn_mfma_f32_16x16x32_bf16(Bt[n][k], At[m][k], acc[ai][bj][m][n], 0, 0, 0); __builtin_amdgcn_s_setprio(0); } while (0)
; #define PG8_WAIT_V(n) asm volatile("s_waitcnt vmcnt(" #n ")" ::: "memory")
; #define PG8_WAIT_L(n) asm volatile("s_waitcnt lgkmcnt(" #n ")" ::: "memory")
; #define PG8_BAR __builtin_amdgcn_s_barrier()
; template <class Epi, class Sched, bool ALIGN_EPI = false, bool SP2 = false, bool ABLK = false, bool BBLK = false>
; __device__ __forceinline__ void gemm_phase(PG8_LAS unsigned char* lds, const Gemm g, const Sched& S, const Epi& E) {
;     ...
;         const char* nA = has_next ? (const char*)g.A + (size_t)nxt.pm * tstepA : cA; const char* nB = has_next ? (const char*)g.Bt + (size_t)nxt.pn * tstepB : cB;
;         for (int t = 0; t < nt; t += 2) {
;             const bool last = (t == nt - 2);
;             const char* a1 = cA + (size_t)(t + 1) * kstepA;
;             const char* a2 = last ? nA : cA + (size_t)(t + 2) * kstepA; const char* b2 = last ? nB : cB + (size_t)(t + 2) * kstepB;
;             const char* a3 = a2 + kstepA; const char* b3 = b2 + kstepB;
;             if (last && has_next) S.a_ready(nxt);
;             if constexpr (SP2) {
;             PG8_LDB(B0, 0, 0); PG8_LDB(B1, 0, 1); PG8_SCHED; PG8_LDA(At, 0, 0); PG8_STAGE(PG8_SA(1, 1), a1 + hstepA, voffA);
;             PG8_WAIT_V(8); PG8_WAIT_L(0); PG8_BAR; PG8_MMA(0, 0, At, B0); PG8_MMA(0, 1, At, B1); PG8_BAR; PG8_SCHED;
.LBB0_1162:
	s_ashr_i32 s21, s20, 31
	s_lshl_b64 s[22:23], s[20:21], 18
	s_add_u32 s22, s33, s22
	s_addc_u32 s23, s36, s23
	s_and_b64 s[24:25], s[6:7], exec
	s_cselect_b32 s21, s23, s31
	s_cselect_b32 s29, s22, s30
	s_ashr_i32 s19, s18, 31
	s_lshl_b64 s[24:25], s[18:19], 18
	s_add_u32 s24, s37, s24
	s_addc_u32 s25, s44, s25
	s_and_b64 s[34:35], s[6:7], exec
	s_cselect_b32 s19, s25, s1
	s_cselect_b32 s61, s24, s0
	s_add_u32 s83, s0, 0x10000
	s_addc_u32 s84, s1, 0
	s_add_u32 s0, s30, 0x20080
	s_addc_u32 s1, s31, 0
	s_mov_b32 s86, -2
	s_add_u32 s30, s0, 0xfffe0080
	s_addc_u32 s31, s1, -1
	s_add_i32 s52, 0, 0x10000
	s_cmp_eq_u32 s86, 4
	s_cselect_b32 s35, s21, s31
	s_cselect_b32 s34, s29, s30
	s_cselect_b32 s31, s19, s84
	s_cselect_b32 s30, s61, s83
	s_add_i32 s75, 0, 0x14000
	v_add_u32_e32 v142, s52, v223
	v_add_u32_e32 v158, s75, v223
	ds_read_b128 v[130:133], v142
	ds_read_b128 v[134:137], v142 offset:1024
	ds_read_b128 v[138:141], v142 offset:2048
	ds_read_b128 v[142:145], v142 offset:3072
	ds_read_b128 v[146:149], v158
	ds_read_b128 v[150:153], v158 offset:1024
	ds_read_b128 v[154:157], v158 offset:2048
	ds_read_b128 v[158:161], v158 offset:3072
	v_lshl_add_u64 v[188:189], s[0:1], 0, v[202:203]
	s_add_i32 m0, s27, 0xc000
	ds_read_b128 v[162:165], v225
	ds_read_b128 v[166:169], v225 offset:1024
	ds_read_b128 v[170:173], v225 offset:2048
	ds_read_b128 v[174:177], v225 offset:3072
	ds_read_b128 v[178:181], v225 offset:4096
	ds_read_b128 v[182:185], v225 offset:5120
	ds_read_b128 v[206:209], v225 offset:6144
	ds_read_b128 v[210:213], v225 offset:7168
	global_load_lds_dwordx4 v[188:189], off
	v_lshl_add_u64 v[188:189], s[0:1], 0, v[204:205]
	s_add_i32 m0, s27, 0xe000
	s_nop 0
	global_load_lds_dwordx4 v[188:189], off
	s_waitcnt vmcnt(8)
	s_waitcnt lgkmcnt(0)
	s_barrier
	s_setprio 1
	s_waitcnt lgkmcnt(0)
	v_mfma_f32_16x16x32_bf16 v[126:129], v[130:133], v[162:165], 0
	v_mfma_f32_16x16x32_bf16 v[122:125], v[138:141], v[162:165], 0
	v_mfma_f32_16x16x32_bf16 v[110:113], v[130:133], v[170:173], 0
	v_mfma_f32_16x16x32_bf16 v[106:109], v[138:141], v[170:173], 0
	v_mfma_f32_16x16x32_bf16 v[94:97], v[130:133], v[178:181], 0
	v_mfma_f32_16x16x32_bf16 v[90:93], v[138:141], v[178:181], 0
	v_mfma_f32_16x16x32_bf16 v[78:81], v[130:133], v[206:209], 0
	v_mfma_f32_16x16x32_bf16 v[74:77], v[138:141], v[206:209], 0
	v_mfma_f32_16x16x32_bf16 v[126:129], v[134:137], v[166:169], v[126:129]
	v_mfma_f32_16x16x32_bf16 v[122:125], v[142:145], v[166:169], v[122:125]
	v_mfma_f32_16x16x32_bf16 v[110:113], v[134:137], v[174:177], v[110:113]
	v_mfma_f32_16x16x32_bf16 v[106:109], v[142:145], v[174:177], v[106:109]
	v_mfma_f32_16x16x32_bf16 v[94:97], v[134:137], v[182:185], v[94:97]
	v_mfma_f32_16x16x32_bf16 v[90:93], v[142:145], v[182:185], v[90:93]
	v_mfma_f32_16x16x32_bf16 v[78:81], v[134:137], v[210:213], v[78:81]
	v_mfma_f32_16x16x32_bf16 v[74:77], v[142:145], v[210:213], v[74:77]
	s_setprio 0
	s_setprio 1
	v_mfma_f32_16x16x32_bf16 v[118:121], v[146:149], v[162:165], 0
	v_mfma_f32_16x16x32_bf16 v[114:117], v[154:157], v[162:165], 0
	v_mfma_f32_16x16x32_bf16 v[102:105], v[146:149], v[170:173], 0
	v_mfma_f32_16x16x32_bf16 v[98:101], v[154:157], v[170:173], 0
	v_mfma_f32_16x16x32_bf16 v[86:89], v[146:149], v[178:181], 0
	v_mfma_f32_16x16x32_bf16 v[82:85], v[154:157], v[178:181], 0
	v_mfma_f32_16x16x32_bf16 v[70:73], v[146:149], v[206:209], 0
	v_mfma_f32_16x16x32_bf16 v[66:69], v[154:157], v[206:209], 0
	v_mfma_f32_16x16x32_bf16 v[118:121], v[150:153], v[166:169], v[118:121]
	v_mfma_f32_16x16x32_bf16 v[114:117], v[158:161], v[166:169], v[114:117]
	v_mfma_f32_16x16x32_bf16 v[102:105], v[150:153], v[174:177], v[102:105]
	v_mfma_f32_16x16x32_bf16 v[98:101], v[158:161], v[174:177], v[98:101]
	v_mfma_f32_16x16x32_bf16 v[86:89], v[150:153], v[182:185], v[86:89]
	v_mfma_f32_16x16x32_bf16 v[82:85], v[158:161], v[182:185], v[82:85]
	v_mfma_f32_16x16x32_bf16 v[70:73], v[150:153], v[210:213], v[70:73]
	v_mfma_f32_16x16x32_bf16 v[66:69], v[158:161], v[210:213], v[66:69]
	s_setprio 0
	s_barrier
; #define PG8_STAGE(bufoff, gbase, voff) do { _Pragma("unroll") for (int _i = 0; _i < 2; ++_i) \
;         __builtin_amdgcn_global_load_lds((const unsigned*)((const char*)(gbase) + (voff)[_i]), (PG8_LAS unsigned*)(lds + (bufoff) + ldsw + _i * 8192), 16, 0, 0); } while (0)
; #define PG8_LDA(dst, b, h) do { _Pragma("unroll") for (int m = 0; m < 4; ++m) _Pragma("unroll") for (int k = 0; k < 2; ++k) dst[m][k] = *(const PG8_LAS bf16x8*)(lds + PG8_SA(b, h) + aoff + m * 2048 + k * 1024); } while (0)
; #define PG8_MMA(ai, bj, At, Bt) do { __builtin_amdgcn_s_setprio(1); _Pragma("unroll") for (int m = 0; m < 4; ++m) _Pragma("unroll") for (int n = 0; n < 2; ++n) _Pragma("unroll") for (int k = 0; k < 2; ++k) \
;         acc[ai][bj][m][n] = __builtin_amdgcn_mfma_f32_16x16x32_bf16(Bt[n][k], At[m][k], acc[ai][bj][m][n], 0, 0, 0); __builtin_amdgcn_s_setprio(0); } while (0)
; #define PG8_WAIT_V(n) asm volatile("s_waitcnt vmcnt(" #n ")" ::: "memory")
; #define PG8_WAIT_L(n) asm volatile("s_waitcnt lgkmcnt(" #n ")" ::: "memory")
; #define PG8_BAR __builtin_amdgcn_s_barrier()
; #define PG8_SCHED __builtin_amdgcn_sched_barrier(0)
; template <class Epi, class Sched, bool ALIGN_EPI = false, bool SP2 = false, bool ABLK = false, bool BBLK = false>
; __device__ __forceinline__ void gemm_phase(PG8_LAS unsigned char* lds, const Gemm g, const Sched& S, const Epi& E) {
;     ...
;             PG8_LDA(At, 0, 1); PG8_STAGE(PG8_SB(0, 0), b2, voffB); PG8_STAGE(PG8_SB(0, 1), b2 + hstepB, voffB); PG8_STAGE(PG8_SA(0, 0), a2, voffA);
;             PG8_WAIT_V(8); PG8_WAIT_L(0); PG8_BAR; PG8_MMA(1, 0, At, B0); PG8_MMA(1, 1, At, B1); PG8_BAR; PG8_SCHED;
	s_add_i32 s52, s52, s45
	v_lshl_add_u64 v[188:189], s[30:31], 0, v[196:197]
	s_mov_b32 m0, s52
	ds_read_b128 v[162:165], v225 offset:16384
	ds_read_b128 v[166:169], v225 offset:17408
	ds_read_b128 v[170:173], v225 offset:18432
	ds_read_b128 v[174:177], v225 offset:19456
	ds_read_b128 v[178:181], v225 offset:20480
	ds_read_b128 v[182:185], v225 offset:21504
	ds_read_b128 v[206:209], v225 offset:22528
	ds_read_b128 v[210:213], v225 offset:23552
	global_load_lds_dwordx4 v[188:189], off
	s_add_i32 m0, s52, 0x2000
	s_add_u32 s88, s30, 0x4000
	v_lshl_add_u64 v[188:189], s[30:31], 0, v[200:201]
	s_addc_u32 s89, s31, 0
	s_add_i32 s52, s75, s45
	global_load_lds_dwordx4 v[188:189], off
	v_lshl_add_u64 v[188:189], s[88:89], 0, v[196:197]
	s_mov_b32 m0, s52
	v_lshl_add_u64 v[190:191], s[34:35], 0, v[198:199]
	global_load_lds_dwordx4 v[188:189], off
	v_lshl_add_u64 v[188:189], s[88:89], 0, v[200:201]
	s_add_i32 m0, s52, 0x2000
	s_nop 0
	global_load_lds_dwordx4 v[188:189], off
	v_lshl_add_u64 v[188:189], s[34:35], 0, v[186:187]
	s_mov_b32 m0, s27
	s_nop 0
	global_load_lds_dwordx4 v[188:189], off
	s_mov_b32 m0, s46
	s_nop 0
	global_load_lds_dwordx4 v[190:191], off
	s_waitcnt vmcnt(8)
	s_waitcnt lgkmcnt(0)
	s_barrier
	s_setprio 1
	s_waitcnt lgkmcnt(0)
	v_mfma_f32_16x16x32_bf16 v[62:65], v[130:133], v[162:165], 0
	v_mfma_f32_16x16x32_bf16 v[58:61], v[138:141], v[162:165], 0
	v_mfma_f32_16x16x32_bf16 v[46:49], v[130:133], v[170:173], 0
	v_mfma_f32_16x16x32_bf16 v[42:45], v[138:141], v[170:173], 0
	v_mfma_f32_16x16x32_bf16 v[30:33], v[130:133], v[178:181], 0
	v_mfma_f32_16x16x32_bf16 v[26:29], v[138:141], v[178:181], 0
	v_mfma_f32_16x16x32_bf16 v[14:17], v[130:133], v[206:209], 0
	v_mfma_f32_16x16x32_bf16 v[10:13], v[138:141], v[206:209], 0
	v_mfma_f32_16x16x32_bf16 v[62:65], v[134:137], v[166:169], v[62:65]
	v_mfma_f32_16x16x32_bf16 v[58:61], v[142:145], v[166:169], v[58:61]
	v_mfma_f32_16x16x32_bf16 v[46:49], v[134:137], v[174:177], v[46:49]
	v_mfma_f32_16x16x32_bf16 v[42:45], v[142:145], v[174:177], v[42:45]
	v_mfma_f32_16x16x32_bf16 v[30:33], v[134:137], v[182:185], v[30:33]
	v_mfma_f32_16x16x32_bf16 v[26:29], v[142:145], v[182:185], v[26:29]
	v_mfma_f32_16x16x32_bf16 v[14:17], v[134:137], v[210:213], v[14:17]
	v_mfma_f32_16x16x32_bf16 v[10:13], v[142:145], v[210:213], v[10:13]
	s_setprio 0
	s_setprio 1
	v_mfma_f32_16x16x32_bf16 v[54:57], v[146:149], v[162:165], 0
	v_mfma_f32_16x16x32_bf16 v[50:53], v[154:157], v[162:165], 0
	v_mfma_f32_16x16x32_bf16 v[38:41], v[146:149], v[170:173], 0
	v_mfma_f32_16x16x32_bf16 v[34:37], v[154:157], v[170:173], 0
	v_mfma_f32_16x16x32_bf16 v[22:25], v[146:149], v[178:181], 0
	v_mfma_f32_16x16x32_bf16 v[18:21], v[154:157], v[178:181], 0
	v_mfma_f32_16x16x32_bf16 v[6:9], v[146:149], v[206:209], 0
	v_mfma_f32_16x16x32_bf16 v[2:5], v[154:157], v[206:209], 0
	v_mfma_f32_16x16x32_bf16 v[54:57], v[150:153], v[166:169], v[54:57]
	v_mfma_f32_16x16x32_bf16 v[50:53], v[158:161], v[166:169], v[50:53]
	v_mfma_f32_16x16x32_bf16 v[38:41], v[150:153], v[174:177], v[38:41]
	v_mfma_f32_16x16x32_bf16 v[34:37], v[158:161], v[174:177], v[34:37]
	v_mfma_f32_16x16x32_bf16 v[22:25], v[150:153], v[182:185], v[22:25]
	v_mfma_f32_16x16x32_bf16 v[18:21], v[158:161], v[182:185], v[18:21]
	v_mfma_f32_16x16x32_bf16 v[6:9], v[150:153], v[210:213], v[6:9]
	v_mfma_f32_16x16x32_bf16 v[2:5], v[158:161], v[210:213], v[2:5]
	s_setprio 0
	s_barrier
	s_branch .Lmid_1163

; #define PG8_STAGE(bufoff, gbase, voff) do { _Pragma("unroll") for (int _i = 0; _i < 2; ++_i) \
;         __builtin_amdgcn_global_load_lds((const unsigned*)((const char*)(gbase) + (voff)[_i]), (PG8_LAS unsigned*)(lds + (bufoff) + ldsw + _i * 8192), 16, 0, 0); } while (0)
; #define PG8_LDA(dst, b, h) do { _Pragma("unroll") for (int m = 0; m < 4; ++m) _Pragma("unroll") for (int k = 0; k < 2; ++k) dst[m][k] = *(const PG8_LAS bf16x8*)(lds + PG8_SA(b, h) + aoff + m * 2048 + k * 1024); } while (0)
; #define PG8_LDB(dst, b, h) do { _Pragma("unroll") for (int n = 0; n < 2; ++n) _Pragma("unroll") for (int k = 0; k < 2; ++k) dst[n][k] = *(const PG8_LAS bf16x8*)(lds + PG8_SB(b, h) + boff + n * 2048 + k * 1024); } while (0)
; #define PG8_MMA(ai, bj, At, Bt) do { __builtin_amdgcn_s_setprio(1); _Pragma("unroll") for (int m = 0; m < 4; ++m) _Pragma("unroll") for (int n = 0; n < 2; ++n) _Pragma("unroll") for (int k = 0; k < 2; ++k) \
;         acc[ai][bj][m][n] = __builtin_amdgcn_mfma_f32_16x16x32_bf16(Bt[n][k], At[m][k], acc[ai][bj][m][n], 0, 0, 0); __builtin_amdgcn_s_setprio(0); } while (0)
; #define PG8_WAIT_V(n) asm volatile("s_waitcnt vmcnt(" #n ")" ::: "memory")
; #define PG8_WAIT_L(n) asm volatile("s_waitcnt lgkmcnt(" #n ")" ::: "memory")
; #define PG8_BAR __builtin_amdgcn_s_barrier()
; template <class Epi, class Sched, bool ALIGN_EPI = false, bool SP2 = false, bool ABLK = false, bool BBLK = false>
; __device__ __forceinline__ void gemm_phase(PG8_LAS unsigned char* lds, const Gemm g, const Sched& S, const Epi& E) {
;     ...
;         const char* nA = has_next ? (const char*)g.A + (size_t)nxt.pm * tstepA : cA; const char* nB = has_next ? (const char*)g.Bt + (size_t)nxt.pn * tstepB : cB;
;         for (int t = 0; t < nt; t += 2) {
;             const bool last = (t == nt - 2);
;             const char* a1 = cA + (size_t)(t + 1) * kstepA;
;             const char* a2 = last ? nA : cA + (size_t)(t + 2) * kstepA; const char* b2 = last ? nB : cB + (size_t)(t + 2) * kstepB;
;             const char* a3 = a2 + kstepA; const char* b3 = b2 + kstepB;
;             if (last && has_next) S.a_ready(nxt);
;             if constexpr (SP2) {
;             PG8_LDB(B0, 0, 0); PG8_LDB(B1, 0, 1); PG8_SCHED; PG8_LDA(At, 0, 0); PG8_STAGE(PG8_SA(1, 1), a1 + hstepA, voffA);
;             PG8_WAIT_V(8); PG8_WAIT_L(0); PG8_BAR; PG8_MMA(0, 0, At, B0); PG8_MMA(0, 1, At, B1); PG8_BAR; PG8_SCHED;
.LBB0_1339:
	s_ashr_i32 s19, s18, 31
	s_lshl_b64 s[20:21], s[18:19], 20
	s_add_u32 s20, s40, s20
	s_addc_u32 s21, s41, s21
	s_and_b64 s[22:23], s[6:7], exec
	s_cselect_b32 s1, s21, s27
	s_cselect_b32 s19, s20, s26
	s_ashr_i32 s15, s14, 31
	s_lshl_b64 s[22:23], s[14:15], 20
	s_add_u32 s22, s42, s22
	s_addc_u32 s23, s43, s23
	s_and_b64 s[30:31], s[6:7], exec
	s_cselect_b32 s15, s23, s29
	s_cselect_b32 s72, s22, s28
	s_add_u32 s26, s26, 0xc000
	s_addc_u32 s27, s27, 0
	s_add_u32 s73, s28, 0x10000
	s_addc_u32 s81, s29, 0
	s_mov_b32 s83, -2
	s_add_u32 s28, s26, 0x4000
	s_addc_u32 s29, s27, 0
	s_cmp_eq_u32 s83, 28
	s_cselect_b32 s34, s19, s28
	s_cselect_b32 s35, s1, s29
	s_cselect_b32 s30, s72, s73
	s_cselect_b32 s31, s15, s81
	s_add_u32 s28, s34, 0x8000
	s_addc_u32 s29, s35, 0
	s_add_i32 s52, 0, 0x10000
	v_add_u32_e32 v142, s52, v145
	s_add_i32 s75, 0, 0x14000
	ds_read_b128 v[148:151], v142
	ds_read_b128 v[152:155], v142 offset:1024
	ds_read_b128 v[156:159], v142 offset:2048
	ds_read_b128 v[160:163], v142 offset:3072
	v_add_u32_e32 v142, s75, v145
	ds_read_b128 v[164:167], v142
	ds_read_b128 v[168:171], v142 offset:1024
	ds_read_b128 v[172:175], v142 offset:2048
	ds_read_b128 v[176:179], v142 offset:3072
	v_lshl_add_u64 v[142:143], s[26:27], 0, v[138:139]
	s_add_i32 m0, s25, 0xc000
	ds_read_b128 v[180:183], v146
	ds_read_b128 v[196:199], v146 offset:1024
	ds_read_b128 v[200:203], v146 offset:2048
	ds_read_b128 v[204:207], v146 offset:3072
	ds_read_b128 v[208:211], v146 offset:4096
	ds_read_b128 v[212:215], v146 offset:5120
	ds_read_b128 v[216:219], v146 offset:6144
	ds_read_b128 v[220:223], v146 offset:7168
	global_load_lds_dwordx4 v[142:143], off
	v_lshl_add_u64 v[142:143], s[26:27], 0, v[140:141]
	s_add_i32 m0, s25, 0xe000
	s_nop 0
	global_load_lds_dwordx4 v[142:143], off
	s_waitcnt vmcnt(8)
	s_waitcnt lgkmcnt(0)
	s_barrier
	s_setprio 1
	s_waitcnt lgkmcnt(0)
	v_mfma_f32_16x16x32_bf16 v[126:129], v[148:151], v[180:183], 0
	v_mfma_f32_16x16x32_bf16 v[118:121], v[156:159], v[180:183], 0
	v_mfma_f32_16x16x32_bf16 v[110:113], v[148:151], v[200:203], 0
	v_mfma_f32_16x16x32_bf16 v[102:105], v[156:159], v[200:203], 0
	v_mfma_f32_16x16x32_bf16 v[94:97], v[148:151], v[208:211], 0
	v_mfma_f32_16x16x32_bf16 v[86:89], v[156:159], v[208:211], 0
	v_mfma_f32_16x16x32_bf16 v[78:81], v[148:151], v[216:219], 0
	v_mfma_f32_16x16x32_bf16 v[70:73], v[156:159], v[216:219], 0
	v_mfma_f32_16x16x32_bf16 v[126:129], v[152:155], v[196:199], v[126:129]
	v_mfma_f32_16x16x32_bf16 v[118:121], v[160:163], v[196:199], v[118:121]
	v_mfma_f32_16x16x32_bf16 v[110:113], v[152:155], v[204:207], v[110:113]
	v_mfma_f32_16x16x32_bf16 v[102:105], v[160:163], v[204:207], v[102:105]
	v_mfma_f32_16x16x32_bf16 v[94:97], v[152:155], v[212:215], v[94:97]
	v_mfma_f32_16x16x32_bf16 v[86:89], v[160:163], v[212:215], v[86:89]
	v_mfma_f32_16x16x32_bf16 v[78:81], v[152:155], v[220:223], v[78:81]
	v_mfma_f32_16x16x32_bf16 v[70:73], v[160:163], v[220:223], v[70:73]
	s_setprio 0
	s_setprio 1
	v_mfma_f32_16x16x32_bf16 v[122:125], v[164:167], v[180:183], 0
	v_mfma_f32_16x16x32_bf16 v[114:117], v[172:175], v[180:183], 0
	v_mfma_f32_16x16x32_bf16 v[106:109], v[164:167], v[200:203], 0
	v_mfma_f32_16x16x32_bf16 v[98:101], v[172:175], v[200:203], 0
	v_mfma_f32_16x16x32_bf16 v[90:93], v[164:167], v[208:211], 0
	v_mfma_f32_16x16x32_bf16 v[82:85], v[172:175], v[208:211], 0
	v_mfma_f32_16x16x32_bf16 v[74:77], v[164:167], v[216:219], 0
	v_mfma_f32_16x16x32_bf16 v[66:69], v[172:175], v[216:219], 0
	v_mfma_f32_16x16x32_bf16 v[122:125], v[168:171], v[196:199], v[122:125]
	v_mfma_f32_16x16x32_bf16 v[114:117], v[176:179], v[196:199], v[114:117]
	v_mfma_f32_16x16x32_bf16 v[106:109], v[168:171], v[204:207], v[106:109]
	v_mfma_f32_16x16x32_bf16 v[98:101], v[176:179], v[204:207], v[98:101]
	v_mfma_f32_16x16x32_bf16 v[90:93], v[168:171], v[212:215], v[90:93]
	v_mfma_f32_16x16x32_bf16 v[82:85], v[176:179], v[212:215], v[82:85]
	v_mfma_f32_16x16x32_bf16 v[74:77], v[168:171], v[220:223], v[74:77]
	v_mfma_f32_16x16x32_bf16 v[66:69], v[176:179], v[220:223], v[66:69]
	s_setprio 0
	s_barrier
; #define PG8_STAGE(bufoff, gbase, voff) do { _Pragma("unroll") for (int _i = 0; _i < 2; ++_i) \
;         __builtin_amdgcn_global_load_lds((const unsigned*)((const char*)(gbase) + (voff)[_i]), (PG8_LAS unsigned*)(lds + (bufoff) + ldsw + _i * 8192), 16, 0, 0); } while (0)
; #define PG8_LDA(dst, b, h) do { _Pragma("unroll") for (int m = 0; m < 4; ++m) _Pragma("unroll") for (int k = 0; k < 2; ++k) dst[m][k] = *(const PG8_LAS bf16x8*)(lds + PG8_SA(b, h) + aoff + m * 2048 + k * 1024); } while (0)
; #define PG8_MMA(ai, bj, At, Bt) do { __builtin_amdgcn_s_setprio(1); _Pragma("unroll") for (int m = 0; m < 4; ++m) _Pragma("unroll") for (int n = 0; n < 2; ++n) _Pragma("unroll") for (int k = 0; k < 2; ++k) \
;         acc[ai][bj][m][n] = __builtin_amdgcn_mfma_f32_16x16x32_bf16(Bt[n][k], At[m][k], acc[ai][bj][m][n], 0, 0, 0); __builtin_amdgcn_s_setprio(0); } while (0)
; #define PG8_WAIT_V(n) asm volatile("s_waitcnt vmcnt(" #n ")" ::: "memory")
; #define PG8_WAIT_L(n) asm volatile("s_waitcnt lgkmcnt(" #n ")" ::: "memory")
; #define PG8_BAR __builtin_amdgcn_s_barrier()
; #define PG8_SCHED __builtin_amdgcn_sched_barrier(0)
; template <class Epi, class Sched, bool ALIGN_EPI = false, bool SP2 = false, bool ABLK = false, bool BBLK = false>
; __device__ __forceinline__ void gemm_phase(PG8_LAS unsigned char* lds, const Gemm g, const Sched& S, const Epi& E) {
;     ...
;             PG8_LDA(At, 0, 1); PG8_STAGE(PG8_SB(0, 0), b2, voffB); PG8_STAGE(PG8_SB(0, 1), b2 + hstepB, voffB); PG8_STAGE(PG8_SA(0, 0), a2, voffA);
;             PG8_WAIT_V(8); PG8_WAIT_L(0); PG8_BAR; PG8_MMA(1, 0, At, B0); PG8_MMA(1, 1, At, B1); PG8_BAR; PG8_SCHED;
	s_add_i32 s52, s52, s44
	v_lshl_add_u64 v[142:143], s[30:31], 0, v[134:135]
	s_mov_b32 m0, s52
	ds_read_b128 v[180:183], v146 offset:16384
	ds_read_b128 v[196:199], v146 offset:17408
	ds_read_b128 v[200:203], v146 offset:18432
	ds_read_b128 v[204:207], v146 offset:19456
	ds_read_b128 v[208:211], v146 offset:20480
	ds_read_b128 v[212:215], v146 offset:21504
	ds_read_b128 v[216:219], v146 offset:22528
	ds_read_b128 v[220:223], v146 offset:23552
	global_load_lds_dwordx4 v[142:143], off
	s_add_i32 m0, s52, 0x2000
	s_add_u32 s88, s30, 0x4000
	v_lshl_add_u64 v[142:143], s[30:31], 0, v[130:131]
	s_addc_u32 s89, s31, 0
	s_add_i32 s52, s75, s44
	global_load_lds_dwordx4 v[142:143], off
	v_lshl_add_u64 v[142:143], s[88:89], 0, v[134:135]
	s_mov_b32 m0, s52
	s_nop 0
	global_load_lds_dwordx4 v[142:143], off
	v_lshl_add_u64 v[142:143], s[88:89], 0, v[130:131]
	s_add_i32 m0, s52, 0x2000
	s_nop 0
	global_load_lds_dwordx4 v[142:143], off
	v_lshl_add_u64 v[142:143], s[34:35], 0, v[136:137]
	s_mov_b32 m0, s25
	s_nop 0
	global_load_lds_dwordx4 v[142:143], off
	v_lshl_add_u64 v[142:143], s[34:35], 0, v[132:133]
	s_mov_b32 m0, s46
	s_nop 0
	global_load_lds_dwordx4 v[142:143], off
	s_waitcnt vmcnt(8)
	s_waitcnt lgkmcnt(0)
	s_barrier
	s_setprio 1
	s_waitcnt lgkmcnt(0)
	v_mfma_f32_16x16x32_bf16 v[62:65], v[148:151], v[180:183], 0
	v_mfma_f32_16x16x32_bf16 v[54:57], v[156:159], v[180:183], 0
	v_mfma_f32_16x16x32_bf16 v[46:49], v[148:151], v[200:203], 0
	v_mfma_f32_16x16x32_bf16 v[38:41], v[156:159], v[200:203], 0
	v_mfma_f32_16x16x32_bf16 v[30:33], v[148:151], v[208:211], 0
	v_mfma_f32_16x16x32_bf16 v[22:25], v[156:159], v[208:211], 0
	v_mfma_f32_16x16x32_bf16 v[14:17], v[148:151], v[216:219], 0
	v_mfma_f32_16x16x32_bf16 v[6:9], v[156:159], v[216:219], 0
	v_mfma_f32_16x16x32_bf16 v[62:65], v[152:155], v[196:199], v[62:65]
	v_mfma_f32_16x16x32_bf16 v[54:57], v[160:163], v[196:199], v[54:57]
	v_mfma_f32_16x16x32_bf16 v[46:49], v[152:155], v[204:207], v[46:49]
	v_mfma_f32_16x16x32_bf16 v[38:41], v[160:163], v[204:207], v[38:41]
	v_mfma_f32_16x16x32_bf16 v[30:33], v[152:155], v[212:215], v[30:33]
	v_mfma_f32_16x16x32_bf16 v[22:25], v[160:163], v[212:215], v[22:25]
	v_mfma_f32_16x16x32_bf16 v[14:17], v[152:155], v[220:223], v[14:17]
	v_mfma_f32_16x16x32_bf16 v[6:9], v[160:163], v[220:223], v[6:9]
	s_setprio 0
	s_setprio 1
	v_mfma_f32_16x16x32_bf16 v[58:61], v[164:167], v[180:183], 0
	v_mfma_f32_16x16x32_bf16 v[50:53], v[172:175], v[180:183], 0
	v_mfma_f32_16x16x32_bf16 v[42:45], v[164:167], v[200:203], 0
	v_mfma_f32_16x16x32_bf16 v[34:37], v[172:175], v[200:203], 0
	v_mfma_f32_16x16x32_bf16 v[26:29], v[164:167], v[208:211], 0
	v_mfma_f32_16x16x32_bf16 v[18:21], v[172:175], v[208:211], 0
	v_mfma_f32_16x16x32_bf16 v[10:13], v[164:167], v[216:219], 0
	v_mfma_f32_16x16x32_bf16 v[2:5], v[172:175], v[216:219], 0
	v_mfma_f32_16x16x32_bf16 v[58:61], v[168:171], v[196:199], v[58:61]
	v_mfma_f32_16x16x32_bf16 v[50:53], v[176:179], v[196:199], v[50:53]
	v_mfma_f32_16x16x32_bf16 v[42:45], v[168:171], v[204:207], v[42:45]
	v_mfma_f32_16x16x32_bf16 v[34:37], v[176:179], v[204:207], v[34:37]
	v_mfma_f32_16x16x32_bf16 v[26:29], v[168:171], v[212:215], v[26:29]
	v_mfma_f32_16x16x32_bf16 v[18:21], v[176:179], v[212:215], v[18:21]
	v_mfma_f32_16x16x32_bf16 v[10:13], v[168:171], v[220:223], v[10:13]
	v_mfma_f32_16x16x32_bf16 v[2:5], v[176:179], v[220:223], v[2:5]
	s_setprio 0
	s_barrier
	s_branch .Lmid_1340

; #define PG8_STAGE(bufoff, gbase, voff) do { _Pragma("unroll") for (int _i = 0; _i < 2; ++_i) \
;         __builtin_amdgcn_global_load_lds((const unsigned*)((const char*)(gbase) + (voff)[_i]), (PG8_LAS unsigned*)(lds + (bufoff) + ldsw + _i * 8192), 16, 0, 0); } while (0)
; #define PG8_LDA(dst, b, h) do { _Pragma("unroll") for (int m = 0; m < 4; ++m) _Pragma("unroll") for (int k = 0; k < 2; ++k) dst[m][k] = *(const PG8_LAS bf16x8*)(lds + PG8_SA(b, h) + aoff + m * 2048 + k * 1024); } while (0)
; #define PG8_LDB(dst, b, h) do { _Pragma("unroll") for (int n = 0; n < 2; ++n) _Pragma("unroll") for (int k = 0; k < 2; ++k) dst[n][k] = *(const PG8_LAS bf16x8*)(lds + PG8_SB(b, h) + boff + n * 2048 + k * 1024); } while (0)
; #define PG8_MMA(ai, bj, At, Bt) do { __builtin_amdgcn_s_setprio(1); _Pragma("unroll") for (int m = 0; m < 4; ++m) _Pragma("unroll") for (int n = 0; n < 2; ++n) _Pragma("unroll") for (int k = 0; k < 2; ++k) \
;         acc[ai][bj][m][n] = __builtin_amdgcn_mfma_f32_16x16x32_bf16(Bt[n][k], At[m][k], acc[ai][bj][m][n], 0, 0, 0); __builtin_amdgcn_s_setprio(0); } while (0)
; #define PG8_WAIT_V(n) asm volatile("s_waitcnt vmcnt(" #n ")" ::: "memory")
; #define PG8_WAIT_L(n) asm volatile("s_waitcnt lgkmcnt(" #n ")" ::: "memory")
; #define PG8_BAR __builtin_amdgcn_s_barrier()
; #define PG8_SCHED __builtin_amdgcn_sched_barrier(0)
; template <class Epi, class Sched, bool ALIGN_EPI = false, bool SP2 = false, bool ABLK = false, bool BBLK = false>
; __device__ __forceinline__ void gemm_phase(PG8_LAS unsigned char* lds, const Gemm g, const Sched& S, const Epi& E) {
;     ...
;             const char* a1 = cA + (size_t)(t + 1) * kstepA;
;             const char* a2 = last ? nA : cA + (size_t)(t + 2) * kstepA; const char* b2 = last ? nB : cB + (size_t)(t + 2) * kstepB;
;             const char* a3 = a2 + kstepA; const char* b3 = b2 + kstepB;
;             if (last && has_next) S.a_ready(nxt);
;             if constexpr (SP2) {
;             PG8_LDB(B0, 0, 0); PG8_LDB(B1, 0, 1); PG8_SCHED; PG8_LDA(At, 0, 0); PG8_STAGE(PG8_SA(1, 1), a1 + hstepA, voffA);
;             PG8_WAIT_V(8); PG8_WAIT_L(0); PG8_BAR; PG8_MMA(0, 0, At, B0); PG8_MMA(0, 1, At, B1); PG8_BAR; PG8_SCHED;
.LBB0_1419:
	s_add_u32 s0, s0, 0xc000
	s_addc_u32 s1, s1, 0
	s_add_u32 s23, s26, 0x10000
	s_addc_u32 s25, s27, 0
	s_mov_b32 s73, -2
	s_add_u32 s8, s0, 0x4000
	s_addc_u32 s9, s1, 0
	s_cmpk_eq_i32 s73, 0x54
	s_cselect_b32 s28, s18, s8
	s_cselect_b32 s29, s19, s9
	s_cselect_b32 s26, s20, s23
	s_cselect_b32 s27, s21, s25
	s_add_u32 s8, s28, 0x8000
	s_addc_u32 s9, s29, 0
	s_add_i32 s52, 0, 0x10000
	s_add_i32 s75, 0, 0x14000
	v_add_u32_e32 v142, s52, v180
	v_add_u32_e32 v168, s75, v180
	ds_read_b128 v[130:133], v142
	ds_read_b128 v[134:137], v142 offset:1024
	ds_read_b128 v[138:141], v142 offset:2048
	ds_read_b128 v[142:145], v142 offset:3072
	ds_read_b128 v[156:159], v168
	ds_read_b128 v[160:163], v168 offset:1024
	ds_read_b128 v[164:167], v168 offset:2048
	ds_read_b128 v[168:171], v168 offset:3072
	v_lshl_add_u64 v[176:177], s[0:1], 0, v[152:153]
	s_add_i32 m0, s3, 0xc000
	ds_read_b128 v[172:175], v181
	ds_read_b128 v[182:185], v181 offset:1024
	ds_read_b128 v[196:199], v181 offset:2048
	ds_read_b128 v[200:203], v181 offset:3072
	ds_read_b128 v[204:207], v181 offset:4096
	ds_read_b128 v[208:211], v181 offset:5120
	ds_read_b128 v[212:215], v181 offset:6144
	ds_read_b128 v[216:219], v181 offset:7168
	global_load_lds_dwordx4 v[176:177], off
	v_lshl_add_u64 v[176:177], s[0:1], 0, v[154:155]
	s_add_i32 m0, s3, 0xe000
	s_nop 0
	global_load_lds_dwordx4 v[176:177], off
	s_waitcnt vmcnt(8)
	s_waitcnt lgkmcnt(0)
	s_barrier
	s_setprio 1
	s_waitcnt lgkmcnt(0)
	v_mfma_f32_16x16x32_bf16 v[58:61], v[130:133], v[172:175], 0
	v_mfma_f32_16x16x32_bf16 v[50:53], v[138:141], v[172:175], 0
	v_mfma_f32_16x16x32_bf16 v[78:81], v[130:133], v[196:199], 0
	v_mfma_f32_16x16x32_bf16 v[70:73], v[138:141], v[196:199], 0
	v_mfma_f32_16x16x32_bf16 v[98:101], v[130:133], v[204:207], 0
	v_mfma_f32_16x16x32_bf16 v[102:105], v[138:141], v[204:207], 0
	v_mfma_f32_16x16x32_bf16 v[114:117], v[130:133], v[212:215], 0
	v_mfma_f32_16x16x32_bf16 v[118:121], v[138:141], v[212:215], 0
	v_mfma_f32_16x16x32_bf16 v[58:61], v[134:137], v[182:185], v[58:61]
	v_mfma_f32_16x16x32_bf16 v[50:53], v[142:145], v[182:185], v[50:53]
	v_mfma_f32_16x16x32_bf16 v[78:81], v[134:137], v[200:203], v[78:81]
	v_mfma_f32_16x16x32_bf16 v[70:73], v[142:145], v[200:203], v[70:73]
	v_mfma_f32_16x16x32_bf16 v[98:101], v[134:137], v[208:211], v[98:101]
	v_mfma_f32_16x16x32_bf16 v[102:105], v[142:145], v[208:211], v[102:105]
	v_mfma_f32_16x16x32_bf16 v[114:117], v[134:137], v[216:219], v[114:117]
	v_mfma_f32_16x16x32_bf16 v[118:121], v[142:145], v[216:219], v[118:121]
	s_setprio 0
	s_setprio 1
	v_mfma_f32_16x16x32_bf16 v[66:69], v[156:159], v[172:175], 0
	v_mfma_f32_16x16x32_bf16 v[54:57], v[164:167], v[172:175], 0
	v_mfma_f32_16x16x32_bf16 v[86:89], v[156:159], v[196:199], 0
	v_mfma_f32_16x16x32_bf16 v[94:97], v[164:167], v[196:199], 0
	v_mfma_f32_16x16x32_bf16 v[106:109], v[156:159], v[204:207], 0
	v_mfma_f32_16x16x32_bf16 v[110:113], v[164:167], v[204:207], 0
	v_mfma_f32_16x16x32_bf16 v[122:125], v[156:159], v[212:215], 0
	v_mfma_f32_16x16x32_bf16 v[126:129], v[164:167], v[212:215], 0
	v_mfma_f32_16x16x32_bf16 v[66:69], v[160:163], v[182:185], v[66:69]
	v_mfma_f32_16x16x32_bf16 v[54:57], v[168:171], v[182:185], v[54:57]
	v_mfma_f32_16x16x32_bf16 v[86:89], v[160:163], v[200:203], v[86:89]
	v_mfma_f32_16x16x32_bf16 v[94:97], v[168:171], v[200:203], v[94:97]
	v_mfma_f32_16x16x32_bf16 v[106:109], v[160:163], v[208:211], v[106:109]
	v_mfma_f32_16x16x32_bf16 v[110:113], v[168:171], v[208:211], v[110:113]
	v_mfma_f32_16x16x32_bf16 v[122:125], v[160:163], v[216:219], v[122:125]
	v_mfma_f32_16x16x32_bf16 v[126:129], v[168:171], v[216:219], v[126:129]
	s_setprio 0
	s_barrier
; #define PG8_STAGE(bufoff, gbase, voff) do { _Pragma("unroll") for (int _i = 0; _i < 2; ++_i) \
;         __builtin_amdgcn_global_load_lds((const unsigned*)((const char*)(gbase) + (voff)[_i]), (PG8_LAS unsigned*)(lds + (bufoff) + ldsw + _i * 8192), 16, 0, 0); } while (0)
; #define PG8_LDA(dst, b, h) do { _Pragma("unroll") for (int m = 0; m < 4; ++m) _Pragma("unroll") for (int k = 0; k < 2; ++k) dst[m][k] = *(const PG8_LAS bf16x8*)(lds + PG8_SA(b, h) + aoff + m * 2048 + k * 1024); } while (0)
; #define PG8_MMA(ai, bj, At, Bt) do { __builtin_amdgcn_s_setprio(1); _Pragma("unroll") for (int m = 0; m < 4; ++m) _Pragma("unroll") for (int n = 0; n < 2; ++n) _Pragma("unroll") for (int k = 0; k < 2; ++k) \
;         acc[ai][bj][m][n] = __builtin_amdgcn_mfma_f32_16x16x32_bf16(Bt[n][k], At[m][k], acc[ai][bj][m][n], 0, 0, 0); __builtin_amdgcn_s_setprio(0); } while (0)
; #define PG8_WAIT_V(n) asm volatile("s_waitcnt vmcnt(" #n ")" ::: "memory")
; #define PG8_WAIT_L(n) asm volatile("s_waitcnt lgkmcnt(" #n ")" ::: "memory")
; #define PG8_BAR __builtin_amdgcn_s_barrier()
; #define PG8_SCHED __builtin_amdgcn_sched_barrier(0)
; template <class Epi, class Sched, bool ALIGN_EPI = false, bool SP2 = false, bool ABLK = false, bool BBLK = false>
; __device__ __forceinline__ void gemm_phase(PG8_LAS unsigned char* lds, const Gemm g, const Sched& S, const Epi& E) {
;     ...
;             PG8_LDA(At, 0, 1); PG8_STAGE(PG8_SB(0, 0), b2, voffB); PG8_STAGE(PG8_SB(0, 1), b2 + hstepB, voffB); PG8_STAGE(PG8_SA(0, 0), a2, voffA);
;             PG8_WAIT_V(8); PG8_WAIT_L(0); PG8_BAR; PG8_MMA(1, 0, At, B0); PG8_MMA(1, 1, At, B1); PG8_BAR; PG8_SCHED;
	s_add_i32 s52, s52, s2
	v_lshl_add_u64 v[176:177], s[26:27], 0, v[186:187]
	s_mov_b32 m0, s52
	ds_read_b128 v[172:175], v181 offset:16384
	ds_read_b128 v[182:185], v181 offset:17408
	ds_read_b128 v[196:199], v181 offset:18432
	ds_read_b128 v[200:203], v181 offset:19456
	ds_read_b128 v[204:207], v181 offset:20480
	ds_read_b128 v[208:211], v181 offset:21504
	ds_read_b128 v[212:215], v181 offset:22528
	ds_read_b128 v[216:219], v181 offset:23552
	global_load_lds_dwordx4 v[176:177], off
	s_add_i32 m0, s52, 0x2000
	s_add_u32 s80, s26, 0x4000
	v_lshl_add_u64 v[176:177], s[26:27], 0, v[150:151]
	s_addc_u32 s81, s27, 0
	s_add_i32 s52, s75, s2
	global_load_lds_dwordx4 v[176:177], off
	v_lshl_add_u64 v[176:177], s[80:81], 0, v[186:187]
	s_mov_b32 m0, s52
	s_nop 0
	global_load_lds_dwordx4 v[176:177], off
	v_lshl_add_u64 v[176:177], s[80:81], 0, v[150:151]
	s_add_i32 m0, s52, 0x2000
	s_nop 0
	global_load_lds_dwordx4 v[176:177], off
	v_lshl_add_u64 v[176:177], s[28:29], 0, v[146:147]
	s_mov_b32 m0, s3
	s_nop 0
	global_load_lds_dwordx4 v[176:177], off
	v_lshl_add_u64 v[176:177], s[28:29], 0, v[148:149]
	s_mov_b32 m0, s16
	s_nop 0
	global_load_lds_dwordx4 v[176:177], off
	s_waitcnt vmcnt(8)
	s_waitcnt lgkmcnt(0)
	s_barrier
	s_setprio 1
	s_waitcnt lgkmcnt(0)
	v_mfma_f32_16x16x32_bf16 v[90:93], v[130:133], v[172:175], 0
	v_mfma_f32_16x16x32_bf16 v[82:85], v[138:141], v[172:175], 0
	v_mfma_f32_16x16x32_bf16 v[46:49], v[130:133], v[196:199], 0
	v_mfma_f32_16x16x32_bf16 v[42:45], v[138:141], v[196:199], 0
	v_mfma_f32_16x16x32_bf16 v[30:33], v[130:133], v[204:207], 0
	v_mfma_f32_16x16x32_bf16 v[26:29], v[138:141], v[204:207], 0
	v_mfma_f32_16x16x32_bf16 v[14:17], v[130:133], v[212:215], 0
	v_mfma_f32_16x16x32_bf16 v[10:13], v[138:141], v[212:215], 0
	v_mfma_f32_16x16x32_bf16 v[90:93], v[134:137], v[182:185], v[90:93]
	v_mfma_f32_16x16x32_bf16 v[82:85], v[142:145], v[182:185], v[82:85]
	v_mfma_f32_16x16x32_bf16 v[46:49], v[134:137], v[200:203], v[46:49]
	v_mfma_f32_16x16x32_bf16 v[42:45], v[142:145], v[200:203], v[42:45]
	v_mfma_f32_16x16x32_bf16 v[30:33], v[134:137], v[208:211], v[30:33]
	v_mfma_f32_16x16x32_bf16 v[26:29], v[142:145], v[208:211], v[26:29]
	v_mfma_f32_16x16x32_bf16 v[14:17], v[134:137], v[216:219], v[14:17]
	v_mfma_f32_16x16x32_bf16 v[10:13], v[142:145], v[216:219], v[10:13]
	s_setprio 0
	s_setprio 1
	v_mfma_f32_16x16x32_bf16 v[74:77], v[156:159], v[172:175], 0
	v_mfma_f32_16x16x32_bf16 v[62:65], v[164:167], v[172:175], 0
	v_mfma_f32_16x16x32_bf16 v[38:41], v[156:159], v[196:199], 0
	v_mfma_f32_16x16x32_bf16 v[34:37], v[164:167], v[196:199], 0
	v_mfma_f32_16x16x32_bf16 v[22:25], v[156:159], v[204:207], 0
	v_mfma_f32_16x16x32_bf16 v[18:21], v[164:167], v[204:207], 0
	v_mfma_f32_16x16x32_bf16 v[6:9], v[156:159], v[212:215], 0
	v_mfma_f32_16x16x32_bf16 v[2:5], v[164:167], v[212:215], 0
	v_mfma_f32_16x16x32_bf16 v[74:77], v[160:163], v[182:185], v[74:77]
	v_mfma_f32_16x16x32_bf16 v[62:65], v[168:171], v[182:185], v[62:65]
	v_mfma_f32_16x16x32_bf16 v[38:41], v[160:163], v[200:203], v[38:41]
	v_mfma_f32_16x16x32_bf16 v[34:37], v[168:171], v[200:203], v[34:37]
	v_mfma_f32_16x16x32_bf16 v[22:25], v[160:163], v[208:211], v[22:25]
	v_mfma_f32_16x16x32_bf16 v[18:21], v[168:171], v[208:211], v[18:21]
	v_mfma_f32_16x16x32_bf16 v[6:9], v[160:163], v[216:219], v[6:9]
	v_mfma_f32_16x16x32_bf16 v[2:5], v[168:171], v[216:219], v[2:5]
	s_setprio 0
	s_barrier
	s_branch .Lmid_1420

; #define PG8_STAGE(bufoff, gbase, voff) do { _Pragma("unroll") for (int _i = 0; _i < 2; ++_i) \
;         __builtin_amdgcn_global_load_lds((const unsigned*)((const char*)(gbase) + (voff)[_i]), (PG8_LAS unsigned*)(lds + (bufoff) + ldsw + _i * 8192), 16, 0, 0); } while (0)
; #define PG8_LDA(dst, b, h) do { _Pragma("unroll") for (int m = 0; m < 4; ++m) _Pragma("unroll") for (int k = 0; k < 2; ++k) dst[m][k] = *(const PG8_LAS bf16x8*)(lds + PG8_SA(b, h) + aoff + m * 2048 + k * 1024); } while (0)
; #define PG8_LDB(dst, b, h) do { _Pragma("unroll") for (int n = 0; n < 2; ++n) _Pragma("unroll") for (int k = 0; k < 2; ++k) dst[n][k] = *(const PG8_LAS bf16x8*)(lds + PG8_SB(b, h) + boff + n * 2048 + k * 1024); } while (0)
; #define PG8_MMA(ai, bj, At, Bt) do { __builtin_amdgcn_s_setprio(1); _Pragma("unroll") for (int m = 0; m < 4; ++m) _Pragma("unroll") for (int n = 0; n < 2; ++n) _Pragma("unroll") for (int k = 0; k < 2; ++k) \
;         acc[ai][bj][m][n] = __builtin_amdgcn_mfma_f32_16x16x32_bf16(Bt[n][k], At[m][k], acc[ai][bj][m][n], 0, 0, 0); __builtin_amdgcn_s_setprio(0); } while (0)
; #define PG8_WAIT_V(n) asm volatile("s_waitcnt vmcnt(" #n ")" ::: "memory")
; #define PG8_WAIT_L(n) asm volatile("s_waitcnt lgkmcnt(" #n ")" ::: "memory")
; #define PG8_BAR __builtin_amdgcn_s_barrier()
; #define PG8_SCHED __builtin_amdgcn_sched_barrier(0)
; template <class Epi, class Sched, bool ALIGN_EPI = false, bool SP2 = false, bool ABLK = false, bool BBLK = false>
; __device__ __forceinline__ void gemm_phase(PG8_LAS unsigned char* lds, const Gemm g, const Sched& S, const Epi& E) {
;     ...
;             const char* a1 = cA + (size_t)(t + 1) * kstepA;
;             const char* a2 = last ? nA : cA + (size_t)(t + 2) * kstepA; const char* b2 = last ? nB : cB + (size_t)(t + 2) * kstepB;
;             const char* a3 = a2 + kstepA; const char* b3 = b2 + kstepB;
;             if (last && has_next) S.a_ready(nxt);
;             if constexpr (SP2) {
;             PG8_LDB(B0, 0, 0); PG8_LDB(B1, 0, 1); PG8_SCHED; PG8_LDA(At, 0, 0); PG8_STAGE(PG8_SA(1, 1), a1 + hstepA, voffA);
;             PG8_WAIT_V(8); PG8_WAIT_L(0); PG8_BAR; PG8_MMA(0, 0, At, B0); PG8_MMA(0, 1, At, B1); PG8_BAR; PG8_SCHED;
.LBB0_1482:
	s_add_u32 s0, s0, 0xc000
	s_addc_u32 s1, s1, 0
	s_add_u32 s31, s36, 0x10000
	s_addc_u32 s33, s37, 0
	s_mov_b32 s35, -2
	s_add_u32 s8, s0, 0x4000
	s_addc_u32 s9, s1, 0
	s_cmpk_eq_i32 s35, 0x54
	s_cselect_b32 s40, s26, s8
	s_cselect_b32 s41, s27, s9
	s_cselect_b32 s36, s28, s31
	s_cselect_b32 s37, s29, s33
	s_add_u32 s8, s40, 0x8000
	s_addc_u32 s9, s41, 0
	s_add_i32 s44, 0, 0x10000
	s_add_i32 s52, 0, 0x14000
	v_add_u32_e32 v142, s44, v206
	v_add_u32_e32 v158, s52, v206
	ds_read_b128 v[130:133], v142
	ds_read_b128 v[134:137], v142 offset:1024
	ds_read_b128 v[138:141], v142 offset:2048
	ds_read_b128 v[142:145], v142 offset:3072
	ds_read_b128 v[146:149], v158
	ds_read_b128 v[150:153], v158 offset:1024
	ds_read_b128 v[154:157], v158 offset:2048
	ds_read_b128 v[158:161], v158 offset:3072
	v_lshl_add_u64 v[188:189], s[0:1], 0, v[184:185]
	s_add_i32 m0, s68, 0xc000
	ds_read_b128 v[162:165], v207
	ds_read_b128 v[166:169], v207 offset:1024
	ds_read_b128 v[170:173], v207 offset:2048
	ds_read_b128 v[174:177], v207 offset:3072
	ds_read_b128 v[198:201], v207 offset:4096
	ds_read_b128 v[208:211], v207 offset:5120
	ds_read_b128 v[212:215], v207 offset:6144
	ds_read_b128 v[216:219], v207 offset:7168
	global_load_lds_dwordx4 v[188:189], off
	v_lshl_add_u64 v[188:189], s[0:1], 0, v[196:197]
	s_add_i32 m0, s68, 0xe000
	s_nop 0
	global_load_lds_dwordx4 v[188:189], off
	s_waitcnt vmcnt(8)
	s_waitcnt lgkmcnt(0)
	s_barrier
	s_setprio 1
	s_waitcnt lgkmcnt(0)
	v_mfma_f32_16x16x32_bf16 v[30:33], v[130:133], v[162:165], 0
	v_mfma_f32_16x16x32_bf16 v[22:25], v[138:141], v[162:165], 0
	v_mfma_f32_16x16x32_bf16 v[18:21], v[130:133], v[170:173], 0
	v_mfma_f32_16x16x32_bf16 v[10:13], v[138:141], v[170:173], 0
	v_mfma_f32_16x16x32_bf16 v[50:53], v[130:133], v[198:201], 0
	v_mfma_f32_16x16x32_bf16 v[54:57], v[138:141], v[198:201], 0
	v_mfma_f32_16x16x32_bf16 v[74:77], v[130:133], v[212:215], 0
	v_mfma_f32_16x16x32_bf16 v[78:81], v[138:141], v[212:215], 0
	v_mfma_f32_16x16x32_bf16 v[30:33], v[134:137], v[166:169], v[30:33]
	v_mfma_f32_16x16x32_bf16 v[22:25], v[142:145], v[166:169], v[22:25]
	v_mfma_f32_16x16x32_bf16 v[18:21], v[134:137], v[174:177], v[18:21]
	v_mfma_f32_16x16x32_bf16 v[10:13], v[142:145], v[174:177], v[10:13]
	v_mfma_f32_16x16x32_bf16 v[50:53], v[134:137], v[208:211], v[50:53]
	v_mfma_f32_16x16x32_bf16 v[54:57], v[142:145], v[208:211], v[54:57]
	v_mfma_f32_16x16x32_bf16 v[74:77], v[134:137], v[216:219], v[74:77]
	v_mfma_f32_16x16x32_bf16 v[78:81], v[142:145], v[216:219], v[78:81]
	s_setprio 0
	s_setprio 1
	v_mfma_f32_16x16x32_bf16 v[26:29], v[146:149], v[162:165], 0
	v_mfma_f32_16x16x32_bf16 v[14:17], v[154:157], v[162:165], 0
	v_mfma_f32_16x16x32_bf16 v[42:45], v[146:149], v[170:173], 0
	v_mfma_f32_16x16x32_bf16 v[46:49], v[154:157], v[170:173], 0
	v_mfma_f32_16x16x32_bf16 v[66:69], v[146:149], v[198:201], 0
	v_mfma_f32_16x16x32_bf16 v[70:73], v[154:157], v[198:201], 0
	v_mfma_f32_16x16x32_bf16 v[82:85], v[146:149], v[212:215], 0
	v_mfma_f32_16x16x32_bf16 v[86:89], v[154:157], v[212:215], 0
	v_mfma_f32_16x16x32_bf16 v[26:29], v[150:153], v[166:169], v[26:29]
	v_mfma_f32_16x16x32_bf16 v[14:17], v[158:161], v[166:169], v[14:17]
	v_mfma_f32_16x16x32_bf16 v[42:45], v[150:153], v[174:177], v[42:45]
	v_mfma_f32_16x16x32_bf16 v[46:49], v[158:161], v[174:177], v[46:49]
	v_mfma_f32_16x16x32_bf16 v[66:69], v[150:153], v[208:211], v[66:69]
	v_mfma_f32_16x16x32_bf16 v[70:73], v[158:161], v[208:211], v[70:73]
	v_mfma_f32_16x16x32_bf16 v[82:85], v[150:153], v[216:219], v[82:85]
	v_mfma_f32_16x16x32_bf16 v[86:89], v[158:161], v[216:219], v[86:89]
	s_setprio 0
	s_barrier
; #define PG8_STAGE(bufoff, gbase, voff) do { _Pragma("unroll") for (int _i = 0; _i < 2; ++_i) \
;         __builtin_amdgcn_global_load_lds((const unsigned*)((const char*)(gbase) + (voff)[_i]), (PG8_LAS unsigned*)(lds + (bufoff) + ldsw + _i * 8192), 16, 0, 0); } while (0)
; #define PG8_LDA(dst, b, h) do { _Pragma("unroll") for (int m = 0; m < 4; ++m) _Pragma("unroll") for (int k = 0; k < 2; ++k) dst[m][k] = *(const PG8_LAS bf16x8*)(lds + PG8_SA(b, h) + aoff + m * 2048 + k * 1024); } while (0)
; #define PG8_MMA(ai, bj, At, Bt) do { __builtin_amdgcn_s_setprio(1); _Pragma("unroll") for (int m = 0; m < 4; ++m) _Pragma("unroll") for (int n = 0; n < 2; ++n) _Pragma("unroll") for (int k = 0; k < 2; ++k) \
;         acc[ai][bj][m][n] = __builtin_amdgcn_mfma_f32_16x16x32_bf16(Bt[n][k], At[m][k], acc[ai][bj][m][n], 0, 0, 0); __builtin_amdgcn_s_setprio(0); } while (0)
; #define PG8_WAIT_V(n) asm volatile("s_waitcnt vmcnt(" #n ")" ::: "memory")
; #define PG8_WAIT_L(n) asm volatile("s_waitcnt lgkmcnt(" #n ")" ::: "memory")
; #define PG8_BAR __builtin_amdgcn_s_barrier()
; #define PG8_SCHED __builtin_amdgcn_sched_barrier(0)
; template <class Epi, class Sched, bool ALIGN_EPI = false, bool SP2 = false, bool ABLK = false, bool BBLK = false>
; __device__ __forceinline__ void gemm_phase(PG8_LAS unsigned char* lds, const Gemm g, const Sched& S, const Epi& E) {
;     ...
;             PG8_LDA(At, 0, 1); PG8_STAGE(PG8_SB(0, 0), b2, voffB); PG8_STAGE(PG8_SB(0, 1), b2 + hstepB, voffB); PG8_STAGE(PG8_SA(0, 0), a2, voffA);
;             PG8_WAIT_V(8); PG8_WAIT_L(0); PG8_BAR; PG8_MMA(1, 0, At, B0); PG8_MMA(1, 1, At, B1); PG8_BAR; PG8_SCHED;
	s_add_i32 s44, s44, s65
	v_lshl_add_u64 v[188:189], s[36:37], 0, v[186:187]
	s_mov_b32 m0, s44
	ds_read_b128 v[162:165], v207 offset:16384
	ds_read_b128 v[166:169], v207 offset:17408
	ds_read_b128 v[170:173], v207 offset:18432
	ds_read_b128 v[174:177], v207 offset:19456
	ds_read_b128 v[198:201], v207 offset:20480
	ds_read_b128 v[208:211], v207 offset:21504
	ds_read_b128 v[212:215], v207 offset:22528
	ds_read_b128 v[216:219], v207 offset:23552
	global_load_lds_dwordx4 v[188:189], off
	s_add_i32 m0, s44, 0x2000
	s_add_u32 s44, s36, 0x4000
	v_lshl_add_u64 v[188:189], s[36:37], 0, v[182:183]
	s_addc_u32 s45, s37, 0
	s_add_i32 s52, s52, s65
	global_load_lds_dwordx4 v[188:189], off
	v_lshl_add_u64 v[188:189], s[44:45], 0, v[186:187]
	s_mov_b32 m0, s52
	s_nop 0
	global_load_lds_dwordx4 v[188:189], off
	v_lshl_add_u64 v[188:189], s[44:45], 0, v[182:183]
	s_add_i32 m0, s52, 0x2000
	s_nop 0
	global_load_lds_dwordx4 v[188:189], off
	v_lshl_add_u64 v[188:189], s[40:41], 0, v[178:179]
	s_mov_b32 m0, s68
	s_nop 0
	global_load_lds_dwordx4 v[188:189], off
	v_lshl_add_u64 v[188:189], s[40:41], 0, v[180:181]
	s_mov_b32 m0, s72
	s_nop 0
	global_load_lds_dwordx4 v[188:189], off
	s_waitcnt vmcnt(8)
	s_waitcnt lgkmcnt(0)
	s_barrier
	s_setprio 1
	s_waitcnt lgkmcnt(0)
	v_mfma_f32_16x16x32_bf16 v[106:109], v[130:133], v[162:165], 0
	v_mfma_f32_16x16x32_bf16 v[110:113], v[138:141], v[162:165], 0
	v_mfma_f32_16x16x32_bf16 v[122:125], v[130:133], v[170:173], 0
	v_mfma_f32_16x16x32_bf16 v[126:129], v[138:141], v[170:173], 0
	v_mfma_f32_16x16x32_bf16 v[94:97], v[130:133], v[198:201], 0
	v_mfma_f32_16x16x32_bf16 v[90:93], v[138:141], v[198:201], 0
	v_mfma_f32_16x16x32_bf16 v[38:41], v[130:133], v[212:215], 0
	v_mfma_f32_16x16x32_bf16 v[34:37], v[138:141], v[212:215], 0
	v_mfma_f32_16x16x32_bf16 v[106:109], v[134:137], v[166:169], v[106:109]
	v_mfma_f32_16x16x32_bf16 v[110:113], v[142:145], v[166:169], v[110:113]
	v_mfma_f32_16x16x32_bf16 v[122:125], v[134:137], v[174:177], v[122:125]
	v_mfma_f32_16x16x32_bf16 v[126:129], v[142:145], v[174:177], v[126:129]
	v_mfma_f32_16x16x32_bf16 v[94:97], v[134:137], v[208:211], v[94:97]
	v_mfma_f32_16x16x32_bf16 v[90:93], v[142:145], v[208:211], v[90:93]
	v_mfma_f32_16x16x32_bf16 v[38:41], v[134:137], v[216:219], v[38:41]
	v_mfma_f32_16x16x32_bf16 v[34:37], v[142:145], v[216:219], v[34:37]
	s_setprio 0
	s_setprio 1
	v_mfma_f32_16x16x32_bf16 v[114:117], v[146:149], v[162:165], 0
	v_mfma_f32_16x16x32_bf16 v[118:121], v[154:157], v[162:165], 0
	v_mfma_f32_16x16x32_bf16 v[102:105], v[146:149], v[170:173], 0
	v_mfma_f32_16x16x32_bf16 v[98:101], v[154:157], v[170:173], 0
	v_mfma_f32_16x16x32_bf16 v[62:65], v[146:149], v[198:201], 0
	v_mfma_f32_16x16x32_bf16 v[58:61], v[154:157], v[198:201], 0
	v_mfma_f32_16x16x32_bf16 v[6:9], v[146:149], v[212:215], 0
	v_mfma_f32_16x16x32_bf16 v[2:5], v[154:157], v[212:215], 0
	v_mfma_f32_16x16x32_bf16 v[114:117], v[150:153], v[166:169], v[114:117]
	v_mfma_f32_16x16x32_bf16 v[118:121], v[158:161], v[166:169], v[118:121]
	v_mfma_f32_16x16x32_bf16 v[102:105], v[150:153], v[174:177], v[102:105]
	v_mfma_f32_16x16x32_bf16 v[98:101], v[158:161], v[174:177], v[98:101]
	v_mfma_f32_16x16x32_bf16 v[62:65], v[150:153], v[208:211], v[62:65]
	v_mfma_f32_16x16x32_bf16 v[58:61], v[158:161], v[208:211], v[58:61]
	v_mfma_f32_16x16x32_bf16 v[6:9], v[150:153], v[216:219], v[6:9]
	v_mfma_f32_16x16x32_bf16 v[2:5], v[158:161], v[216:219], v[2:5]
	s_setprio 0
	s_barrier
	s_branch .Lmid_1483
